# 8-phase GEMM loops: loop counter update and compare moved ahead of the closing barrier (only the branch follows it)
# baseline (speedup 1.0000x reference)
; #define MFMA(a, b, c) __builtin_amdgcn_mfma_f32_32x32x16_bf16((a), (b), (c), 0, 0, 0)
; template <bool SWAP>
; DI void gemm_mainloop(f32x16 (&acc)[4][2], const u16* __restrict__ A, int lda, int rlo, int rhi,
;                       const u16* __restrict__ B, int ldb, int K, char* lds, const u16* zero_line) {
;     ...
;   auto ldfrag = [&](const char* st, int ks, int buf) {
;     const int co = ((2 * ks + h) ^ sw) << 4;
; #pragma unroll
;     for (int mi = 0; mi < 4; ++mi) fa[buf][mi] = *(const bf16x8*)(st + arow_off + mi * 4096 + co);
; #pragma unroll
;     for (int ni = 0; ni < 2; ++ni) fb[buf][ni] = *(const bf16x8*)(st + brow_off + ni * 4096 + co);
;   };
;   auto mma = [&](int buf) {
; #pragma unroll
;     for (int mi = 0; mi < 4; ++mi)
; #pragma unroll
;       for (int ni = 0; ni < 2; ++ni)
;         acc[mi][ni] = SWAP ? MFMA(fb[buf][ni], fa[buf][mi], acc[mi][ni]) : MFMA(fa[buf][mi], fb[buf][ni], acc[mi][ni]);
;   };
;   auto pat_rd = [&]() {
; #pragma unroll
;     for (int g = 0; g < 6; ++g) {
;       __builtin_amdgcn_sched_group_barrier(0x100, 1, 0);
;       __builtin_amdgcn_sched_group_barrier(0x008, 1, 0);
;     }
;     __builtin_amdgcn_sched_group_barrier(0x008, 2, 0);
;   };
; #pragma unroll 2
;   for (int kt = 0; kt < nk; ++kt) {
;     const char* st = lds + (kt & 1) * 65536;
;     ldfrag(st, 0, 0);
;     mma(1);
;     pat_rd();
;     if (kt + 1 < nk) glds(kt + 1, (kt + 1) & 1);
;     ldfrag(st, 1, 1);
;     mma(0);
;     pat_rd();
;     ldfrag(st, 2, 0);
;     mma(1);
;     pat_rd();
;     ldfrag(st, 3, 1);
;     mma(0);
;     pat_rd();
;     asm volatile("s_waitcnt vmcnt(0)" ::: "memory");
;     __syncthreads();
;   }
.Lg8_u0u:
	ds_read_b128 v[130:133], v244
	ds_read_b128 v[134:137], v245
	ds_read_b128 v[138:141], v246
	ds_read_b128 v[142:145], v247
	ds_read_b128 v[146:149], v244 offset:4096
	ds_read_b128 v[150:153], v245 offset:4096
	ds_read_b128 v[158:161], v246 offset:4096
	ds_read_b128 v[162:165], v247 offset:4096
	s_add_u32 m0, s100, 0x14000
	s_nop 0
	global_load_lds_dwordx4 v237, s[18:19]
	v_add_u32_e32 v237, 0x80, v237
	s_add_u32 m0, s100, 0x16000
	s_nop 0
	global_load_lds_dwordx4 v239, s[18:19]
	v_add_u32_e32 v239, 0x80, v239
	s_barrier
	s_waitcnt lgkmcnt(0)
	v_mfma_f32_32x32x16_bf16 v[114:129], v[176:179], v[130:133], v[114:129]
	v_mfma_f32_32x32x16_bf16 v[82:97], v[176:179], v[146:149], v[82:97]
	v_mfma_f32_32x32x16_bf16 v[114:129], v[180:183], v[134:137], v[114:129]
	v_mfma_f32_32x32x16_bf16 v[82:97], v[180:183], v[150:153], v[82:97]
	v_mfma_f32_32x32x16_bf16 v[114:129], v[186:189], v[138:141], v[114:129]
	v_mfma_f32_32x32x16_bf16 v[82:97], v[186:189], v[158:161], v[82:97]
	v_mfma_f32_32x32x16_bf16 v[114:129], v[190:193], v[142:145], v[114:129]
	v_mfma_f32_32x32x16_bf16 v[82:97], v[190:193], v[162:165], v[82:97]
	s_barrier
	ds_read_b128 v[194:197], v202 offset:49152
	ds_read_b128 v[198:201], v203 offset:49152
	ds_read_b128 v[228:231], v175 offset:49152
	ds_read_b128 v[232:235], v185 offset:49152
	s_add_u32 m0, s100, 0x8000
	s_nop 0
	global_load_lds_dwordx4 v240, s[22:23]
	v_add_u32_e32 v240, 0x80, v240
	s_add_u32 m0, s100, 0xa000
	s_nop 0
	global_load_lds_dwordx4 v242, s[22:23]
	v_add_u32_e32 v242, 0x80, v242
	s_barrier
	s_waitcnt lgkmcnt(0)
	v_mfma_f32_32x32x16_bf16 v[98:113], v[194:197], v[130:133], v[98:113]
	v_mfma_f32_32x32x16_bf16 v[66:81], v[194:197], v[146:149], v[66:81]
	v_mfma_f32_32x32x16_bf16 v[98:113], v[198:201], v[134:137], v[98:113]
	v_mfma_f32_32x32x16_bf16 v[66:81], v[198:201], v[150:153], v[66:81]
	v_mfma_f32_32x32x16_bf16 v[98:113], v[228:231], v[138:141], v[98:113]
	v_mfma_f32_32x32x16_bf16 v[66:81], v[228:231], v[158:161], v[66:81]
	v_mfma_f32_32x32x16_bf16 v[98:113], v[232:235], v[142:145], v[98:113]
	v_mfma_f32_32x32x16_bf16 v[66:81], v[232:235], v[162:165], v[66:81]
	s_barrier
	ds_read_b128 v[130:133], v244 offset:16384
	ds_read_b128 v[134:137], v245 offset:16384
	ds_read_b128 v[138:141], v246 offset:16384
	ds_read_b128 v[142:145], v247 offset:16384
	ds_read_b128 v[146:149], v244 offset:20480
	ds_read_b128 v[150:153], v245 offset:20480
	ds_read_b128 v[158:161], v246 offset:20480
	ds_read_b128 v[162:165], v247 offset:20480
	s_add_u32 m0, s100, 0x0
	s_nop 0
	global_load_lds_dwordx4 v236, s[18:19]
	v_add_u32_e32 v236, 0x80, v236
	s_add_u32 m0, s100, 0x2000
	s_nop 0
	global_load_lds_dwordx4 v238, s[18:19]
	v_add_u32_e32 v238, 0x80, v238
	s_waitcnt vmcnt(10)
	s_barrier
	s_waitcnt lgkmcnt(0)
	v_mfma_f32_32x32x16_bf16 v[50:65], v[176:179], v[130:133], v[50:65]
	v_mfma_f32_32x32x16_bf16 v[18:33], v[176:179], v[146:149], v[18:33]
	v_mfma_f32_32x32x16_bf16 v[50:65], v[180:183], v[134:137], v[50:65]
	v_mfma_f32_32x32x16_bf16 v[18:33], v[180:183], v[150:153], v[18:33]
	v_mfma_f32_32x32x16_bf16 v[50:65], v[186:189], v[138:141], v[50:65]
	v_mfma_f32_32x32x16_bf16 v[18:33], v[186:189], v[158:161], v[18:33]
	v_mfma_f32_32x32x16_bf16 v[50:65], v[190:193], v[142:145], v[50:65]
	v_mfma_f32_32x32x16_bf16 v[18:33], v[190:193], v[162:165], v[18:33]
	s_barrier
	v_add_u32_e32 v166, s21, v202
	v_add_u32_e32 v167, s21, v203
	ds_read_b128 v[176:179], v166 offset:32768
	ds_read_b128 v[180:183], v167 offset:32768
	v_add_u32_e32 v166, s21, v175
	v_add_u32_e32 v167, s21, v185
	ds_read_b128 v[186:189], v166 offset:32768
	ds_read_b128 v[190:193], v167 offset:32768
	s_add_u32 m0, s100, 0xc000
	s_nop 0
	global_load_lds_dwordx4 v241, s[22:23]
	v_add_u32_e32 v241, 0x80, v241
	s_add_u32 m0, s100, 0xe000
	s_nop 0
	global_load_lds_dwordx4 v243, s[22:23]
	v_add_u32_e32 v243, 0x80, v243
	s_waitcnt vmcnt(6)
	s_barrier
	s_waitcnt lgkmcnt(0)
	v_mfma_f32_32x32x16_bf16 v[34:49], v[194:197], v[130:133], v[34:49]
	v_mfma_f32_32x32x16_bf16 v[2:17], v[194:197], v[146:149], v[2:17]
	v_mfma_f32_32x32x16_bf16 v[34:49], v[198:201], v[134:137], v[34:49]
	v_mfma_f32_32x32x16_bf16 v[2:17], v[198:201], v[150:153], v[2:17]
	v_mfma_f32_32x32x16_bf16 v[34:49], v[228:231], v[138:141], v[34:49]
	v_mfma_f32_32x32x16_bf16 v[2:17], v[228:231], v[158:161], v[2:17]
	v_mfma_f32_32x32x16_bf16 v[34:49], v[232:235], v[142:145], v[34:49]
	v_mfma_f32_32x32x16_bf16 v[2:17], v[232:235], v[162:165], v[2:17]
	s_barrier
	v_add_u32_e32 v166, s21, v244
	v_add_u32_e32 v167, s21, v245
	ds_read_b128 v[130:133], v166
	ds_read_b128 v[134:137], v167
	ds_read_b128 v[146:149], v166 offset:4096
	ds_read_b128 v[150:153], v167 offset:4096
	v_add_u32_e32 v166, s21, v246
	v_add_u32_e32 v167, s21, v247
	ds_read_b128 v[138:141], v166
	ds_read_b128 v[142:145], v167
	ds_read_b128 v[158:161], v166 offset:4096
	ds_read_b128 v[162:165], v167 offset:4096
	s_add_u32 m0, s100, 0x4000
	s_nop 0
	global_load_lds_dwordx4 v237, s[18:19]
	v_add_u32_e32 v237, 0x80, v237
	s_add_u32 m0, s100, 0x6000
	s_nop 0
	global_load_lds_dwordx4 v239, s[18:19]
	v_add_u32_e32 v239, 0x80, v239
	s_barrier
	s_waitcnt lgkmcnt(0)
	v_mfma_f32_32x32x16_bf16 v[114:129], v[176:179], v[130:133], v[114:129]
	v_mfma_f32_32x32x16_bf16 v[82:97], v[176:179], v[146:149], v[82:97]
	v_mfma_f32_32x32x16_bf16 v[114:129], v[180:183], v[134:137], v[114:129]
	v_mfma_f32_32x32x16_bf16 v[82:97], v[180:183], v[150:153], v[82:97]
	v_mfma_f32_32x32x16_bf16 v[114:129], v[186:189], v[138:141], v[114:129]
	v_mfma_f32_32x32x16_bf16 v[82:97], v[186:189], v[158:161], v[82:97]
	v_mfma_f32_32x32x16_bf16 v[114:129], v[190:193], v[142:145], v[114:129]
	v_mfma_f32_32x32x16_bf16 v[82:97], v[190:193], v[162:165], v[82:97]
	s_barrier
; template <bool SWAP>
; DI void gemm_mainloop(f32x16 (&acc)[4][2], const u16* __restrict__ A, int lda, int rlo, int rhi,
;                       const u16* __restrict__ B, int ldb, int K, char* lds, const u16* zero_line) {
;     ...
; #pragma unroll 2
;   for (int kt = 0; kt < nk; ++kt) {
;     const char* st = lds + (kt & 1) * 65536;
;     ldfrag(st, 0, 0);
;     mma(1);
;     pat_rd();
;     if (kt + 1 < nk) glds(kt + 1, (kt + 1) & 1);
;     ldfrag(st, 1, 1);
;     mma(0);
;     pat_rd();
;     ldfrag(st, 2, 0);
;     mma(1);
;     pat_rd();
;     ldfrag(st, 3, 1);
;     mma(0);
;     pat_rd();
;     asm volatile("s_waitcnt vmcnt(0)" ::: "memory");
;     __syncthreads();
;   }
;   mma(1);
	v_add_u32_e32 v166, s21, v202
	v_add_u32_e32 v167, s21, v203
	ds_read_b128 v[194:197], v166 offset:49152
	ds_read_b128 v[198:201], v167 offset:49152
	v_add_u32_e32 v166, s21, v175
	v_add_u32_e32 v167, s21, v185
	ds_read_b128 v[228:231], v166 offset:49152
	ds_read_b128 v[232:235], v167 offset:49152
	s_add_u32 m0, s100, 0x18000
	s_nop 0
	global_load_lds_dwordx4 v240, s[22:23]
	v_add_u32_e32 v240, 0x80, v240
	s_add_u32 m0, s100, 0x1a000
	s_nop 0
	global_load_lds_dwordx4 v242, s[22:23]
	v_add_u32_e32 v242, 0x80, v242
	s_barrier
	s_waitcnt lgkmcnt(0)
	v_mfma_f32_32x32x16_bf16 v[98:113], v[194:197], v[130:133], v[98:113]
	v_mfma_f32_32x32x16_bf16 v[66:81], v[194:197], v[146:149], v[66:81]
	v_mfma_f32_32x32x16_bf16 v[98:113], v[198:201], v[134:137], v[98:113]
	v_mfma_f32_32x32x16_bf16 v[66:81], v[198:201], v[150:153], v[66:81]
	v_mfma_f32_32x32x16_bf16 v[98:113], v[228:231], v[138:141], v[98:113]
	v_mfma_f32_32x32x16_bf16 v[66:81], v[228:231], v[158:161], v[66:81]
	v_mfma_f32_32x32x16_bf16 v[98:113], v[232:235], v[142:145], v[98:113]
	v_mfma_f32_32x32x16_bf16 v[66:81], v[232:235], v[162:165], v[66:81]
	s_barrier
	v_add_u32_e32 v166, s21, v244
	v_add_u32_e32 v167, s21, v245
	ds_read_b128 v[130:133], v166 offset:16384
	ds_read_b128 v[134:137], v167 offset:16384
	ds_read_b128 v[146:149], v166 offset:20480
	ds_read_b128 v[150:153], v167 offset:20480
	v_add_u32_e32 v166, s21, v246
	v_add_u32_e32 v167, s21, v247
	ds_read_b128 v[138:141], v166 offset:16384
	ds_read_b128 v[142:145], v167 offset:16384
	ds_read_b128 v[158:161], v166 offset:20480
	ds_read_b128 v[162:165], v167 offset:20480
	s_add_u32 m0, s100, 0x10000
	s_nop 0
	global_load_lds_dwordx4 v236, s[18:19]
	v_add_u32_e32 v236, 0x80, v236
	s_add_u32 m0, s100, 0x12000
	s_nop 0
	global_load_lds_dwordx4 v238, s[18:19]
	v_add_u32_e32 v238, 0x80, v238
	s_waitcnt vmcnt(10)
	s_barrier
	s_waitcnt lgkmcnt(0)
	v_mfma_f32_32x32x16_bf16 v[50:65], v[176:179], v[130:133], v[50:65]
	v_mfma_f32_32x32x16_bf16 v[18:33], v[176:179], v[146:149], v[18:33]
	v_mfma_f32_32x32x16_bf16 v[50:65], v[180:183], v[134:137], v[50:65]
	v_mfma_f32_32x32x16_bf16 v[18:33], v[180:183], v[150:153], v[18:33]
	v_mfma_f32_32x32x16_bf16 v[50:65], v[186:189], v[138:141], v[50:65]
	v_mfma_f32_32x32x16_bf16 v[18:33], v[186:189], v[158:161], v[18:33]
	v_mfma_f32_32x32x16_bf16 v[50:65], v[190:193], v[142:145], v[50:65]
	v_mfma_f32_32x32x16_bf16 v[18:33], v[190:193], v[162:165], v[18:33]
	s_barrier
	ds_read_b128 v[176:179], v202 offset:32768
	ds_read_b128 v[180:183], v203 offset:32768
	ds_read_b128 v[186:189], v175 offset:32768
	ds_read_b128 v[190:193], v185 offset:32768
	s_add_u32 m0, s100, 0x1c000
	s_nop 0
	global_load_lds_dwordx4 v241, s[22:23]
	v_add_u32_e32 v241, 0x80, v241
	s_add_u32 m0, s100, 0x1e000
	s_nop 0
	global_load_lds_dwordx4 v243, s[22:23]
	v_add_u32_e32 v243, 0x80, v243
	s_waitcnt vmcnt(6)
	s_barrier
	s_waitcnt lgkmcnt(0)
	v_mfma_f32_32x32x16_bf16 v[34:49], v[194:197], v[130:133], v[34:49]
	v_mfma_f32_32x32x16_bf16 v[2:17], v[194:197], v[146:149], v[2:17]
	v_mfma_f32_32x32x16_bf16 v[34:49], v[198:201], v[134:137], v[34:49]
	v_mfma_f32_32x32x16_bf16 v[2:17], v[198:201], v[150:153], v[2:17]
	v_mfma_f32_32x32x16_bf16 v[34:49], v[228:231], v[138:141], v[34:49]
	v_mfma_f32_32x32x16_bf16 v[2:17], v[228:231], v[158:161], v[2:17]
	v_mfma_f32_32x32x16_bf16 v[34:49], v[232:235], v[142:145], v[34:49]
	v_mfma_f32_32x32x16_bf16 v[2:17], v[232:235], v[162:165], v[2:17]
	s_add_i32 s29, s29, 2
	s_cmp_lt_u32 s29, 14
	s_barrier
	s_cbranch_scc1 .Lg8_u0u
	ds_read_b128 v[130:133], v244
	ds_read_b128 v[134:137], v245
	ds_read_b128 v[138:141], v246
	ds_read_b128 v[142:145], v247
	ds_read_b128 v[146:149], v244 offset:4096
	ds_read_b128 v[150:153], v245 offset:4096
	ds_read_b128 v[158:161], v246 offset:4096
	ds_read_b128 v[162:165], v247 offset:4096
	s_add_u32 m0, s100, 0x14000
	s_nop 0
	global_load_lds_dwordx4 v237, s[18:19]
	v_add_u32_e32 v237, 0x80, v237
	s_add_u32 m0, s100, 0x16000
	s_nop 0
	global_load_lds_dwordx4 v239, s[18:19]
	v_add_u32_e32 v239, 0x80, v239
	s_barrier
	s_waitcnt lgkmcnt(0)
	v_mfma_f32_32x32x16_bf16 v[114:129], v[176:179], v[130:133], v[114:129]
	v_mfma_f32_32x32x16_bf16 v[82:97], v[176:179], v[146:149], v[82:97]
	v_mfma_f32_32x32x16_bf16 v[114:129], v[180:183], v[134:137], v[114:129]
	v_mfma_f32_32x32x16_bf16 v[82:97], v[180:183], v[150:153], v[82:97]
	v_mfma_f32_32x32x16_bf16 v[114:129], v[186:189], v[138:141], v[114:129]
	v_mfma_f32_32x32x16_bf16 v[82:97], v[186:189], v[158:161], v[82:97]
	v_mfma_f32_32x32x16_bf16 v[114:129], v[190:193], v[142:145], v[114:129]
	v_mfma_f32_32x32x16_bf16 v[82:97], v[190:193], v[162:165], v[82:97]
	s_barrier
	ds_read_b128 v[194:197], v202 offset:49152
	ds_read_b128 v[198:201], v203 offset:49152
	ds_read_b128 v[228:231], v175 offset:49152
	ds_read_b128 v[232:235], v185 offset:49152
	s_barrier
	s_waitcnt lgkmcnt(0)
	v_mfma_f32_32x32x16_bf16 v[98:113], v[194:197], v[130:133], v[98:113]
	v_mfma_f32_32x32x16_bf16 v[66:81], v[194:197], v[146:149], v[66:81]
	v_mfma_f32_32x32x16_bf16 v[98:113], v[198:201], v[134:137], v[98:113]
	v_mfma_f32_32x32x16_bf16 v[66:81], v[198:201], v[150:153], v[66:81]
	v_mfma_f32_32x32x16_bf16 v[98:113], v[228:231], v[138:141], v[98:113]
	v_mfma_f32_32x32x16_bf16 v[66:81], v[228:231], v[158:161], v[66:81]
	v_mfma_f32_32x32x16_bf16 v[98:113], v[232:235], v[142:145], v[98:113]
	v_mfma_f32_32x32x16_bf16 v[66:81], v[232:235], v[162:165], v[66:81]
	s_barrier
; template <bool SWAP>
; DI void gemm_mainloop(f32x16 (&acc)[4][2], const u16* __restrict__ A, int lda, int rlo, int rhi,
;                       const u16* __restrict__ B, int ldb, int K, char* lds, const u16* zero_line) {
;     ...
; #pragma unroll 2
;   for (int kt = 0; kt < nk; ++kt) {
;     const char* st = lds + (kt & 1) * 65536;
;     ldfrag(st, 0, 0);
;     mma(1);
;     pat_rd();
;     if (kt + 1 < nk) glds(kt + 1, (kt + 1) & 1);
;     ldfrag(st, 1, 1);
;     mma(0);
;     pat_rd();
;     ldfrag(st, 2, 0);
;     mma(1);
;     pat_rd();
;     ldfrag(st, 3, 1);
;     mma(0);
;     pat_rd();
;     asm volatile("s_waitcnt vmcnt(0)" ::: "memory");
;     __syncthreads();
;   }
;   mma(1);
	ds_read_b128 v[130:133], v244 offset:16384
	ds_read_b128 v[134:137], v245 offset:16384
	ds_read_b128 v[138:141], v246 offset:16384
	ds_read_b128 v[142:145], v247 offset:16384
	ds_read_b128 v[146:149], v244 offset:20480
	ds_read_b128 v[150:153], v245 offset:20480
	ds_read_b128 v[158:161], v246 offset:20480
	ds_read_b128 v[162:165], v247 offset:20480
	s_waitcnt vmcnt(4)
	s_barrier
	s_waitcnt lgkmcnt(0)
	v_mfma_f32_32x32x16_bf16 v[50:65], v[176:179], v[130:133], v[50:65]
	v_mfma_f32_32x32x16_bf16 v[18:33], v[176:179], v[146:149], v[18:33]
	v_mfma_f32_32x32x16_bf16 v[50:65], v[180:183], v[134:137], v[50:65]
	v_mfma_f32_32x32x16_bf16 v[18:33], v[180:183], v[150:153], v[18:33]
	v_mfma_f32_32x32x16_bf16 v[50:65], v[186:189], v[138:141], v[50:65]
	v_mfma_f32_32x32x16_bf16 v[18:33], v[186:189], v[158:161], v[18:33]
	v_mfma_f32_32x32x16_bf16 v[50:65], v[190:193], v[142:145], v[50:65]
	v_mfma_f32_32x32x16_bf16 v[18:33], v[190:193], v[162:165], v[18:33]
	v_mfma_f32_32x32x16_bf16 v[34:49], v[194:197], v[130:133], v[34:49]
	v_mfma_f32_32x32x16_bf16 v[2:17], v[194:197], v[146:149], v[2:17]
	v_mfma_f32_32x32x16_bf16 v[34:49], v[198:201], v[134:137], v[34:49]
	v_mfma_f32_32x32x16_bf16 v[2:17], v[198:201], v[150:153], v[2:17]
	v_mfma_f32_32x32x16_bf16 v[34:49], v[228:231], v[138:141], v[34:49]
	v_mfma_f32_32x32x16_bf16 v[2:17], v[228:231], v[158:161], v[2:17]
	v_mfma_f32_32x32x16_bf16 v[34:49], v[232:235], v[142:145], v[34:49]
	v_mfma_f32_32x32x16_bf16 v[2:17], v[232:235], v[162:165], v[2:17]
	s_barrier
	v_add_u32_e32 v166, s21, v202
	v_add_u32_e32 v167, s21, v203
	ds_read_b128 v[176:179], v166 offset:32768
	ds_read_b128 v[180:183], v167 offset:32768
	v_add_u32_e32 v166, s21, v175
	v_add_u32_e32 v167, s21, v185
	ds_read_b128 v[186:189], v166 offset:32768
	ds_read_b128 v[190:193], v167 offset:32768
	v_add_u32_e32 v166, s21, v244
	v_add_u32_e32 v167, s21, v245
	ds_read_b128 v[130:133], v166
	ds_read_b128 v[134:137], v167
	ds_read_b128 v[146:149], v166 offset:4096
	ds_read_b128 v[150:153], v167 offset:4096
	v_add_u32_e32 v166, s21, v246
	v_add_u32_e32 v167, s21, v247
	ds_read_b128 v[138:141], v166
	ds_read_b128 v[142:145], v167
	ds_read_b128 v[158:161], v166 offset:4096
	ds_read_b128 v[162:165], v167 offset:4096
	s_waitcnt vmcnt(2)
	s_barrier
	s_waitcnt lgkmcnt(0)
	v_mfma_f32_32x32x16_bf16 v[114:129], v[176:179], v[130:133], v[114:129]
	v_mfma_f32_32x32x16_bf16 v[82:97], v[176:179], v[146:149], v[82:97]
	v_mfma_f32_32x32x16_bf16 v[114:129], v[180:183], v[134:137], v[114:129]
	v_mfma_f32_32x32x16_bf16 v[82:97], v[180:183], v[150:153], v[82:97]
	v_mfma_f32_32x32x16_bf16 v[114:129], v[186:189], v[138:141], v[114:129]
	v_mfma_f32_32x32x16_bf16 v[82:97], v[186:189], v[158:161], v[82:97]
	v_mfma_f32_32x32x16_bf16 v[114:129], v[190:193], v[142:145], v[114:129]
	v_mfma_f32_32x32x16_bf16 v[82:97], v[190:193], v[162:165], v[82:97]
	s_barrier
	v_add_u32_e32 v166, s21, v202
	v_add_u32_e32 v167, s21, v203
	ds_read_b128 v[194:197], v166 offset:49152
	ds_read_b128 v[198:201], v167 offset:49152
	v_add_u32_e32 v166, s21, v175
	v_add_u32_e32 v167, s21, v185
	ds_read_b128 v[228:231], v166 offset:49152
	ds_read_b128 v[232:235], v167 offset:49152
	s_waitcnt vmcnt(0)
	s_barrier
	s_waitcnt lgkmcnt(0)
	v_mfma_f32_32x32x16_bf16 v[98:113], v[194:197], v[130:133], v[98:113]
	v_mfma_f32_32x32x16_bf16 v[66:81], v[194:197], v[146:149], v[66:81]
	v_mfma_f32_32x32x16_bf16 v[98:113], v[198:201], v[134:137], v[98:113]
	v_mfma_f32_32x32x16_bf16 v[66:81], v[198:201], v[150:153], v[66:81]
	v_mfma_f32_32x32x16_bf16 v[98:113], v[228:231], v[138:141], v[98:113]
	v_mfma_f32_32x32x16_bf16 v[66:81], v[228:231], v[158:161], v[66:81]
	v_mfma_f32_32x32x16_bf16 v[98:113], v[232:235], v[142:145], v[98:113]
	v_mfma_f32_32x32x16_bf16 v[66:81], v[232:235], v[162:165], v[66:81]
	s_barrier
	v_add_u32_e32 v166, s21, v244
	v_add_u32_e32 v167, s21, v245
	ds_read_b128 v[130:133], v166 offset:16384
	ds_read_b128 v[134:137], v167 offset:16384
	ds_read_b128 v[146:149], v166 offset:20480
	ds_read_b128 v[150:153], v167 offset:20480
	v_add_u32_e32 v166, s21, v246
	v_add_u32_e32 v167, s21, v247
	ds_read_b128 v[138:141], v166 offset:16384
	ds_read_b128 v[142:145], v167 offset:16384
	ds_read_b128 v[158:161], v166 offset:20480
	ds_read_b128 v[162:165], v167 offset:20480
	s_barrier
	s_waitcnt lgkmcnt(0)
	v_mfma_f32_32x32x16_bf16 v[50:65], v[176:179], v[130:133], v[50:65]
	v_mfma_f32_32x32x16_bf16 v[18:33], v[176:179], v[146:149], v[18:33]
	v_mfma_f32_32x32x16_bf16 v[50:65], v[180:183], v[134:137], v[50:65]
	v_mfma_f32_32x32x16_bf16 v[18:33], v[180:183], v[150:153], v[18:33]
	v_mfma_f32_32x32x16_bf16 v[50:65], v[186:189], v[138:141], v[50:65]
	v_mfma_f32_32x32x16_bf16 v[18:33], v[186:189], v[158:161], v[18:33]
	v_mfma_f32_32x32x16_bf16 v[50:65], v[190:193], v[142:145], v[50:65]
	v_mfma_f32_32x32x16_bf16 v[18:33], v[190:193], v[162:165], v[18:33]
	v_mfma_f32_32x32x16_bf16 v[34:49], v[194:197], v[130:133], v[34:49]
	v_mfma_f32_32x32x16_bf16 v[2:17], v[194:197], v[146:149], v[2:17]
	v_mfma_f32_32x32x16_bf16 v[34:49], v[198:201], v[134:137], v[34:49]
	v_mfma_f32_32x32x16_bf16 v[2:17], v[198:201], v[150:153], v[2:17]
	v_mfma_f32_32x32x16_bf16 v[34:49], v[228:231], v[138:141], v[34:49]
	v_mfma_f32_32x32x16_bf16 v[2:17], v[228:231], v[158:161], v[2:17]
	v_mfma_f32_32x32x16_bf16 v[34:49], v[232:235], v[142:145], v[34:49]
	v_mfma_f32_32x32x16_bf16 v[2:17], v[232:235], v[162:165], v[2:17]
	s_barrier
	s_cmp_eq_u32 s101, 0
	s_cbranch_scc0 .Lg8_u0u_p1
	s_barrier

; template <bool SWAP>
; DI void gemm_mainloop(f32x16 (&acc)[4][2], const u16* __restrict__ A, int lda, int rlo, int rhi,
;                       const u16* __restrict__ B, int ldb, int K, char* lds, const u16* zero_line) {
;     ...
;   auto glds = [&](int kt, int st) {
;     char* as_ = lds + st * 65536 + tid * 16;
; #pragma unroll
;     for (int i = 0; i < 4; ++i) {
;       const int rr = lr + 64 * i;
;       const u16* srca = (rr >= rlo && rr < rhi) ? (ap + (ptrdiff_t)(64 * i) * lda + kt * 64) : (zero_line + lc * 8);
;       __builtin_amdgcn_global_load_lds((const unsigned*)srca, (lds_u32*)(as_ + i * 8192), 16, 0, 0);
;       __builtin_amdgcn_global_load_lds((const unsigned*)(bp + (ptrdiff_t)(64 * i) * ldb + kt * 64), (lds_u32*)(as_ + 32768 + i * 8192), 16, 0, 0);
;     }
;   };
;     ...
; #pragma unroll 2
;   for (int kt = 0; kt < nk; ++kt) {
;     const char* st = lds + (kt & 1) * 65536;
;     ldfrag(st, 0, 0);
;     mma(1);
;     pat_rd();
;     if (kt + 1 < nk) glds(kt + 1, (kt + 1) & 1);
;     ldfrag(st, 1, 1);
;     mma(0);
;     pat_rd();
;     ldfrag(st, 2, 0);
;     mma(1);
;     pat_rd();
;     ldfrag(st, 3, 1);
;     mma(0);
;     pat_rd();
;     asm volatile("s_waitcnt vmcnt(0)" ::: "memory");
;     __syncthreads();
;   }
.Lg8_u0m:
	ds_read_b128 v[130:133], v244
	ds_read_b128 v[134:137], v245
	ds_read_b128 v[138:141], v246
	ds_read_b128 v[142:145], v247
	ds_read_b128 v[146:149], v244 offset:4096
	ds_read_b128 v[150:153], v245 offset:4096
	ds_read_b128 v[158:161], v246 offset:4096
	ds_read_b128 v[162:165], v247 offset:4096
	s_add_u32 m0, s100, 0x14000
	s_mov_b64 exec, s[12:13]
	global_load_lds_dwordx4 v237, s[18:19]
	s_mov_b64 exec, -1
	v_add_u32_e32 v237, 0x80, v237
	s_add_u32 m0, s100, 0x16000
	s_mov_b64 exec, s[16:17]
	global_load_lds_dwordx4 v239, s[18:19]
	s_mov_b64 exec, -1
	v_add_u32_e32 v239, 0x80, v239
	s_barrier
	s_waitcnt lgkmcnt(0)
	v_mfma_f32_32x32x16_bf16 v[114:129], v[176:179], v[130:133], v[114:129]
	v_mfma_f32_32x32x16_bf16 v[82:97], v[176:179], v[146:149], v[82:97]
	v_mfma_f32_32x32x16_bf16 v[114:129], v[180:183], v[134:137], v[114:129]
	v_mfma_f32_32x32x16_bf16 v[82:97], v[180:183], v[150:153], v[82:97]
	v_mfma_f32_32x32x16_bf16 v[114:129], v[186:189], v[138:141], v[114:129]
	v_mfma_f32_32x32x16_bf16 v[82:97], v[186:189], v[158:161], v[82:97]
	v_mfma_f32_32x32x16_bf16 v[114:129], v[190:193], v[142:145], v[114:129]
	v_mfma_f32_32x32x16_bf16 v[82:97], v[190:193], v[162:165], v[82:97]
	s_barrier
	ds_read_b128 v[194:197], v202 offset:49152
	ds_read_b128 v[198:201], v203 offset:49152
	ds_read_b128 v[228:231], v175 offset:49152
	ds_read_b128 v[232:235], v185 offset:49152
	s_add_u32 m0, s100, 0x8000
	s_nop 0
	global_load_lds_dwordx4 v240, s[22:23]
	v_add_u32_e32 v240, 0x80, v240
	s_add_u32 m0, s100, 0xa000
	s_nop 0
	global_load_lds_dwordx4 v242, s[22:23]
	v_add_u32_e32 v242, 0x80, v242
	s_barrier
	s_waitcnt lgkmcnt(0)
	v_mfma_f32_32x32x16_bf16 v[98:113], v[194:197], v[130:133], v[98:113]
	v_mfma_f32_32x32x16_bf16 v[66:81], v[194:197], v[146:149], v[66:81]
	v_mfma_f32_32x32x16_bf16 v[98:113], v[198:201], v[134:137], v[98:113]
	v_mfma_f32_32x32x16_bf16 v[66:81], v[198:201], v[150:153], v[66:81]
	v_mfma_f32_32x32x16_bf16 v[98:113], v[228:231], v[138:141], v[98:113]
	v_mfma_f32_32x32x16_bf16 v[66:81], v[228:231], v[158:161], v[66:81]
	v_mfma_f32_32x32x16_bf16 v[98:113], v[232:235], v[142:145], v[98:113]
	v_mfma_f32_32x32x16_bf16 v[66:81], v[232:235], v[162:165], v[66:81]
	s_barrier
	ds_read_b128 v[130:133], v244 offset:16384
	ds_read_b128 v[134:137], v245 offset:16384
	ds_read_b128 v[138:141], v246 offset:16384
	ds_read_b128 v[142:145], v247 offset:16384
	ds_read_b128 v[146:149], v244 offset:20480
	ds_read_b128 v[150:153], v245 offset:20480
	ds_read_b128 v[158:161], v246 offset:20480
	ds_read_b128 v[162:165], v247 offset:20480
	s_add_u32 m0, s100, 0x0
	s_mov_b64 exec, s[10:11]
	global_load_lds_dwordx4 v236, s[18:19]
	s_mov_b64 exec, -1
	v_add_u32_e32 v236, 0x80, v236
	s_add_u32 m0, s100, 0x2000
	s_mov_b64 exec, s[14:15]
	global_load_lds_dwordx4 v238, s[18:19]
	s_mov_b64 exec, -1
	v_add_u32_e32 v238, 0x80, v238
	s_waitcnt vmcnt(10)
	s_barrier
	s_waitcnt lgkmcnt(0)
	v_mfma_f32_32x32x16_bf16 v[50:65], v[176:179], v[130:133], v[50:65]
	v_mfma_f32_32x32x16_bf16 v[18:33], v[176:179], v[146:149], v[18:33]
	v_mfma_f32_32x32x16_bf16 v[50:65], v[180:183], v[134:137], v[50:65]
	v_mfma_f32_32x32x16_bf16 v[18:33], v[180:183], v[150:153], v[18:33]
	v_mfma_f32_32x32x16_bf16 v[50:65], v[186:189], v[138:141], v[50:65]
	v_mfma_f32_32x32x16_bf16 v[18:33], v[186:189], v[158:161], v[18:33]
	v_mfma_f32_32x32x16_bf16 v[50:65], v[190:193], v[142:145], v[50:65]
	v_mfma_f32_32x32x16_bf16 v[18:33], v[190:193], v[162:165], v[18:33]
	s_barrier
	v_add_u32_e32 v166, s21, v202
	v_add_u32_e32 v167, s21, v203
	ds_read_b128 v[176:179], v166 offset:32768
	ds_read_b128 v[180:183], v167 offset:32768
	v_add_u32_e32 v166, s21, v175
	v_add_u32_e32 v167, s21, v185
	ds_read_b128 v[186:189], v166 offset:32768
	ds_read_b128 v[190:193], v167 offset:32768
	s_add_u32 m0, s100, 0xc000
	s_nop 0
	global_load_lds_dwordx4 v241, s[22:23]
	v_add_u32_e32 v241, 0x80, v241
	s_add_u32 m0, s100, 0xe000
	s_nop 0
	global_load_lds_dwordx4 v243, s[22:23]
	v_add_u32_e32 v243, 0x80, v243
	s_waitcnt vmcnt(6)
	s_barrier
	s_waitcnt lgkmcnt(0)
	v_mfma_f32_32x32x16_bf16 v[34:49], v[194:197], v[130:133], v[34:49]
	v_mfma_f32_32x32x16_bf16 v[2:17], v[194:197], v[146:149], v[2:17]
	v_mfma_f32_32x32x16_bf16 v[34:49], v[198:201], v[134:137], v[34:49]
	v_mfma_f32_32x32x16_bf16 v[2:17], v[198:201], v[150:153], v[2:17]
	v_mfma_f32_32x32x16_bf16 v[34:49], v[228:231], v[138:141], v[34:49]
	v_mfma_f32_32x32x16_bf16 v[2:17], v[228:231], v[158:161], v[2:17]
	v_mfma_f32_32x32x16_bf16 v[34:49], v[232:235], v[142:145], v[34:49]
	v_mfma_f32_32x32x16_bf16 v[2:17], v[232:235], v[162:165], v[2:17]
	s_barrier
	v_add_u32_e32 v166, s21, v244
	v_add_u32_e32 v167, s21, v245
	ds_read_b128 v[130:133], v166
	ds_read_b128 v[134:137], v167
	ds_read_b128 v[146:149], v166 offset:4096
	ds_read_b128 v[150:153], v167 offset:4096
	v_add_u32_e32 v166, s21, v246
	v_add_u32_e32 v167, s21, v247
	ds_read_b128 v[138:141], v166
	ds_read_b128 v[142:145], v167
	ds_read_b128 v[158:161], v166 offset:4096
	ds_read_b128 v[162:165], v167 offset:4096
	s_add_u32 m0, s100, 0x4000
	s_mov_b64 exec, s[12:13]
	global_load_lds_dwordx4 v237, s[18:19]
	s_mov_b64 exec, -1
	v_add_u32_e32 v237, 0x80, v237
	s_add_u32 m0, s100, 0x6000
	s_mov_b64 exec, s[16:17]
	global_load_lds_dwordx4 v239, s[18:19]
	s_mov_b64 exec, -1
	v_add_u32_e32 v239, 0x80, v239
	s_barrier
	s_waitcnt lgkmcnt(0)
	v_mfma_f32_32x32x16_bf16 v[114:129], v[176:179], v[130:133], v[114:129]
	v_mfma_f32_32x32x16_bf16 v[82:97], v[176:179], v[146:149], v[82:97]
	v_mfma_f32_32x32x16_bf16 v[114:129], v[180:183], v[134:137], v[114:129]
	v_mfma_f32_32x32x16_bf16 v[82:97], v[180:183], v[150:153], v[82:97]
	v_mfma_f32_32x32x16_bf16 v[114:129], v[186:189], v[138:141], v[114:129]
	v_mfma_f32_32x32x16_bf16 v[82:97], v[186:189], v[158:161], v[82:97]
	v_mfma_f32_32x32x16_bf16 v[114:129], v[190:193], v[142:145], v[114:129]
	v_mfma_f32_32x32x16_bf16 v[82:97], v[190:193], v[162:165], v[82:97]
	s_barrier
; template <bool SWAP>
; DI void gemm_mainloop(f32x16 (&acc)[4][2], const u16* __restrict__ A, int lda, int rlo, int rhi,
;                       const u16* __restrict__ B, int ldb, int K, char* lds, const u16* zero_line) {
;     ...
; #pragma unroll 2
;   for (int kt = 0; kt < nk; ++kt) {
;     const char* st = lds + (kt & 1) * 65536;
;     ldfrag(st, 0, 0);
;     mma(1);
;     pat_rd();
;     if (kt + 1 < nk) glds(kt + 1, (kt + 1) & 1);
;     ldfrag(st, 1, 1);
;     mma(0);
;     pat_rd();
;     ldfrag(st, 2, 0);
;     mma(1);
;     pat_rd();
;     ldfrag(st, 3, 1);
;     mma(0);
;     pat_rd();
;     asm volatile("s_waitcnt vmcnt(0)" ::: "memory");
;     __syncthreads();
;   }
;   mma(1);
	v_add_u32_e32 v166, s21, v202
	v_add_u32_e32 v167, s21, v203
	ds_read_b128 v[194:197], v166 offset:49152
	ds_read_b128 v[198:201], v167 offset:49152
	v_add_u32_e32 v166, s21, v175
	v_add_u32_e32 v167, s21, v185
	ds_read_b128 v[228:231], v166 offset:49152
	ds_read_b128 v[232:235], v167 offset:49152
	s_add_u32 m0, s100, 0x18000
	s_nop 0
	global_load_lds_dwordx4 v240, s[22:23]
	v_add_u32_e32 v240, 0x80, v240
	s_add_u32 m0, s100, 0x1a000
	s_nop 0
	global_load_lds_dwordx4 v242, s[22:23]
	v_add_u32_e32 v242, 0x80, v242
	s_barrier
	s_waitcnt lgkmcnt(0)
	v_mfma_f32_32x32x16_bf16 v[98:113], v[194:197], v[130:133], v[98:113]
	v_mfma_f32_32x32x16_bf16 v[66:81], v[194:197], v[146:149], v[66:81]
	v_mfma_f32_32x32x16_bf16 v[98:113], v[198:201], v[134:137], v[98:113]
	v_mfma_f32_32x32x16_bf16 v[66:81], v[198:201], v[150:153], v[66:81]
	v_mfma_f32_32x32x16_bf16 v[98:113], v[228:231], v[138:141], v[98:113]
	v_mfma_f32_32x32x16_bf16 v[66:81], v[228:231], v[158:161], v[66:81]
	v_mfma_f32_32x32x16_bf16 v[98:113], v[232:235], v[142:145], v[98:113]
	v_mfma_f32_32x32x16_bf16 v[66:81], v[232:235], v[162:165], v[66:81]
	s_barrier
	v_add_u32_e32 v166, s21, v244
	v_add_u32_e32 v167, s21, v245
	ds_read_b128 v[130:133], v166 offset:16384
	ds_read_b128 v[134:137], v167 offset:16384
	ds_read_b128 v[146:149], v166 offset:20480
	ds_read_b128 v[150:153], v167 offset:20480
	v_add_u32_e32 v166, s21, v246
	v_add_u32_e32 v167, s21, v247
	ds_read_b128 v[138:141], v166 offset:16384
	ds_read_b128 v[142:145], v167 offset:16384
	ds_read_b128 v[158:161], v166 offset:20480
	ds_read_b128 v[162:165], v167 offset:20480
	s_add_u32 m0, s100, 0x10000
	s_mov_b64 exec, s[10:11]
	global_load_lds_dwordx4 v236, s[18:19]
	s_mov_b64 exec, -1
	v_add_u32_e32 v236, 0x80, v236
	s_add_u32 m0, s100, 0x12000
	s_mov_b64 exec, s[14:15]
	global_load_lds_dwordx4 v238, s[18:19]
	s_mov_b64 exec, -1
	v_add_u32_e32 v238, 0x80, v238
	s_waitcnt vmcnt(10)
	s_barrier
	s_waitcnt lgkmcnt(0)
	v_mfma_f32_32x32x16_bf16 v[50:65], v[176:179], v[130:133], v[50:65]
	v_mfma_f32_32x32x16_bf16 v[18:33], v[176:179], v[146:149], v[18:33]
	v_mfma_f32_32x32x16_bf16 v[50:65], v[180:183], v[134:137], v[50:65]
	v_mfma_f32_32x32x16_bf16 v[18:33], v[180:183], v[150:153], v[18:33]
	v_mfma_f32_32x32x16_bf16 v[50:65], v[186:189], v[138:141], v[50:65]
	v_mfma_f32_32x32x16_bf16 v[18:33], v[186:189], v[158:161], v[18:33]
	v_mfma_f32_32x32x16_bf16 v[50:65], v[190:193], v[142:145], v[50:65]
	v_mfma_f32_32x32x16_bf16 v[18:33], v[190:193], v[162:165], v[18:33]
	s_barrier
	ds_read_b128 v[176:179], v202 offset:32768
	ds_read_b128 v[180:183], v203 offset:32768
	ds_read_b128 v[186:189], v175 offset:32768
	ds_read_b128 v[190:193], v185 offset:32768
	s_add_u32 m0, s100, 0x1c000
	s_nop 0
	global_load_lds_dwordx4 v241, s[22:23]
	v_add_u32_e32 v241, 0x80, v241
	s_add_u32 m0, s100, 0x1e000
	s_nop 0
	global_load_lds_dwordx4 v243, s[22:23]
	v_add_u32_e32 v243, 0x80, v243
	s_waitcnt vmcnt(6)
	s_barrier
	s_waitcnt lgkmcnt(0)
	v_mfma_f32_32x32x16_bf16 v[34:49], v[194:197], v[130:133], v[34:49]
	v_mfma_f32_32x32x16_bf16 v[2:17], v[194:197], v[146:149], v[2:17]
	v_mfma_f32_32x32x16_bf16 v[34:49], v[198:201], v[134:137], v[34:49]
	v_mfma_f32_32x32x16_bf16 v[2:17], v[198:201], v[150:153], v[2:17]
	v_mfma_f32_32x32x16_bf16 v[34:49], v[228:231], v[138:141], v[34:49]
	v_mfma_f32_32x32x16_bf16 v[2:17], v[228:231], v[158:161], v[2:17]
	v_mfma_f32_32x32x16_bf16 v[34:49], v[232:235], v[142:145], v[34:49]
	v_mfma_f32_32x32x16_bf16 v[2:17], v[232:235], v[162:165], v[2:17]
	s_add_i32 s29, s29, 2
	s_cmp_lt_u32 s29, 14
	s_barrier
	s_cbranch_scc1 .Lg8_u0m
	ds_read_b128 v[130:133], v244
	ds_read_b128 v[134:137], v245
	ds_read_b128 v[138:141], v246
	ds_read_b128 v[142:145], v247
	ds_read_b128 v[146:149], v244 offset:4096
	ds_read_b128 v[150:153], v245 offset:4096
	ds_read_b128 v[158:161], v246 offset:4096
	ds_read_b128 v[162:165], v247 offset:4096
	s_add_u32 m0, s100, 0x14000
	s_mov_b64 exec, s[12:13]
	global_load_lds_dwordx4 v237, s[18:19]
	s_mov_b64 exec, -1
	v_add_u32_e32 v237, 0x80, v237
	s_add_u32 m0, s100, 0x16000
	s_mov_b64 exec, s[16:17]
	global_load_lds_dwordx4 v239, s[18:19]
	s_mov_b64 exec, -1
	v_add_u32_e32 v239, 0x80, v239
	s_barrier
	s_waitcnt lgkmcnt(0)
	v_mfma_f32_32x32x16_bf16 v[114:129], v[176:179], v[130:133], v[114:129]
	v_mfma_f32_32x32x16_bf16 v[82:97], v[176:179], v[146:149], v[82:97]
	v_mfma_f32_32x32x16_bf16 v[114:129], v[180:183], v[134:137], v[114:129]
	v_mfma_f32_32x32x16_bf16 v[82:97], v[180:183], v[150:153], v[82:97]
	v_mfma_f32_32x32x16_bf16 v[114:129], v[186:189], v[138:141], v[114:129]
	v_mfma_f32_32x32x16_bf16 v[82:97], v[186:189], v[158:161], v[82:97]
	v_mfma_f32_32x32x16_bf16 v[114:129], v[190:193], v[142:145], v[114:129]
	v_mfma_f32_32x32x16_bf16 v[82:97], v[190:193], v[162:165], v[82:97]
	s_barrier
	ds_read_b128 v[194:197], v202 offset:49152
	ds_read_b128 v[198:201], v203 offset:49152
	ds_read_b128 v[228:231], v175 offset:49152
	ds_read_b128 v[232:235], v185 offset:49152
	s_barrier
	s_waitcnt lgkmcnt(0)
	v_mfma_f32_32x32x16_bf16 v[98:113], v[194:197], v[130:133], v[98:113]
	v_mfma_f32_32x32x16_bf16 v[66:81], v[194:197], v[146:149], v[66:81]
	v_mfma_f32_32x32x16_bf16 v[98:113], v[198:201], v[134:137], v[98:113]
	v_mfma_f32_32x32x16_bf16 v[66:81], v[198:201], v[150:153], v[66:81]
	v_mfma_f32_32x32x16_bf16 v[98:113], v[228:231], v[138:141], v[98:113]
	v_mfma_f32_32x32x16_bf16 v[66:81], v[228:231], v[158:161], v[66:81]
	v_mfma_f32_32x32x16_bf16 v[98:113], v[232:235], v[142:145], v[98:113]
	v_mfma_f32_32x32x16_bf16 v[66:81], v[232:235], v[162:165], v[66:81]
	s_barrier
; template <bool SWAP>
; DI void gemm_mainloop(f32x16 (&acc)[4][2], const u16* __restrict__ A, int lda, int rlo, int rhi,
;                       const u16* __restrict__ B, int ldb, int K, char* lds, const u16* zero_line) {
;     ...
; #pragma unroll 2
;   for (int kt = 0; kt < nk; ++kt) {
;     const char* st = lds + (kt & 1) * 65536;
;     ldfrag(st, 0, 0);
;     mma(1);
;     pat_rd();
;     if (kt + 1 < nk) glds(kt + 1, (kt + 1) & 1);
;     ldfrag(st, 1, 1);
;     mma(0);
;     pat_rd();
;     ldfrag(st, 2, 0);
;     mma(1);
;     pat_rd();
;     ldfrag(st, 3, 1);
;     mma(0);
;     pat_rd();
;     asm volatile("s_waitcnt vmcnt(0)" ::: "memory");
;     __syncthreads();
;   }
;   mma(1);
	ds_read_b128 v[130:133], v244 offset:16384
	ds_read_b128 v[134:137], v245 offset:16384
	ds_read_b128 v[138:141], v246 offset:16384
	ds_read_b128 v[142:145], v247 offset:16384
	ds_read_b128 v[146:149], v244 offset:20480
	ds_read_b128 v[150:153], v245 offset:20480
	ds_read_b128 v[158:161], v246 offset:20480
	ds_read_b128 v[162:165], v247 offset:20480
	s_waitcnt vmcnt(4)
	s_barrier
	s_waitcnt lgkmcnt(0)
	v_mfma_f32_32x32x16_bf16 v[50:65], v[176:179], v[130:133], v[50:65]
	v_mfma_f32_32x32x16_bf16 v[18:33], v[176:179], v[146:149], v[18:33]
	v_mfma_f32_32x32x16_bf16 v[50:65], v[180:183], v[134:137], v[50:65]
	v_mfma_f32_32x32x16_bf16 v[18:33], v[180:183], v[150:153], v[18:33]
	v_mfma_f32_32x32x16_bf16 v[50:65], v[186:189], v[138:141], v[50:65]
	v_mfma_f32_32x32x16_bf16 v[18:33], v[186:189], v[158:161], v[18:33]
	v_mfma_f32_32x32x16_bf16 v[50:65], v[190:193], v[142:145], v[50:65]
	v_mfma_f32_32x32x16_bf16 v[18:33], v[190:193], v[162:165], v[18:33]
	v_mfma_f32_32x32x16_bf16 v[34:49], v[194:197], v[130:133], v[34:49]
	v_mfma_f32_32x32x16_bf16 v[2:17], v[194:197], v[146:149], v[2:17]
	v_mfma_f32_32x32x16_bf16 v[34:49], v[198:201], v[134:137], v[34:49]
	v_mfma_f32_32x32x16_bf16 v[2:17], v[198:201], v[150:153], v[2:17]
	v_mfma_f32_32x32x16_bf16 v[34:49], v[228:231], v[138:141], v[34:49]
	v_mfma_f32_32x32x16_bf16 v[2:17], v[228:231], v[158:161], v[2:17]
	v_mfma_f32_32x32x16_bf16 v[34:49], v[232:235], v[142:145], v[34:49]
	v_mfma_f32_32x32x16_bf16 v[2:17], v[232:235], v[162:165], v[2:17]
	s_barrier
	v_add_u32_e32 v166, s21, v202
	v_add_u32_e32 v167, s21, v203
	ds_read_b128 v[176:179], v166 offset:32768
	ds_read_b128 v[180:183], v167 offset:32768
	v_add_u32_e32 v166, s21, v175
	v_add_u32_e32 v167, s21, v185
	ds_read_b128 v[186:189], v166 offset:32768
	ds_read_b128 v[190:193], v167 offset:32768
	v_add_u32_e32 v166, s21, v244
	v_add_u32_e32 v167, s21, v245
	ds_read_b128 v[130:133], v166
	ds_read_b128 v[134:137], v167
	ds_read_b128 v[146:149], v166 offset:4096
	ds_read_b128 v[150:153], v167 offset:4096
	v_add_u32_e32 v166, s21, v246
	v_add_u32_e32 v167, s21, v247
	ds_read_b128 v[138:141], v166
	ds_read_b128 v[142:145], v167
	ds_read_b128 v[158:161], v166 offset:4096
	ds_read_b128 v[162:165], v167 offset:4096
	s_waitcnt vmcnt(2)
	s_barrier
	s_waitcnt lgkmcnt(0)
	v_mfma_f32_32x32x16_bf16 v[114:129], v[176:179], v[130:133], v[114:129]
	v_mfma_f32_32x32x16_bf16 v[82:97], v[176:179], v[146:149], v[82:97]
	v_mfma_f32_32x32x16_bf16 v[114:129], v[180:183], v[134:137], v[114:129]
	v_mfma_f32_32x32x16_bf16 v[82:97], v[180:183], v[150:153], v[82:97]
	v_mfma_f32_32x32x16_bf16 v[114:129], v[186:189], v[138:141], v[114:129]
	v_mfma_f32_32x32x16_bf16 v[82:97], v[186:189], v[158:161], v[82:97]
	v_mfma_f32_32x32x16_bf16 v[114:129], v[190:193], v[142:145], v[114:129]
	v_mfma_f32_32x32x16_bf16 v[82:97], v[190:193], v[162:165], v[82:97]
	s_barrier
	v_add_u32_e32 v166, s21, v202
	v_add_u32_e32 v167, s21, v203
	ds_read_b128 v[194:197], v166 offset:49152
	ds_read_b128 v[198:201], v167 offset:49152
	v_add_u32_e32 v166, s21, v175
	v_add_u32_e32 v167, s21, v185
	ds_read_b128 v[228:231], v166 offset:49152
	ds_read_b128 v[232:235], v167 offset:49152
	s_waitcnt vmcnt(0)
	s_barrier
	s_waitcnt lgkmcnt(0)
	v_mfma_f32_32x32x16_bf16 v[98:113], v[194:197], v[130:133], v[98:113]
	v_mfma_f32_32x32x16_bf16 v[66:81], v[194:197], v[146:149], v[66:81]
	v_mfma_f32_32x32x16_bf16 v[98:113], v[198:201], v[134:137], v[98:113]
	v_mfma_f32_32x32x16_bf16 v[66:81], v[198:201], v[150:153], v[66:81]
	v_mfma_f32_32x32x16_bf16 v[98:113], v[228:231], v[138:141], v[98:113]
	v_mfma_f32_32x32x16_bf16 v[66:81], v[228:231], v[158:161], v[66:81]
	v_mfma_f32_32x32x16_bf16 v[98:113], v[232:235], v[142:145], v[98:113]
	v_mfma_f32_32x32x16_bf16 v[66:81], v[232:235], v[162:165], v[66:81]
	s_barrier
	v_add_u32_e32 v166, s21, v244
	v_add_u32_e32 v167, s21, v245
	ds_read_b128 v[130:133], v166 offset:16384
	ds_read_b128 v[134:137], v167 offset:16384
	ds_read_b128 v[146:149], v166 offset:20480
	ds_read_b128 v[150:153], v167 offset:20480
	v_add_u32_e32 v166, s21, v246
	v_add_u32_e32 v167, s21, v247
	ds_read_b128 v[138:141], v166 offset:16384
	ds_read_b128 v[142:145], v167 offset:16384
	ds_read_b128 v[158:161], v166 offset:20480
	ds_read_b128 v[162:165], v167 offset:20480
	s_barrier
	s_waitcnt lgkmcnt(0)
	v_mfma_f32_32x32x16_bf16 v[50:65], v[176:179], v[130:133], v[50:65]
	v_mfma_f32_32x32x16_bf16 v[18:33], v[176:179], v[146:149], v[18:33]
	v_mfma_f32_32x32x16_bf16 v[50:65], v[180:183], v[134:137], v[50:65]
	v_mfma_f32_32x32x16_bf16 v[18:33], v[180:183], v[150:153], v[18:33]
	v_mfma_f32_32x32x16_bf16 v[50:65], v[186:189], v[138:141], v[50:65]
	v_mfma_f32_32x32x16_bf16 v[18:33], v[186:189], v[158:161], v[18:33]
	v_mfma_f32_32x32x16_bf16 v[50:65], v[190:193], v[142:145], v[50:65]
	v_mfma_f32_32x32x16_bf16 v[18:33], v[190:193], v[162:165], v[18:33]
	v_mfma_f32_32x32x16_bf16 v[34:49], v[194:197], v[130:133], v[34:49]
	v_mfma_f32_32x32x16_bf16 v[2:17], v[194:197], v[146:149], v[2:17]
	v_mfma_f32_32x32x16_bf16 v[34:49], v[198:201], v[134:137], v[34:49]
	v_mfma_f32_32x32x16_bf16 v[2:17], v[198:201], v[150:153], v[2:17]
	v_mfma_f32_32x32x16_bf16 v[34:49], v[228:231], v[138:141], v[34:49]
	v_mfma_f32_32x32x16_bf16 v[2:17], v[228:231], v[158:161], v[2:17]
	v_mfma_f32_32x32x16_bf16 v[34:49], v[232:235], v[142:145], v[34:49]
	v_mfma_f32_32x32x16_bf16 v[2:17], v[232:235], v[162:165], v[2:17]
	s_barrier
	s_cmp_eq_u32 s101, 0
	s_cbranch_scc0 .Lg8_u0m_p1
	s_barrier

; #define MFMA(a, b, c) __builtin_amdgcn_mfma_f32_32x32x16_bf16((a), (b), (c), 0, 0, 0)
; template <bool SWAP>
; DI void gemm_mainloop(f32x16 (&acc)[4][2], const u16* __restrict__ A, int lda, int rlo, int rhi,
;                       const u16* __restrict__ B, int ldb, int K, char* lds, const u16* zero_line) {
;     ...
;   auto ldfrag = [&](const char* st, int ks, int buf) {
;     const int co = ((2 * ks + h) ^ sw) << 4;
; #pragma unroll
;     for (int mi = 0; mi < 4; ++mi) fa[buf][mi] = *(const bf16x8*)(st + arow_off + mi * 4096 + co);
; #pragma unroll
;     for (int ni = 0; ni < 2; ++ni) fb[buf][ni] = *(const bf16x8*)(st + brow_off + ni * 4096 + co);
;   };
;   auto mma = [&](int buf) {
; #pragma unroll
;     for (int mi = 0; mi < 4; ++mi)
; #pragma unroll
;       for (int ni = 0; ni < 2; ++ni)
;         acc[mi][ni] = SWAP ? MFMA(fb[buf][ni], fa[buf][mi], acc[mi][ni]) : MFMA(fa[buf][mi], fb[buf][ni], acc[mi][ni]);
;   };
;   auto pat_rd = [&]() {
; #pragma unroll
;     for (int g = 0; g < 6; ++g) {
;       __builtin_amdgcn_sched_group_barrier(0x100, 1, 0);
;       __builtin_amdgcn_sched_group_barrier(0x008, 1, 0);
;     }
;     __builtin_amdgcn_sched_group_barrier(0x008, 2, 0);
;   };
; #pragma unroll 2
;   for (int kt = 0; kt < nk; ++kt) {
;     const char* st = lds + (kt & 1) * 65536;
;     ldfrag(st, 0, 0);
;     mma(1);
;     pat_rd();
;     if (kt + 1 < nk) glds(kt + 1, (kt + 1) & 1);
;     ldfrag(st, 1, 1);
;     mma(0);
;     pat_rd();
;     ldfrag(st, 2, 0);
;     mma(1);
;     pat_rd();
;     ldfrag(st, 3, 1);
;     mma(0);
;     pat_rd();
;     asm volatile("s_waitcnt vmcnt(0)" ::: "memory");
;     __syncthreads();
;   }
.Lg8_qa:
	ds_read_b128 v[130:133], v240
	ds_read_b128 v[134:137], v241
	ds_read_b128 v[138:141], v242
	ds_read_b128 v[142:145], v243
	ds_read_b128 v[146:149], v240 offset:4096
	ds_read_b128 v[150:153], v241 offset:4096
	ds_read_b128 v[156:159], v242 offset:4096
	ds_read_b128 v[160:163], v243 offset:4096
	s_add_u32 m0, s100, 0x14000
	s_nop 0
	global_load_lds_dwordx4 v233, s[6:7]
	v_add_u32_e32 v233, 0x80, v233
	s_add_u32 m0, s100, 0x16000
	s_nop 0
	global_load_lds_dwordx4 v235, s[6:7]
	v_add_u32_e32 v235, 0x80, v235
	s_barrier
	s_waitcnt lgkmcnt(0)
	v_mfma_f32_32x32x16_bf16 v[114:129], v[130:133], v[170:173], v[114:129]
	v_mfma_f32_32x32x16_bf16 v[82:97], v[146:149], v[170:173], v[82:97]
	v_mfma_f32_32x32x16_bf16 v[114:129], v[134:137], v[174:177], v[114:129]
	v_mfma_f32_32x32x16_bf16 v[82:97], v[150:153], v[174:177], v[82:97]
	v_mfma_f32_32x32x16_bf16 v[114:129], v[138:141], v[178:181], v[114:129]
	v_mfma_f32_32x32x16_bf16 v[82:97], v[156:159], v[178:181], v[82:97]
	v_mfma_f32_32x32x16_bf16 v[114:129], v[142:145], v[186:189], v[114:129]
	v_mfma_f32_32x32x16_bf16 v[82:97], v[160:163], v[186:189], v[82:97]
	s_barrier
	ds_read_b128 v[190:193], v164 offset:49152
	ds_read_b128 v[194:197], v165 offset:49152
	ds_read_b128 v[198:201], v202 offset:49152
	ds_read_b128 v[228:231], v203 offset:49152
	s_add_u32 m0, s100, 0x8000
	s_nop 0
	global_load_lds_dwordx4 v236, s[8:9]
	v_add_u32_e32 v236, 0x80, v236
	s_add_u32 m0, s100, 0xa000
	s_nop 0
	global_load_lds_dwordx4 v238, s[8:9]
	v_add_u32_e32 v238, 0x80, v238
	s_barrier
	s_waitcnt lgkmcnt(0)
	v_mfma_f32_32x32x16_bf16 v[98:113], v[130:133], v[190:193], v[98:113]
	v_mfma_f32_32x32x16_bf16 v[66:81], v[146:149], v[190:193], v[66:81]
	v_mfma_f32_32x32x16_bf16 v[98:113], v[134:137], v[194:197], v[98:113]
	v_mfma_f32_32x32x16_bf16 v[66:81], v[150:153], v[194:197], v[66:81]
	v_mfma_f32_32x32x16_bf16 v[98:113], v[138:141], v[198:201], v[98:113]
	v_mfma_f32_32x32x16_bf16 v[66:81], v[156:159], v[198:201], v[66:81]
	v_mfma_f32_32x32x16_bf16 v[98:113], v[142:145], v[228:231], v[98:113]
	v_mfma_f32_32x32x16_bf16 v[66:81], v[160:163], v[228:231], v[66:81]
	s_barrier
	ds_read_b128 v[130:133], v240 offset:16384
	ds_read_b128 v[134:137], v241 offset:16384
	ds_read_b128 v[138:141], v242 offset:16384
	ds_read_b128 v[142:145], v243 offset:16384
	ds_read_b128 v[146:149], v240 offset:20480
	ds_read_b128 v[150:153], v241 offset:20480
	ds_read_b128 v[156:159], v242 offset:20480
	ds_read_b128 v[160:163], v243 offset:20480
	s_add_u32 m0, s100, 0x0
	s_nop 0
	global_load_lds_dwordx4 v232, s[6:7]
	v_add_u32_e32 v232, 0x80, v232
	s_add_u32 m0, s100, 0x2000
	s_nop 0
	global_load_lds_dwordx4 v234, s[6:7]
	v_add_u32_e32 v234, 0x80, v234
	s_waitcnt vmcnt(10)
	s_barrier
	s_waitcnt lgkmcnt(0)
	v_mfma_f32_32x32x16_bf16 v[50:65], v[130:133], v[170:173], v[50:65]
	v_mfma_f32_32x32x16_bf16 v[18:33], v[146:149], v[170:173], v[18:33]
	v_mfma_f32_32x32x16_bf16 v[50:65], v[134:137], v[174:177], v[50:65]
	v_mfma_f32_32x32x16_bf16 v[18:33], v[150:153], v[174:177], v[18:33]
	v_mfma_f32_32x32x16_bf16 v[50:65], v[138:141], v[178:181], v[50:65]
	v_mfma_f32_32x32x16_bf16 v[18:33], v[156:159], v[178:181], v[18:33]
	v_mfma_f32_32x32x16_bf16 v[50:65], v[142:145], v[186:189], v[50:65]
	v_mfma_f32_32x32x16_bf16 v[18:33], v[160:163], v[186:189], v[18:33]
	s_barrier
	v_add_u32_e32 v246, s10, v164
	v_add_u32_e32 v247, s10, v165
	v_add_u32_e32 v248, s10, v202
	v_add_u32_e32 v249, s10, v203
	ds_read_b128 v[170:173], v246 offset:32768
	ds_read_b128 v[174:177], v247 offset:32768
	ds_read_b128 v[178:181], v248 offset:32768
	ds_read_b128 v[186:189], v249 offset:32768
	s_add_u32 m0, s100, 0xc000
	s_nop 0
	global_load_lds_dwordx4 v237, s[8:9]
	v_add_u32_e32 v237, 0x80, v237
	s_add_u32 m0, s100, 0xe000
	s_nop 0
	global_load_lds_dwordx4 v239, s[8:9]
	v_add_u32_e32 v239, 0x80, v239
	s_waitcnt vmcnt(6)
	s_barrier
	s_waitcnt lgkmcnt(0)
	v_mfma_f32_32x32x16_bf16 v[34:49], v[130:133], v[190:193], v[34:49]
	v_mfma_f32_32x32x16_bf16 v[2:17], v[146:149], v[190:193], v[2:17]
	v_mfma_f32_32x32x16_bf16 v[34:49], v[134:137], v[194:197], v[34:49]
	v_mfma_f32_32x32x16_bf16 v[2:17], v[150:153], v[194:197], v[2:17]
	v_mfma_f32_32x32x16_bf16 v[34:49], v[138:141], v[198:201], v[34:49]
	v_mfma_f32_32x32x16_bf16 v[2:17], v[156:159], v[198:201], v[2:17]
	v_mfma_f32_32x32x16_bf16 v[34:49], v[142:145], v[228:231], v[34:49]
	v_mfma_f32_32x32x16_bf16 v[2:17], v[160:163], v[228:231], v[2:17]
	s_barrier
	v_add_u32_e32 v246, s10, v240
	v_add_u32_e32 v247, s10, v241
	v_add_u32_e32 v248, s10, v242
	v_add_u32_e32 v249, s10, v243
	ds_read_b128 v[130:133], v246
	ds_read_b128 v[134:137], v247
	ds_read_b128 v[138:141], v248
	ds_read_b128 v[142:145], v249
	ds_read_b128 v[146:149], v246 offset:4096
	ds_read_b128 v[150:153], v247 offset:4096
	ds_read_b128 v[156:159], v248 offset:4096
	ds_read_b128 v[160:163], v249 offset:4096
	s_add_u32 m0, s100, 0x4000
	s_nop 0
	global_load_lds_dwordx4 v233, s[6:7]
	v_add_u32_e32 v233, 0x80, v233
	s_add_u32 m0, s100, 0x6000
	s_nop 0
	global_load_lds_dwordx4 v235, s[6:7]
	v_add_u32_e32 v235, 0x80, v235
	s_barrier
	s_waitcnt lgkmcnt(0)
	v_mfma_f32_32x32x16_bf16 v[114:129], v[130:133], v[170:173], v[114:129]
	v_mfma_f32_32x32x16_bf16 v[82:97], v[146:149], v[170:173], v[82:97]
	v_mfma_f32_32x32x16_bf16 v[114:129], v[134:137], v[174:177], v[114:129]
	v_mfma_f32_32x32x16_bf16 v[82:97], v[150:153], v[174:177], v[82:97]
	v_mfma_f32_32x32x16_bf16 v[114:129], v[138:141], v[178:181], v[114:129]
	v_mfma_f32_32x32x16_bf16 v[82:97], v[156:159], v[178:181], v[82:97]
	v_mfma_f32_32x32x16_bf16 v[114:129], v[142:145], v[186:189], v[114:129]
	v_mfma_f32_32x32x16_bf16 v[82:97], v[160:163], v[186:189], v[82:97]
	s_barrier
; template <bool SWAP>
; DI void gemm_mainloop(f32x16 (&acc)[4][2], const u16* __restrict__ A, int lda, int rlo, int rhi,
;                       const u16* __restrict__ B, int ldb, int K, char* lds, const u16* zero_line) {
;     ...
; #pragma unroll 2
;   for (int kt = 0; kt < nk; ++kt) {
;     const char* st = lds + (kt & 1) * 65536;
;     ldfrag(st, 0, 0);
;     mma(1);
;     pat_rd();
;     if (kt + 1 < nk) glds(kt + 1, (kt + 1) & 1);
;     ldfrag(st, 1, 1);
;     mma(0);
;     pat_rd();
;     ldfrag(st, 2, 0);
;     mma(1);
;     pat_rd();
;     ldfrag(st, 3, 1);
;     mma(0);
;     pat_rd();
;     asm volatile("s_waitcnt vmcnt(0)" ::: "memory");
;     __syncthreads();
;   }
;   mma(1);
	v_add_u32_e32 v246, s10, v164
	v_add_u32_e32 v247, s10, v165
	v_add_u32_e32 v248, s10, v202
	v_add_u32_e32 v249, s10, v203
	ds_read_b128 v[190:193], v246 offset:49152
	ds_read_b128 v[194:197], v247 offset:49152
	ds_read_b128 v[198:201], v248 offset:49152
	ds_read_b128 v[228:231], v249 offset:49152
	s_add_u32 m0, s100, 0x18000
	s_nop 0
	global_load_lds_dwordx4 v236, s[8:9]
	v_add_u32_e32 v236, 0x80, v236
	s_add_u32 m0, s100, 0x1a000
	s_nop 0
	global_load_lds_dwordx4 v238, s[8:9]
	v_add_u32_e32 v238, 0x80, v238
	s_barrier
	s_waitcnt lgkmcnt(0)
	v_mfma_f32_32x32x16_bf16 v[98:113], v[130:133], v[190:193], v[98:113]
	v_mfma_f32_32x32x16_bf16 v[66:81], v[146:149], v[190:193], v[66:81]
	v_mfma_f32_32x32x16_bf16 v[98:113], v[134:137], v[194:197], v[98:113]
	v_mfma_f32_32x32x16_bf16 v[66:81], v[150:153], v[194:197], v[66:81]
	v_mfma_f32_32x32x16_bf16 v[98:113], v[138:141], v[198:201], v[98:113]
	v_mfma_f32_32x32x16_bf16 v[66:81], v[156:159], v[198:201], v[66:81]
	v_mfma_f32_32x32x16_bf16 v[98:113], v[142:145], v[228:231], v[98:113]
	v_mfma_f32_32x32x16_bf16 v[66:81], v[160:163], v[228:231], v[66:81]
	s_barrier
	v_add_u32_e32 v246, s10, v240
	v_add_u32_e32 v247, s10, v241
	v_add_u32_e32 v248, s10, v242
	v_add_u32_e32 v249, s10, v243
	ds_read_b128 v[130:133], v246 offset:16384
	ds_read_b128 v[134:137], v247 offset:16384
	ds_read_b128 v[138:141], v248 offset:16384
	ds_read_b128 v[142:145], v249 offset:16384
	ds_read_b128 v[146:149], v246 offset:20480
	ds_read_b128 v[150:153], v247 offset:20480
	ds_read_b128 v[156:159], v248 offset:20480
	ds_read_b128 v[160:163], v249 offset:20480
	s_add_u32 m0, s100, 0x10000
	s_nop 0
	global_load_lds_dwordx4 v232, s[6:7]
	v_add_u32_e32 v232, 0x80, v232
	s_add_u32 m0, s100, 0x12000
	s_nop 0
	global_load_lds_dwordx4 v234, s[6:7]
	v_add_u32_e32 v234, 0x80, v234
	s_waitcnt vmcnt(10)
	s_barrier
	s_waitcnt lgkmcnt(0)
	v_mfma_f32_32x32x16_bf16 v[50:65], v[130:133], v[170:173], v[50:65]
	v_mfma_f32_32x32x16_bf16 v[18:33], v[146:149], v[170:173], v[18:33]
	v_mfma_f32_32x32x16_bf16 v[50:65], v[134:137], v[174:177], v[50:65]
	v_mfma_f32_32x32x16_bf16 v[18:33], v[150:153], v[174:177], v[18:33]
	v_mfma_f32_32x32x16_bf16 v[50:65], v[138:141], v[178:181], v[50:65]
	v_mfma_f32_32x32x16_bf16 v[18:33], v[156:159], v[178:181], v[18:33]
	v_mfma_f32_32x32x16_bf16 v[50:65], v[142:145], v[186:189], v[50:65]
	v_mfma_f32_32x32x16_bf16 v[18:33], v[160:163], v[186:189], v[18:33]
	s_barrier
	ds_read_b128 v[170:173], v164 offset:32768
	ds_read_b128 v[174:177], v165 offset:32768
	ds_read_b128 v[178:181], v202 offset:32768
	ds_read_b128 v[186:189], v203 offset:32768
	s_add_u32 m0, s100, 0x1c000
	s_nop 0
	global_load_lds_dwordx4 v237, s[8:9]
	v_add_u32_e32 v237, 0x80, v237
	s_add_u32 m0, s100, 0x1e000
	s_nop 0
	global_load_lds_dwordx4 v239, s[8:9]
	v_add_u32_e32 v239, 0x80, v239
	s_waitcnt vmcnt(6)
	s_barrier
	s_waitcnt lgkmcnt(0)
	v_mfma_f32_32x32x16_bf16 v[34:49], v[130:133], v[190:193], v[34:49]
	v_mfma_f32_32x32x16_bf16 v[2:17], v[146:149], v[190:193], v[2:17]
	v_mfma_f32_32x32x16_bf16 v[34:49], v[134:137], v[194:197], v[34:49]
	v_mfma_f32_32x32x16_bf16 v[2:17], v[150:153], v[194:197], v[2:17]
	v_mfma_f32_32x32x16_bf16 v[34:49], v[138:141], v[198:201], v[34:49]
	v_mfma_f32_32x32x16_bf16 v[2:17], v[156:159], v[198:201], v[2:17]
	v_mfma_f32_32x32x16_bf16 v[34:49], v[142:145], v[228:231], v[34:49]
	v_mfma_f32_32x32x16_bf16 v[2:17], v[160:163], v[228:231], v[2:17]
	s_add_i32 s11, s11, 2
	s_cmp_lt_u32 s11, 14
	s_barrier
	s_cbranch_scc1 .Lg8_qa
	ds_read_b128 v[130:133], v240
	ds_read_b128 v[134:137], v241
	ds_read_b128 v[138:141], v242
	ds_read_b128 v[142:145], v243
	ds_read_b128 v[146:149], v240 offset:4096
	ds_read_b128 v[150:153], v241 offset:4096
	ds_read_b128 v[156:159], v242 offset:4096
	ds_read_b128 v[160:163], v243 offset:4096
	s_add_u32 m0, s100, 0x14000
	s_nop 0
	global_load_lds_dwordx4 v233, s[6:7]
	v_add_u32_e32 v233, 0x80, v233
	s_add_u32 m0, s100, 0x16000
	s_nop 0
	global_load_lds_dwordx4 v235, s[6:7]
	v_add_u32_e32 v235, 0x80, v235
	s_barrier
	s_waitcnt lgkmcnt(0)
	v_mfma_f32_32x32x16_bf16 v[114:129], v[130:133], v[170:173], v[114:129]
	v_mfma_f32_32x32x16_bf16 v[82:97], v[146:149], v[170:173], v[82:97]
	v_mfma_f32_32x32x16_bf16 v[114:129], v[134:137], v[174:177], v[114:129]
	v_mfma_f32_32x32x16_bf16 v[82:97], v[150:153], v[174:177], v[82:97]
	v_mfma_f32_32x32x16_bf16 v[114:129], v[138:141], v[178:181], v[114:129]
	v_mfma_f32_32x32x16_bf16 v[82:97], v[156:159], v[178:181], v[82:97]
	v_mfma_f32_32x32x16_bf16 v[114:129], v[142:145], v[186:189], v[114:129]
	v_mfma_f32_32x32x16_bf16 v[82:97], v[160:163], v[186:189], v[82:97]
	s_barrier
	ds_read_b128 v[190:193], v164 offset:49152
	ds_read_b128 v[194:197], v165 offset:49152
	ds_read_b128 v[198:201], v202 offset:49152
	ds_read_b128 v[228:231], v203 offset:49152
	s_barrier
	s_waitcnt lgkmcnt(0)
	v_mfma_f32_32x32x16_bf16 v[98:113], v[130:133], v[190:193], v[98:113]
	v_mfma_f32_32x32x16_bf16 v[66:81], v[146:149], v[190:193], v[66:81]
	v_mfma_f32_32x32x16_bf16 v[98:113], v[134:137], v[194:197], v[98:113]
	v_mfma_f32_32x32x16_bf16 v[66:81], v[150:153], v[194:197], v[66:81]
	v_mfma_f32_32x32x16_bf16 v[98:113], v[138:141], v[198:201], v[98:113]
	v_mfma_f32_32x32x16_bf16 v[66:81], v[156:159], v[198:201], v[66:81]
	v_mfma_f32_32x32x16_bf16 v[98:113], v[142:145], v[228:231], v[98:113]
	v_mfma_f32_32x32x16_bf16 v[66:81], v[160:163], v[228:231], v[66:81]
	s_barrier
; template <bool SWAP>
; DI void gemm_mainloop(f32x16 (&acc)[4][2], const u16* __restrict__ A, int lda, int rlo, int rhi,
;                       const u16* __restrict__ B, int ldb, int K, char* lds, const u16* zero_line) {
;     ...
; #pragma unroll 2
;   for (int kt = 0; kt < nk; ++kt) {
;     const char* st = lds + (kt & 1) * 65536;
;     ldfrag(st, 0, 0);
;     mma(1);
;     pat_rd();
;     if (kt + 1 < nk) glds(kt + 1, (kt + 1) & 1);
;     ldfrag(st, 1, 1);
;     mma(0);
;     pat_rd();
;     ldfrag(st, 2, 0);
;     mma(1);
;     pat_rd();
;     ldfrag(st, 3, 1);
;     mma(0);
;     pat_rd();
;     asm volatile("s_waitcnt vmcnt(0)" ::: "memory");
;     __syncthreads();
;   }
;   mma(1);
	ds_read_b128 v[130:133], v240 offset:16384
	ds_read_b128 v[134:137], v241 offset:16384
	ds_read_b128 v[138:141], v242 offset:16384
	ds_read_b128 v[142:145], v243 offset:16384
	ds_read_b128 v[146:149], v240 offset:20480
	ds_read_b128 v[150:153], v241 offset:20480
	ds_read_b128 v[156:159], v242 offset:20480
	ds_read_b128 v[160:163], v243 offset:20480
	s_waitcnt vmcnt(4)
	s_barrier
	s_waitcnt lgkmcnt(0)
	v_mfma_f32_32x32x16_bf16 v[50:65], v[130:133], v[170:173], v[50:65]
	v_mfma_f32_32x32x16_bf16 v[18:33], v[146:149], v[170:173], v[18:33]
	v_mfma_f32_32x32x16_bf16 v[50:65], v[134:137], v[174:177], v[50:65]
	v_mfma_f32_32x32x16_bf16 v[18:33], v[150:153], v[174:177], v[18:33]
	v_mfma_f32_32x32x16_bf16 v[50:65], v[138:141], v[178:181], v[50:65]
	v_mfma_f32_32x32x16_bf16 v[18:33], v[156:159], v[178:181], v[18:33]
	v_mfma_f32_32x32x16_bf16 v[50:65], v[142:145], v[186:189], v[50:65]
	v_mfma_f32_32x32x16_bf16 v[18:33], v[160:163], v[186:189], v[18:33]
	v_mfma_f32_32x32x16_bf16 v[34:49], v[130:133], v[190:193], v[34:49]
	v_mfma_f32_32x32x16_bf16 v[2:17], v[146:149], v[190:193], v[2:17]
	v_mfma_f32_32x32x16_bf16 v[34:49], v[134:137], v[194:197], v[34:49]
	v_mfma_f32_32x32x16_bf16 v[2:17], v[150:153], v[194:197], v[2:17]
	v_mfma_f32_32x32x16_bf16 v[34:49], v[138:141], v[198:201], v[34:49]
	v_mfma_f32_32x32x16_bf16 v[2:17], v[156:159], v[198:201], v[2:17]
	v_mfma_f32_32x32x16_bf16 v[34:49], v[142:145], v[228:231], v[34:49]
	v_mfma_f32_32x32x16_bf16 v[2:17], v[160:163], v[228:231], v[2:17]
	s_barrier
	v_add_u32_e32 v246, s10, v164
	v_add_u32_e32 v247, s10, v165
	v_add_u32_e32 v248, s10, v202
	v_add_u32_e32 v249, s10, v203
	ds_read_b128 v[170:173], v246 offset:32768
	ds_read_b128 v[174:177], v247 offset:32768
	ds_read_b128 v[178:181], v248 offset:32768
	ds_read_b128 v[186:189], v249 offset:32768
	v_add_u32_e32 v246, s10, v240
	v_add_u32_e32 v247, s10, v241
	v_add_u32_e32 v248, s10, v242
	v_add_u32_e32 v249, s10, v243
	ds_read_b128 v[130:133], v246
	ds_read_b128 v[134:137], v247
	ds_read_b128 v[138:141], v248
	ds_read_b128 v[142:145], v249
	ds_read_b128 v[146:149], v246 offset:4096
	ds_read_b128 v[150:153], v247 offset:4096
	ds_read_b128 v[156:159], v248 offset:4096
	ds_read_b128 v[160:163], v249 offset:4096
	s_waitcnt vmcnt(2)
	s_barrier
	s_waitcnt lgkmcnt(0)
	v_mfma_f32_32x32x16_bf16 v[114:129], v[130:133], v[170:173], v[114:129]
	v_mfma_f32_32x32x16_bf16 v[82:97], v[146:149], v[170:173], v[82:97]
	v_mfma_f32_32x32x16_bf16 v[114:129], v[134:137], v[174:177], v[114:129]
	v_mfma_f32_32x32x16_bf16 v[82:97], v[150:153], v[174:177], v[82:97]
	v_mfma_f32_32x32x16_bf16 v[114:129], v[138:141], v[178:181], v[114:129]
	v_mfma_f32_32x32x16_bf16 v[82:97], v[156:159], v[178:181], v[82:97]
	v_mfma_f32_32x32x16_bf16 v[114:129], v[142:145], v[186:189], v[114:129]
	v_mfma_f32_32x32x16_bf16 v[82:97], v[160:163], v[186:189], v[82:97]
	s_barrier
	v_add_u32_e32 v246, s10, v164
	v_add_u32_e32 v247, s10, v165
	v_add_u32_e32 v248, s10, v202
	v_add_u32_e32 v249, s10, v203
	ds_read_b128 v[190:193], v246 offset:49152
	ds_read_b128 v[194:197], v247 offset:49152
	ds_read_b128 v[198:201], v248 offset:49152
	ds_read_b128 v[228:231], v249 offset:49152
	s_waitcnt vmcnt(0)
	s_barrier
	s_waitcnt lgkmcnt(0)
	v_mfma_f32_32x32x16_bf16 v[98:113], v[130:133], v[190:193], v[98:113]
	v_mfma_f32_32x32x16_bf16 v[66:81], v[146:149], v[190:193], v[66:81]
	v_mfma_f32_32x32x16_bf16 v[98:113], v[134:137], v[194:197], v[98:113]
	v_mfma_f32_32x32x16_bf16 v[66:81], v[150:153], v[194:197], v[66:81]
	v_mfma_f32_32x32x16_bf16 v[98:113], v[138:141], v[198:201], v[98:113]
	v_mfma_f32_32x32x16_bf16 v[66:81], v[156:159], v[198:201], v[66:81]
	v_mfma_f32_32x32x16_bf16 v[98:113], v[142:145], v[228:231], v[98:113]
	v_mfma_f32_32x32x16_bf16 v[66:81], v[160:163], v[228:231], v[66:81]
	s_barrier
	v_add_u32_e32 v246, s10, v240
	v_add_u32_e32 v247, s10, v241
	v_add_u32_e32 v248, s10, v242
	v_add_u32_e32 v249, s10, v243
	ds_read_b128 v[130:133], v246 offset:16384
	ds_read_b128 v[134:137], v247 offset:16384
	ds_read_b128 v[138:141], v248 offset:16384
	ds_read_b128 v[142:145], v249 offset:16384
	ds_read_b128 v[146:149], v246 offset:20480
	ds_read_b128 v[150:153], v247 offset:20480
	ds_read_b128 v[156:159], v248 offset:20480
	ds_read_b128 v[160:163], v249 offset:20480
	s_barrier
	s_waitcnt lgkmcnt(0)
	v_mfma_f32_32x32x16_bf16 v[50:65], v[130:133], v[170:173], v[50:65]
	v_mfma_f32_32x32x16_bf16 v[18:33], v[146:149], v[170:173], v[18:33]
	v_mfma_f32_32x32x16_bf16 v[50:65], v[134:137], v[174:177], v[50:65]
	v_mfma_f32_32x32x16_bf16 v[18:33], v[150:153], v[174:177], v[18:33]
	v_mfma_f32_32x32x16_bf16 v[50:65], v[138:141], v[178:181], v[50:65]
	v_mfma_f32_32x32x16_bf16 v[18:33], v[156:159], v[178:181], v[18:33]
	v_mfma_f32_32x32x16_bf16 v[50:65], v[142:145], v[186:189], v[50:65]
	v_mfma_f32_32x32x16_bf16 v[18:33], v[160:163], v[186:189], v[18:33]
	v_mfma_f32_32x32x16_bf16 v[34:49], v[130:133], v[190:193], v[34:49]
	v_mfma_f32_32x32x16_bf16 v[2:17], v[146:149], v[190:193], v[2:17]
	v_mfma_f32_32x32x16_bf16 v[34:49], v[134:137], v[194:197], v[34:49]
	v_mfma_f32_32x32x16_bf16 v[2:17], v[150:153], v[194:197], v[2:17]
	v_mfma_f32_32x32x16_bf16 v[34:49], v[138:141], v[198:201], v[34:49]
	v_mfma_f32_32x32x16_bf16 v[2:17], v[156:159], v[198:201], v[2:17]
	v_mfma_f32_32x32x16_bf16 v[34:49], v[142:145], v[228:231], v[34:49]
	v_mfma_f32_32x32x16_bf16 v[2:17], v[160:163], v[228:231], v[2:17]
	s_barrier
	s_cmp_eq_u32 s101, 0
	s_cbranch_scc0 .Lg8_qa_p1
	s_barrier

; #define MFMA(a, b, c) __builtin_amdgcn_mfma_f32_32x32x16_bf16((a), (b), (c), 0, 0, 0)
; template <bool SWAP>
; DI void gemm_mainloop(f32x16 (&acc)[4][2], const u16* __restrict__ A, int lda, int rlo, int rhi,
;                       const u16* __restrict__ B, int ldb, int K, char* lds, const u16* zero_line) {
;     ...
;   auto ldfrag = [&](const char* st, int ks, int buf) {
;     const int co = ((2 * ks + h) ^ sw) << 4;
; #pragma unroll
;     for (int mi = 0; mi < 4; ++mi) fa[buf][mi] = *(const bf16x8*)(st + arow_off + mi * 4096 + co);
; #pragma unroll
;     for (int ni = 0; ni < 2; ++ni) fb[buf][ni] = *(const bf16x8*)(st + brow_off + ni * 4096 + co);
;   };
;   auto mma = [&](int buf) {
; #pragma unroll
;     for (int mi = 0; mi < 4; ++mi)
; #pragma unroll
;       for (int ni = 0; ni < 2; ++ni)
;         acc[mi][ni] = SWAP ? MFMA(fb[buf][ni], fa[buf][mi], acc[mi][ni]) : MFMA(fa[buf][mi], fb[buf][ni], acc[mi][ni]);
;   };
;   auto pat_rd = [&]() {
; #pragma unroll
;     for (int g = 0; g < 6; ++g) {
;       __builtin_amdgcn_sched_group_barrier(0x100, 1, 0);
;       __builtin_amdgcn_sched_group_barrier(0x008, 1, 0);
;     }
;     __builtin_amdgcn_sched_group_barrier(0x008, 2, 0);
;   };
; #pragma unroll 2
;   for (int kt = 0; kt < nk; ++kt) {
;     const char* st = lds + (kt & 1) * 65536;
;     ldfrag(st, 0, 0);
;     mma(1);
;     pat_rd();
;     if (kt + 1 < nk) glds(kt + 1, (kt + 1) & 1);
;     ldfrag(st, 1, 1);
;     mma(0);
;     pat_rd();
;     ldfrag(st, 2, 0);
;     mma(1);
;     pat_rd();
;     ldfrag(st, 3, 1);
;     mma(0);
;     pat_rd();
;     asm volatile("s_waitcnt vmcnt(0)" ::: "memory");
;     __syncthreads();
;   }
.Lg8_qb:
	ds_read_b128 v[130:133], v240
	ds_read_b128 v[134:137], v241
	ds_read_b128 v[138:141], v242
	ds_read_b128 v[142:145], v243
	ds_read_b128 v[146:149], v240 offset:4096
	ds_read_b128 v[150:153], v241 offset:4096
	ds_read_b128 v[156:159], v242 offset:4096
	ds_read_b128 v[160:163], v243 offset:4096
	s_add_u32 m0, s100, 0x14000
	s_nop 0
	global_load_lds_dwordx4 v233, s[6:7]
	v_add_u32_e32 v233, 0x80, v233
	s_add_u32 m0, s100, 0x16000
	s_nop 0
	global_load_lds_dwordx4 v235, s[6:7]
	v_add_u32_e32 v235, 0x80, v235
	s_barrier
	s_waitcnt lgkmcnt(0)
	v_mfma_f32_32x32x16_bf16 v[114:129], v[170:173], v[130:133], v[114:129]
	v_mfma_f32_32x32x16_bf16 v[82:97], v[170:173], v[146:149], v[82:97]
	v_mfma_f32_32x32x16_bf16 v[114:129], v[174:177], v[134:137], v[114:129]
	v_mfma_f32_32x32x16_bf16 v[82:97], v[174:177], v[150:153], v[82:97]
	v_mfma_f32_32x32x16_bf16 v[114:129], v[178:181], v[138:141], v[114:129]
	v_mfma_f32_32x32x16_bf16 v[82:97], v[178:181], v[156:159], v[82:97]
	v_mfma_f32_32x32x16_bf16 v[114:129], v[186:189], v[142:145], v[114:129]
	v_mfma_f32_32x32x16_bf16 v[82:97], v[186:189], v[160:163], v[82:97]
	s_barrier
	ds_read_b128 v[190:193], v164 offset:49152
	ds_read_b128 v[194:197], v165 offset:49152
	ds_read_b128 v[198:201], v202 offset:49152
	ds_read_b128 v[228:231], v203 offset:49152
	s_add_u32 m0, s100, 0x8000
	s_nop 0
	global_load_lds_dwordx4 v236, s[8:9]
	v_add_u32_e32 v236, 0x80, v236
	s_add_u32 m0, s100, 0xa000
	s_nop 0
	global_load_lds_dwordx4 v238, s[8:9]
	v_add_u32_e32 v238, 0x80, v238
	s_barrier
	s_waitcnt lgkmcnt(0)
	v_mfma_f32_32x32x16_bf16 v[98:113], v[190:193], v[130:133], v[98:113]
	v_mfma_f32_32x32x16_bf16 v[66:81], v[190:193], v[146:149], v[66:81]
	v_mfma_f32_32x32x16_bf16 v[98:113], v[194:197], v[134:137], v[98:113]
	v_mfma_f32_32x32x16_bf16 v[66:81], v[194:197], v[150:153], v[66:81]
	v_mfma_f32_32x32x16_bf16 v[98:113], v[198:201], v[138:141], v[98:113]
	v_mfma_f32_32x32x16_bf16 v[66:81], v[198:201], v[156:159], v[66:81]
	v_mfma_f32_32x32x16_bf16 v[98:113], v[228:231], v[142:145], v[98:113]
	v_mfma_f32_32x32x16_bf16 v[66:81], v[228:231], v[160:163], v[66:81]
	s_barrier
	ds_read_b128 v[130:133], v240 offset:16384
	ds_read_b128 v[134:137], v241 offset:16384
	ds_read_b128 v[138:141], v242 offset:16384
	ds_read_b128 v[142:145], v243 offset:16384
	ds_read_b128 v[146:149], v240 offset:20480
	ds_read_b128 v[150:153], v241 offset:20480
	ds_read_b128 v[156:159], v242 offset:20480
	ds_read_b128 v[160:163], v243 offset:20480
	s_add_u32 m0, s100, 0x0
	s_nop 0
	global_load_lds_dwordx4 v232, s[6:7]
	v_add_u32_e32 v232, 0x80, v232
	s_add_u32 m0, s100, 0x2000
	s_nop 0
	global_load_lds_dwordx4 v234, s[6:7]
	v_add_u32_e32 v234, 0x80, v234
	s_waitcnt vmcnt(10)
	s_barrier
	s_waitcnt lgkmcnt(0)
	v_mfma_f32_32x32x16_bf16 v[50:65], v[170:173], v[130:133], v[50:65]
	v_mfma_f32_32x32x16_bf16 v[18:33], v[170:173], v[146:149], v[18:33]
	v_mfma_f32_32x32x16_bf16 v[50:65], v[174:177], v[134:137], v[50:65]
	v_mfma_f32_32x32x16_bf16 v[18:33], v[174:177], v[150:153], v[18:33]
	v_mfma_f32_32x32x16_bf16 v[50:65], v[178:181], v[138:141], v[50:65]
	v_mfma_f32_32x32x16_bf16 v[18:33], v[178:181], v[156:159], v[18:33]
	v_mfma_f32_32x32x16_bf16 v[50:65], v[186:189], v[142:145], v[50:65]
	v_mfma_f32_32x32x16_bf16 v[18:33], v[186:189], v[160:163], v[18:33]
	s_barrier
	v_add_u32_e32 v246, s10, v164
	v_add_u32_e32 v247, s10, v165
	v_add_u32_e32 v248, s10, v202
	v_add_u32_e32 v249, s10, v203
	ds_read_b128 v[170:173], v246 offset:32768
	ds_read_b128 v[174:177], v247 offset:32768
	ds_read_b128 v[178:181], v248 offset:32768
	ds_read_b128 v[186:189], v249 offset:32768
	s_add_u32 m0, s100, 0xc000
	s_nop 0
	global_load_lds_dwordx4 v237, s[8:9]
	v_add_u32_e32 v237, 0x80, v237
	s_add_u32 m0, s100, 0xe000
	s_nop 0
	global_load_lds_dwordx4 v239, s[8:9]
	v_add_u32_e32 v239, 0x80, v239
	s_waitcnt vmcnt(6)
	s_barrier
	s_waitcnt lgkmcnt(0)
	v_mfma_f32_32x32x16_bf16 v[34:49], v[190:193], v[130:133], v[34:49]
	v_mfma_f32_32x32x16_bf16 v[2:17], v[190:193], v[146:149], v[2:17]
	v_mfma_f32_32x32x16_bf16 v[34:49], v[194:197], v[134:137], v[34:49]
	v_mfma_f32_32x32x16_bf16 v[2:17], v[194:197], v[150:153], v[2:17]
	v_mfma_f32_32x32x16_bf16 v[34:49], v[198:201], v[138:141], v[34:49]
	v_mfma_f32_32x32x16_bf16 v[2:17], v[198:201], v[156:159], v[2:17]
	v_mfma_f32_32x32x16_bf16 v[34:49], v[228:231], v[142:145], v[34:49]
	v_mfma_f32_32x32x16_bf16 v[2:17], v[228:231], v[160:163], v[2:17]
	s_barrier
	v_add_u32_e32 v246, s10, v240
	v_add_u32_e32 v247, s10, v241
	v_add_u32_e32 v248, s10, v242
	v_add_u32_e32 v249, s10, v243
	ds_read_b128 v[130:133], v246
	ds_read_b128 v[134:137], v247
	ds_read_b128 v[138:141], v248
	ds_read_b128 v[142:145], v249
	ds_read_b128 v[146:149], v246 offset:4096
	ds_read_b128 v[150:153], v247 offset:4096
	ds_read_b128 v[156:159], v248 offset:4096
	ds_read_b128 v[160:163], v249 offset:4096
	s_add_u32 m0, s100, 0x4000
	s_nop 0
	global_load_lds_dwordx4 v233, s[6:7]
	v_add_u32_e32 v233, 0x80, v233
	s_add_u32 m0, s100, 0x6000
	s_nop 0
	global_load_lds_dwordx4 v235, s[6:7]
	v_add_u32_e32 v235, 0x80, v235
	s_barrier
	s_waitcnt lgkmcnt(0)
	v_mfma_f32_32x32x16_bf16 v[114:129], v[170:173], v[130:133], v[114:129]
	v_mfma_f32_32x32x16_bf16 v[82:97], v[170:173], v[146:149], v[82:97]
	v_mfma_f32_32x32x16_bf16 v[114:129], v[174:177], v[134:137], v[114:129]
	v_mfma_f32_32x32x16_bf16 v[82:97], v[174:177], v[150:153], v[82:97]
	v_mfma_f32_32x32x16_bf16 v[114:129], v[178:181], v[138:141], v[114:129]
	v_mfma_f32_32x32x16_bf16 v[82:97], v[178:181], v[156:159], v[82:97]
	v_mfma_f32_32x32x16_bf16 v[114:129], v[186:189], v[142:145], v[114:129]
	v_mfma_f32_32x32x16_bf16 v[82:97], v[186:189], v[160:163], v[82:97]
	s_barrier
; template <bool SWAP>
; DI void gemm_mainloop(f32x16 (&acc)[4][2], const u16* __restrict__ A, int lda, int rlo, int rhi,
;                       const u16* __restrict__ B, int ldb, int K, char* lds, const u16* zero_line) {
;     ...
; #pragma unroll 2
;   for (int kt = 0; kt < nk; ++kt) {
;     const char* st = lds + (kt & 1) * 65536;
;     ldfrag(st, 0, 0);
;     mma(1);
;     pat_rd();
;     if (kt + 1 < nk) glds(kt + 1, (kt + 1) & 1);
;     ldfrag(st, 1, 1);
;     mma(0);
;     pat_rd();
;     ldfrag(st, 2, 0);
;     mma(1);
;     pat_rd();
;     ldfrag(st, 3, 1);
;     mma(0);
;     pat_rd();
;     asm volatile("s_waitcnt vmcnt(0)" ::: "memory");
;     __syncthreads();
;   }
;   mma(1);
	v_add_u32_e32 v246, s10, v164
	v_add_u32_e32 v247, s10, v165
	v_add_u32_e32 v248, s10, v202
	v_add_u32_e32 v249, s10, v203
	ds_read_b128 v[190:193], v246 offset:49152
	ds_read_b128 v[194:197], v247 offset:49152
	ds_read_b128 v[198:201], v248 offset:49152
	ds_read_b128 v[228:231], v249 offset:49152
	s_add_u32 m0, s100, 0x18000
	s_nop 0
	global_load_lds_dwordx4 v236, s[8:9]
	v_add_u32_e32 v236, 0x80, v236
	s_add_u32 m0, s100, 0x1a000
	s_nop 0
	global_load_lds_dwordx4 v238, s[8:9]
	v_add_u32_e32 v238, 0x80, v238
	s_barrier
	s_waitcnt lgkmcnt(0)
	v_mfma_f32_32x32x16_bf16 v[98:113], v[190:193], v[130:133], v[98:113]
	v_mfma_f32_32x32x16_bf16 v[66:81], v[190:193], v[146:149], v[66:81]
	v_mfma_f32_32x32x16_bf16 v[98:113], v[194:197], v[134:137], v[98:113]
	v_mfma_f32_32x32x16_bf16 v[66:81], v[194:197], v[150:153], v[66:81]
	v_mfma_f32_32x32x16_bf16 v[98:113], v[198:201], v[138:141], v[98:113]
	v_mfma_f32_32x32x16_bf16 v[66:81], v[198:201], v[156:159], v[66:81]
	v_mfma_f32_32x32x16_bf16 v[98:113], v[228:231], v[142:145], v[98:113]
	v_mfma_f32_32x32x16_bf16 v[66:81], v[228:231], v[160:163], v[66:81]
	s_barrier
	v_add_u32_e32 v246, s10, v240
	v_add_u32_e32 v247, s10, v241
	v_add_u32_e32 v248, s10, v242
	v_add_u32_e32 v249, s10, v243
	ds_read_b128 v[130:133], v246 offset:16384
	ds_read_b128 v[134:137], v247 offset:16384
	ds_read_b128 v[138:141], v248 offset:16384
	ds_read_b128 v[142:145], v249 offset:16384
	ds_read_b128 v[146:149], v246 offset:20480
	ds_read_b128 v[150:153], v247 offset:20480
	ds_read_b128 v[156:159], v248 offset:20480
	ds_read_b128 v[160:163], v249 offset:20480
	s_add_u32 m0, s100, 0x10000
	s_nop 0
	global_load_lds_dwordx4 v232, s[6:7]
	v_add_u32_e32 v232, 0x80, v232
	s_add_u32 m0, s100, 0x12000
	s_nop 0
	global_load_lds_dwordx4 v234, s[6:7]
	v_add_u32_e32 v234, 0x80, v234
	s_waitcnt vmcnt(10)
	s_barrier
	s_waitcnt lgkmcnt(0)
	v_mfma_f32_32x32x16_bf16 v[50:65], v[170:173], v[130:133], v[50:65]
	v_mfma_f32_32x32x16_bf16 v[18:33], v[170:173], v[146:149], v[18:33]
	v_mfma_f32_32x32x16_bf16 v[50:65], v[174:177], v[134:137], v[50:65]
	v_mfma_f32_32x32x16_bf16 v[18:33], v[174:177], v[150:153], v[18:33]
	v_mfma_f32_32x32x16_bf16 v[50:65], v[178:181], v[138:141], v[50:65]
	v_mfma_f32_32x32x16_bf16 v[18:33], v[178:181], v[156:159], v[18:33]
	v_mfma_f32_32x32x16_bf16 v[50:65], v[186:189], v[142:145], v[50:65]
	v_mfma_f32_32x32x16_bf16 v[18:33], v[186:189], v[160:163], v[18:33]
	s_barrier
	ds_read_b128 v[170:173], v164 offset:32768
	ds_read_b128 v[174:177], v165 offset:32768
	ds_read_b128 v[178:181], v202 offset:32768
	ds_read_b128 v[186:189], v203 offset:32768
	s_add_u32 m0, s100, 0x1c000
	s_nop 0
	global_load_lds_dwordx4 v237, s[8:9]
	v_add_u32_e32 v237, 0x80, v237
	s_add_u32 m0, s100, 0x1e000
	s_nop 0
	global_load_lds_dwordx4 v239, s[8:9]
	v_add_u32_e32 v239, 0x80, v239
	s_waitcnt vmcnt(6)
	s_barrier
	s_waitcnt lgkmcnt(0)
	v_mfma_f32_32x32x16_bf16 v[34:49], v[190:193], v[130:133], v[34:49]
	v_mfma_f32_32x32x16_bf16 v[2:17], v[190:193], v[146:149], v[2:17]
	v_mfma_f32_32x32x16_bf16 v[34:49], v[194:197], v[134:137], v[34:49]
	v_mfma_f32_32x32x16_bf16 v[2:17], v[194:197], v[150:153], v[2:17]
	v_mfma_f32_32x32x16_bf16 v[34:49], v[198:201], v[138:141], v[34:49]
	v_mfma_f32_32x32x16_bf16 v[2:17], v[198:201], v[156:159], v[2:17]
	v_mfma_f32_32x32x16_bf16 v[34:49], v[228:231], v[142:145], v[34:49]
	v_mfma_f32_32x32x16_bf16 v[2:17], v[228:231], v[160:163], v[2:17]
	s_add_i32 s11, s11, 2
	s_cmp_lt_u32 s11, 14
	s_barrier
	s_cbranch_scc1 .Lg8_qb
	ds_read_b128 v[130:133], v240
	ds_read_b128 v[134:137], v241
	ds_read_b128 v[138:141], v242
	ds_read_b128 v[142:145], v243
	ds_read_b128 v[146:149], v240 offset:4096
	ds_read_b128 v[150:153], v241 offset:4096
	ds_read_b128 v[156:159], v242 offset:4096
	ds_read_b128 v[160:163], v243 offset:4096
	s_add_u32 m0, s100, 0x14000
	s_nop 0
	global_load_lds_dwordx4 v233, s[6:7]
	v_add_u32_e32 v233, 0x80, v233
	s_add_u32 m0, s100, 0x16000
	s_nop 0
	global_load_lds_dwordx4 v235, s[6:7]
	v_add_u32_e32 v235, 0x80, v235
	s_barrier
	s_waitcnt lgkmcnt(0)
	v_mfma_f32_32x32x16_bf16 v[114:129], v[170:173], v[130:133], v[114:129]
	v_mfma_f32_32x32x16_bf16 v[82:97], v[170:173], v[146:149], v[82:97]
	v_mfma_f32_32x32x16_bf16 v[114:129], v[174:177], v[134:137], v[114:129]
	v_mfma_f32_32x32x16_bf16 v[82:97], v[174:177], v[150:153], v[82:97]
	v_mfma_f32_32x32x16_bf16 v[114:129], v[178:181], v[138:141], v[114:129]
	v_mfma_f32_32x32x16_bf16 v[82:97], v[178:181], v[156:159], v[82:97]
	v_mfma_f32_32x32x16_bf16 v[114:129], v[186:189], v[142:145], v[114:129]
	v_mfma_f32_32x32x16_bf16 v[82:97], v[186:189], v[160:163], v[82:97]
	s_barrier
	ds_read_b128 v[190:193], v164 offset:49152
	ds_read_b128 v[194:197], v165 offset:49152
	ds_read_b128 v[198:201], v202 offset:49152
	ds_read_b128 v[228:231], v203 offset:49152
	s_barrier
	s_waitcnt lgkmcnt(0)
	v_mfma_f32_32x32x16_bf16 v[98:113], v[190:193], v[130:133], v[98:113]
	v_mfma_f32_32x32x16_bf16 v[66:81], v[190:193], v[146:149], v[66:81]
	v_mfma_f32_32x32x16_bf16 v[98:113], v[194:197], v[134:137], v[98:113]
	v_mfma_f32_32x32x16_bf16 v[66:81], v[194:197], v[150:153], v[66:81]
	v_mfma_f32_32x32x16_bf16 v[98:113], v[198:201], v[138:141], v[98:113]
	v_mfma_f32_32x32x16_bf16 v[66:81], v[198:201], v[156:159], v[66:81]
	v_mfma_f32_32x32x16_bf16 v[98:113], v[228:231], v[142:145], v[98:113]
	v_mfma_f32_32x32x16_bf16 v[66:81], v[228:231], v[160:163], v[66:81]
	s_barrier
; template <bool SWAP>
; DI void gemm_mainloop(f32x16 (&acc)[4][2], const u16* __restrict__ A, int lda, int rlo, int rhi,
;                       const u16* __restrict__ B, int ldb, int K, char* lds, const u16* zero_line) {
;     ...
; #pragma unroll 2
;   for (int kt = 0; kt < nk; ++kt) {
;     const char* st = lds + (kt & 1) * 65536;
;     ldfrag(st, 0, 0);
;     mma(1);
;     pat_rd();
;     if (kt + 1 < nk) glds(kt + 1, (kt + 1) & 1);
;     ldfrag(st, 1, 1);
;     mma(0);
;     pat_rd();
;     ldfrag(st, 2, 0);
;     mma(1);
;     pat_rd();
;     ldfrag(st, 3, 1);
;     mma(0);
;     pat_rd();
;     asm volatile("s_waitcnt vmcnt(0)" ::: "memory");
;     __syncthreads();
;   }
;   mma(1);
	ds_read_b128 v[130:133], v240 offset:16384
	ds_read_b128 v[134:137], v241 offset:16384
	ds_read_b128 v[138:141], v242 offset:16384
	ds_read_b128 v[142:145], v243 offset:16384
	ds_read_b128 v[146:149], v240 offset:20480
	ds_read_b128 v[150:153], v241 offset:20480
	ds_read_b128 v[156:159], v242 offset:20480
	ds_read_b128 v[160:163], v243 offset:20480
	s_waitcnt vmcnt(4)
	s_barrier
	s_waitcnt lgkmcnt(0)
	v_mfma_f32_32x32x16_bf16 v[50:65], v[170:173], v[130:133], v[50:65]
	v_mfma_f32_32x32x16_bf16 v[18:33], v[170:173], v[146:149], v[18:33]
	v_mfma_f32_32x32x16_bf16 v[50:65], v[174:177], v[134:137], v[50:65]
	v_mfma_f32_32x32x16_bf16 v[18:33], v[174:177], v[150:153], v[18:33]
	v_mfma_f32_32x32x16_bf16 v[50:65], v[178:181], v[138:141], v[50:65]
	v_mfma_f32_32x32x16_bf16 v[18:33], v[178:181], v[156:159], v[18:33]
	v_mfma_f32_32x32x16_bf16 v[50:65], v[186:189], v[142:145], v[50:65]
	v_mfma_f32_32x32x16_bf16 v[18:33], v[186:189], v[160:163], v[18:33]
	v_mfma_f32_32x32x16_bf16 v[34:49], v[190:193], v[130:133], v[34:49]
	v_mfma_f32_32x32x16_bf16 v[2:17], v[190:193], v[146:149], v[2:17]
	v_mfma_f32_32x32x16_bf16 v[34:49], v[194:197], v[134:137], v[34:49]
	v_mfma_f32_32x32x16_bf16 v[2:17], v[194:197], v[150:153], v[2:17]
	v_mfma_f32_32x32x16_bf16 v[34:49], v[198:201], v[138:141], v[34:49]
	v_mfma_f32_32x32x16_bf16 v[2:17], v[198:201], v[156:159], v[2:17]
	v_mfma_f32_32x32x16_bf16 v[34:49], v[228:231], v[142:145], v[34:49]
	v_mfma_f32_32x32x16_bf16 v[2:17], v[228:231], v[160:163], v[2:17]
	s_barrier
	v_add_u32_e32 v246, s10, v164
	v_add_u32_e32 v247, s10, v165
	v_add_u32_e32 v248, s10, v202
	v_add_u32_e32 v249, s10, v203
	ds_read_b128 v[170:173], v246 offset:32768
	ds_read_b128 v[174:177], v247 offset:32768
	ds_read_b128 v[178:181], v248 offset:32768
	ds_read_b128 v[186:189], v249 offset:32768
	v_add_u32_e32 v246, s10, v240
	v_add_u32_e32 v247, s10, v241
	v_add_u32_e32 v248, s10, v242
	v_add_u32_e32 v249, s10, v243
	ds_read_b128 v[130:133], v246
	ds_read_b128 v[134:137], v247
	ds_read_b128 v[138:141], v248
	ds_read_b128 v[142:145], v249
	ds_read_b128 v[146:149], v246 offset:4096
	ds_read_b128 v[150:153], v247 offset:4096
	ds_read_b128 v[156:159], v248 offset:4096
	ds_read_b128 v[160:163], v249 offset:4096
	s_waitcnt vmcnt(2)
	s_barrier
	s_waitcnt lgkmcnt(0)
	v_mfma_f32_32x32x16_bf16 v[114:129], v[170:173], v[130:133], v[114:129]
	v_mfma_f32_32x32x16_bf16 v[82:97], v[170:173], v[146:149], v[82:97]
	v_mfma_f32_32x32x16_bf16 v[114:129], v[174:177], v[134:137], v[114:129]
	v_mfma_f32_32x32x16_bf16 v[82:97], v[174:177], v[150:153], v[82:97]
	v_mfma_f32_32x32x16_bf16 v[114:129], v[178:181], v[138:141], v[114:129]
	v_mfma_f32_32x32x16_bf16 v[82:97], v[178:181], v[156:159], v[82:97]
	v_mfma_f32_32x32x16_bf16 v[114:129], v[186:189], v[142:145], v[114:129]
	v_mfma_f32_32x32x16_bf16 v[82:97], v[186:189], v[160:163], v[82:97]
	s_barrier
	v_add_u32_e32 v246, s10, v164
	v_add_u32_e32 v247, s10, v165
	v_add_u32_e32 v248, s10, v202
	v_add_u32_e32 v249, s10, v203
	ds_read_b128 v[190:193], v246 offset:49152
	ds_read_b128 v[194:197], v247 offset:49152
	ds_read_b128 v[198:201], v248 offset:49152
	ds_read_b128 v[228:231], v249 offset:49152
	s_waitcnt vmcnt(0)
	s_barrier
	s_waitcnt lgkmcnt(0)
	v_mfma_f32_32x32x16_bf16 v[98:113], v[190:193], v[130:133], v[98:113]
	v_mfma_f32_32x32x16_bf16 v[66:81], v[190:193], v[146:149], v[66:81]
	v_mfma_f32_32x32x16_bf16 v[98:113], v[194:197], v[134:137], v[98:113]
	v_mfma_f32_32x32x16_bf16 v[66:81], v[194:197], v[150:153], v[66:81]
	v_mfma_f32_32x32x16_bf16 v[98:113], v[198:201], v[138:141], v[98:113]
	v_mfma_f32_32x32x16_bf16 v[66:81], v[198:201], v[156:159], v[66:81]
	v_mfma_f32_32x32x16_bf16 v[98:113], v[228:231], v[142:145], v[98:113]
	v_mfma_f32_32x32x16_bf16 v[66:81], v[228:231], v[160:163], v[66:81]
	s_barrier
	v_add_u32_e32 v246, s10, v240
	v_add_u32_e32 v247, s10, v241
	v_add_u32_e32 v248, s10, v242
	v_add_u32_e32 v249, s10, v243
	ds_read_b128 v[130:133], v246 offset:16384
	ds_read_b128 v[134:137], v247 offset:16384
	ds_read_b128 v[138:141], v248 offset:16384
	ds_read_b128 v[142:145], v249 offset:16384
	ds_read_b128 v[146:149], v246 offset:20480
	ds_read_b128 v[150:153], v247 offset:20480
	ds_read_b128 v[156:159], v248 offset:20480
	ds_read_b128 v[160:163], v249 offset:20480
	s_barrier
	s_waitcnt lgkmcnt(0)
	v_mfma_f32_32x32x16_bf16 v[50:65], v[170:173], v[130:133], v[50:65]
	v_mfma_f32_32x32x16_bf16 v[18:33], v[170:173], v[146:149], v[18:33]
	v_mfma_f32_32x32x16_bf16 v[50:65], v[174:177], v[134:137], v[50:65]
	v_mfma_f32_32x32x16_bf16 v[18:33], v[174:177], v[150:153], v[18:33]
	v_mfma_f32_32x32x16_bf16 v[50:65], v[178:181], v[138:141], v[50:65]
	v_mfma_f32_32x32x16_bf16 v[18:33], v[178:181], v[156:159], v[18:33]
	v_mfma_f32_32x32x16_bf16 v[50:65], v[186:189], v[142:145], v[50:65]
	v_mfma_f32_32x32x16_bf16 v[18:33], v[186:189], v[160:163], v[18:33]
	v_mfma_f32_32x32x16_bf16 v[34:49], v[190:193], v[130:133], v[34:49]
	v_mfma_f32_32x32x16_bf16 v[2:17], v[190:193], v[146:149], v[2:17]
	v_mfma_f32_32x32x16_bf16 v[34:49], v[194:197], v[134:137], v[34:49]
	v_mfma_f32_32x32x16_bf16 v[2:17], v[194:197], v[150:153], v[2:17]
	v_mfma_f32_32x32x16_bf16 v[34:49], v[198:201], v[138:141], v[34:49]
	v_mfma_f32_32x32x16_bf16 v[2:17], v[198:201], v[156:159], v[2:17]
	v_mfma_f32_32x32x16_bf16 v[34:49], v[228:231], v[142:145], v[34:49]
	v_mfma_f32_32x32x16_bf16 v[2:17], v[228:231], v[160:163], v[2:17]
	s_barrier
	s_cmp_eq_u32 s101, 0
	s_cbranch_scc0 .Lg8_qb_p1
	s_barrier

; #define MFMA(a, b, c) __builtin_amdgcn_mfma_f32_32x32x16_bf16((a), (b), (c), 0, 0, 0)
; template <bool SWAP>
; DI void gemm_mainloop(f32x16 (&acc)[4][2], const u16* __restrict__ A, int lda, int rlo, int rhi,
;                       const u16* __restrict__ B, int ldb, int K, char* lds, const u16* zero_line) {
;     ...
;   auto glds = [&](int kt, int st) {
;     char* as_ = lds + st * 65536 + tid * 16;
; #pragma unroll
;     for (int i = 0; i < 4; ++i) {
;       const int rr = lr + 64 * i;
;       const u16* srca = (rr >= rlo && rr < rhi) ? (ap + (ptrdiff_t)(64 * i) * lda + kt * 64) : (zero_line + lc * 8);
;       __builtin_amdgcn_global_load_lds((const unsigned*)srca, (lds_u32*)(as_ + i * 8192), 16, 0, 0);
;       __builtin_amdgcn_global_load_lds((const unsigned*)(bp + (ptrdiff_t)(64 * i) * ldb + kt * 64), (lds_u32*)(as_ + 32768 + i * 8192), 16, 0, 0);
;     }
;   };
;     ...
;   auto ldfrag = [&](const char* st, int ks, int buf) {
;     const int co = ((2 * ks + h) ^ sw) << 4;
; #pragma unroll
;     for (int mi = 0; mi < 4; ++mi) fa[buf][mi] = *(const bf16x8*)(st + arow_off + mi * 4096 + co);
; #pragma unroll
;     for (int ni = 0; ni < 2; ++ni) fb[buf][ni] = *(const bf16x8*)(st + brow_off + ni * 4096 + co);
;   };
;   auto mma = [&](int buf) {
; #pragma unroll
;     for (int mi = 0; mi < 4; ++mi)
; #pragma unroll
;       for (int ni = 0; ni < 2; ++ni)
;         acc[mi][ni] = SWAP ? MFMA(fb[buf][ni], fa[buf][mi], acc[mi][ni]) : MFMA(fa[buf][mi], fb[buf][ni], acc[mi][ni]);
;   };
;   auto pat_rd = [&]() {
; #pragma unroll
;     for (int g = 0; g < 6; ++g) {
;       __builtin_amdgcn_sched_group_barrier(0x100, 1, 0);
;       __builtin_amdgcn_sched_group_barrier(0x008, 1, 0);
;     }
;     __builtin_amdgcn_sched_group_barrier(0x008, 2, 0);
;   };
; #pragma unroll 2
;   for (int kt = 0; kt < nk; ++kt) {
;     const char* st = lds + (kt & 1) * 65536;
;     ldfrag(st, 0, 0);
;     mma(1);
;     pat_rd();
;     if (kt + 1 < nk) glds(kt + 1, (kt + 1) & 1);
;     ldfrag(st, 1, 1);
;     mma(0);
;     pat_rd();
;     ldfrag(st, 2, 0);
;     mma(1);
;     pat_rd();
;     ldfrag(st, 3, 1);
;     mma(0);
;     pat_rd();
;     asm volatile("s_waitcnt vmcnt(0)" ::: "memory");
;     __syncthreads();
.Lg8_m246:
	ds_read_b128 v[130:133], v240
	ds_read_b128 v[134:137], v241
	ds_read_b128 v[138:141], v242
	ds_read_b128 v[142:145], v243
	ds_read_b128 v[146:149], v240 offset:4096
	ds_read_b128 v[150:153], v241 offset:4096
	ds_read_b128 v[154:157], v242 offset:4096
	ds_read_b128 v[158:161], v243 offset:4096
	s_add_u32 m0, s100, 0x14000
	s_nop 0
	global_load_lds_dwordx4 v233, s[6:7]
	v_add_u32_e32 v233, 0x80, v233
	s_add_u32 m0, s100, 0x16000
	s_nop 0
	global_load_lds_dwordx4 v235, s[6:7]
	v_add_u32_e32 v235, 0x80, v235
	s_barrier
	s_waitcnt lgkmcnt(0)
	v_mfma_f32_32x32x16_bf16 v[114:129], v[162:165], v[130:133], v[114:129]
	v_mfma_f32_32x32x16_bf16 v[82:97], v[162:165], v[146:149], v[82:97]
	v_mfma_f32_32x32x16_bf16 v[114:129], v[166:169], v[134:137], v[114:129]
	v_mfma_f32_32x32x16_bf16 v[82:97], v[166:169], v[150:153], v[82:97]
	v_mfma_f32_32x32x16_bf16 v[114:129], v[170:173], v[138:141], v[114:129]
	v_mfma_f32_32x32x16_bf16 v[82:97], v[170:173], v[154:157], v[82:97]
	v_mfma_f32_32x32x16_bf16 v[114:129], v[174:177], v[142:145], v[114:129]
	v_mfma_f32_32x32x16_bf16 v[82:97], v[174:177], v[158:161], v[82:97]
	s_barrier
	ds_read_b128 v[180:183], v246 offset:49152
	ds_read_b128 v[186:189], v247 offset:49152
	ds_read_b128 v[190:193], v248 offset:49152
	ds_read_b128 v[194:197], v249 offset:49152
	s_add_u32 m0, s100, 0x8000
	s_nop 0
	global_load_lds_dwordx4 v236, s[8:9]
	v_add_u32_e32 v236, 0x80, v236
	s_add_u32 m0, s100, 0xa000
	s_nop 0
	global_load_lds_dwordx4 v238, s[8:9]
	v_add_u32_e32 v238, 0x80, v238
	s_barrier
	s_waitcnt lgkmcnt(0)
	v_mfma_f32_32x32x16_bf16 v[98:113], v[180:183], v[130:133], v[98:113]
	v_mfma_f32_32x32x16_bf16 v[66:81], v[180:183], v[146:149], v[66:81]
	v_mfma_f32_32x32x16_bf16 v[98:113], v[186:189], v[134:137], v[98:113]
	v_mfma_f32_32x32x16_bf16 v[66:81], v[186:189], v[150:153], v[66:81]
	v_mfma_f32_32x32x16_bf16 v[98:113], v[190:193], v[138:141], v[98:113]
	v_mfma_f32_32x32x16_bf16 v[66:81], v[190:193], v[154:157], v[66:81]
	v_mfma_f32_32x32x16_bf16 v[98:113], v[194:197], v[142:145], v[98:113]
	v_mfma_f32_32x32x16_bf16 v[66:81], v[194:197], v[158:161], v[66:81]
	s_barrier
	ds_read_b128 v[130:133], v240 offset:16384
	ds_read_b128 v[134:137], v241 offset:16384
	ds_read_b128 v[138:141], v242 offset:16384
	ds_read_b128 v[142:145], v243 offset:16384
	ds_read_b128 v[146:149], v240 offset:20480
	ds_read_b128 v[150:153], v241 offset:20480
	ds_read_b128 v[154:157], v242 offset:20480
	ds_read_b128 v[158:161], v243 offset:20480
	s_add_u32 m0, s100, 0x0
	s_nop 0
	global_load_lds_dwordx4 v232, s[6:7]
	v_add_u32_e32 v232, 0x80, v232
	s_add_u32 m0, s100, 0x2000
	s_nop 0
	global_load_lds_dwordx4 v234, s[6:7]
	v_add_u32_e32 v234, 0x80, v234
	s_waitcnt vmcnt(10)
	s_barrier
	s_waitcnt lgkmcnt(0)
	v_mfma_f32_32x32x16_bf16 v[50:65], v[162:165], v[130:133], v[50:65]
	v_mfma_f32_32x32x16_bf16 v[18:33], v[162:165], v[146:149], v[18:33]
	v_mfma_f32_32x32x16_bf16 v[50:65], v[166:169], v[134:137], v[50:65]
	v_mfma_f32_32x32x16_bf16 v[18:33], v[166:169], v[150:153], v[18:33]
	v_mfma_f32_32x32x16_bf16 v[50:65], v[170:173], v[138:141], v[50:65]
	v_mfma_f32_32x32x16_bf16 v[18:33], v[170:173], v[154:157], v[18:33]
	v_mfma_f32_32x32x16_bf16 v[50:65], v[174:177], v[142:145], v[50:65]
	v_mfma_f32_32x32x16_bf16 v[18:33], v[174:177], v[158:161], v[18:33]
	s_barrier
	v_add_u32_e32 v244, s10, v246
	v_add_u32_e32 v245, s10, v247
	ds_read_b128 v[162:165], v244 offset:32768
	ds_read_b128 v[166:169], v245 offset:32768
	v_add_u32_e32 v244, s10, v248
	v_add_u32_e32 v245, s10, v249
	ds_read_b128 v[170:173], v244 offset:32768
	ds_read_b128 v[174:177], v245 offset:32768
	s_add_u32 m0, s100, 0xc000
	s_nop 0
	global_load_lds_dwordx4 v237, s[8:9]
	v_add_u32_e32 v237, 0x80, v237
	s_add_u32 m0, s100, 0xe000
	s_nop 0
	global_load_lds_dwordx4 v239, s[8:9]
	v_add_u32_e32 v239, 0x80, v239
	s_waitcnt vmcnt(6)
	s_barrier
	s_waitcnt lgkmcnt(0)
	v_mfma_f32_32x32x16_bf16 v[34:49], v[180:183], v[130:133], v[34:49]
	v_mfma_f32_32x32x16_bf16 v[2:17], v[180:183], v[146:149], v[2:17]
	v_mfma_f32_32x32x16_bf16 v[34:49], v[186:189], v[134:137], v[34:49]
	v_mfma_f32_32x32x16_bf16 v[2:17], v[186:189], v[150:153], v[2:17]
	v_mfma_f32_32x32x16_bf16 v[34:49], v[190:193], v[138:141], v[34:49]
	v_mfma_f32_32x32x16_bf16 v[2:17], v[190:193], v[154:157], v[2:17]
	v_mfma_f32_32x32x16_bf16 v[34:49], v[194:197], v[142:145], v[34:49]
	v_mfma_f32_32x32x16_bf16 v[2:17], v[194:197], v[158:161], v[2:17]
	s_barrier
	v_add_u32_e32 v244, s10, v240
	v_add_u32_e32 v245, s10, v241
	ds_read_b128 v[130:133], v244
	ds_read_b128 v[134:137], v245
	ds_read_b128 v[146:149], v244 offset:4096
	ds_read_b128 v[150:153], v245 offset:4096
	v_add_u32_e32 v244, s10, v242
	v_add_u32_e32 v245, s10, v243
	ds_read_b128 v[138:141], v244
	ds_read_b128 v[142:145], v245
	ds_read_b128 v[154:157], v244 offset:4096
	ds_read_b128 v[158:161], v245 offset:4096
	s_add_u32 m0, s100, 0x4000
	s_nop 0
	global_load_lds_dwordx4 v233, s[6:7]
	v_add_u32_e32 v233, 0x80, v233
	s_add_u32 m0, s100, 0x6000
	s_nop 0
	global_load_lds_dwordx4 v235, s[6:7]
	v_add_u32_e32 v235, 0x80, v235
	s_barrier
	s_waitcnt lgkmcnt(0)
	v_mfma_f32_32x32x16_bf16 v[114:129], v[162:165], v[130:133], v[114:129]
	v_mfma_f32_32x32x16_bf16 v[82:97], v[162:165], v[146:149], v[82:97]
	v_mfma_f32_32x32x16_bf16 v[114:129], v[166:169], v[134:137], v[114:129]
	v_mfma_f32_32x32x16_bf16 v[82:97], v[166:169], v[150:153], v[82:97]
	v_mfma_f32_32x32x16_bf16 v[114:129], v[170:173], v[138:141], v[114:129]
	v_mfma_f32_32x32x16_bf16 v[82:97], v[170:173], v[154:157], v[82:97]
	v_mfma_f32_32x32x16_bf16 v[114:129], v[174:177], v[142:145], v[114:129]
	v_mfma_f32_32x32x16_bf16 v[82:97], v[174:177], v[158:161], v[82:97]
	s_barrier
; template <bool SWAP>
; DI void gemm_mainloop(f32x16 (&acc)[4][2], const u16* __restrict__ A, int lda, int rlo, int rhi,
;                       const u16* __restrict__ B, int ldb, int K, char* lds, const u16* zero_line) {
;     ...
;   auto glds = [&](int kt, int st) {
;     char* as_ = lds + st * 65536 + tid * 16;
; #pragma unroll
;     for (int i = 0; i < 4; ++i) {
;       const int rr = lr + 64 * i;
;       const u16* srca = (rr >= rlo && rr < rhi) ? (ap + (ptrdiff_t)(64 * i) * lda + kt * 64) : (zero_line + lc * 8);
;       __builtin_amdgcn_global_load_lds((const unsigned*)srca, (lds_u32*)(as_ + i * 8192), 16, 0, 0);
;       __builtin_amdgcn_global_load_lds((const unsigned*)(bp + (ptrdiff_t)(64 * i) * ldb + kt * 64), (lds_u32*)(as_ + 32768 + i * 8192), 16, 0, 0);
;     }
;   };
;     ...
; #pragma unroll 2
;   for (int kt = 0; kt < nk; ++kt) {
;     const char* st = lds + (kt & 1) * 65536;
;     ldfrag(st, 0, 0);
;     mma(1);
;     pat_rd();
;     if (kt + 1 < nk) glds(kt + 1, (kt + 1) & 1);
;     ldfrag(st, 1, 1);
;     mma(0);
;     pat_rd();
;     ldfrag(st, 2, 0);
;     mma(1);
;     pat_rd();
;     ldfrag(st, 3, 1);
;     mma(0);
;     pat_rd();
;     asm volatile("s_waitcnt vmcnt(0)" ::: "memory");
;     __syncthreads();
;   }
;   mma(1);
	v_add_u32_e32 v244, s10, v246
	v_add_u32_e32 v245, s10, v247
	ds_read_b128 v[180:183], v244 offset:49152
	ds_read_b128 v[186:189], v245 offset:49152
	v_add_u32_e32 v244, s10, v248
	v_add_u32_e32 v245, s10, v249
	ds_read_b128 v[190:193], v244 offset:49152
	ds_read_b128 v[194:197], v245 offset:49152
	s_add_u32 m0, s100, 0x18000
	s_nop 0
	global_load_lds_dwordx4 v236, s[8:9]
	v_add_u32_e32 v236, 0x80, v236
	s_add_u32 m0, s100, 0x1a000
	s_nop 0
	global_load_lds_dwordx4 v238, s[8:9]
	v_add_u32_e32 v238, 0x80, v238
	s_barrier
	s_waitcnt lgkmcnt(0)
	v_mfma_f32_32x32x16_bf16 v[98:113], v[180:183], v[130:133], v[98:113]
	v_mfma_f32_32x32x16_bf16 v[66:81], v[180:183], v[146:149], v[66:81]
	v_mfma_f32_32x32x16_bf16 v[98:113], v[186:189], v[134:137], v[98:113]
	v_mfma_f32_32x32x16_bf16 v[66:81], v[186:189], v[150:153], v[66:81]
	v_mfma_f32_32x32x16_bf16 v[98:113], v[190:193], v[138:141], v[98:113]
	v_mfma_f32_32x32x16_bf16 v[66:81], v[190:193], v[154:157], v[66:81]
	v_mfma_f32_32x32x16_bf16 v[98:113], v[194:197], v[142:145], v[98:113]
	v_mfma_f32_32x32x16_bf16 v[66:81], v[194:197], v[158:161], v[66:81]
	s_barrier
	v_add_u32_e32 v244, s10, v240
	v_add_u32_e32 v245, s10, v241
	ds_read_b128 v[130:133], v244 offset:16384
	ds_read_b128 v[134:137], v245 offset:16384
	ds_read_b128 v[146:149], v244 offset:20480
	ds_read_b128 v[150:153], v245 offset:20480
	v_add_u32_e32 v244, s10, v242
	v_add_u32_e32 v245, s10, v243
	ds_read_b128 v[138:141], v244 offset:16384
	ds_read_b128 v[142:145], v245 offset:16384
	ds_read_b128 v[154:157], v244 offset:20480
	ds_read_b128 v[158:161], v245 offset:20480
	s_add_u32 m0, s100, 0x10000
	s_nop 0
	global_load_lds_dwordx4 v232, s[6:7]
	v_add_u32_e32 v232, 0x80, v232
	s_add_u32 m0, s100, 0x12000
	s_nop 0
	global_load_lds_dwordx4 v234, s[6:7]
	v_add_u32_e32 v234, 0x80, v234
	s_waitcnt vmcnt(10)
	s_barrier
	s_waitcnt lgkmcnt(0)
	v_mfma_f32_32x32x16_bf16 v[50:65], v[162:165], v[130:133], v[50:65]
	v_mfma_f32_32x32x16_bf16 v[18:33], v[162:165], v[146:149], v[18:33]
	v_mfma_f32_32x32x16_bf16 v[50:65], v[166:169], v[134:137], v[50:65]
	v_mfma_f32_32x32x16_bf16 v[18:33], v[166:169], v[150:153], v[18:33]
	v_mfma_f32_32x32x16_bf16 v[50:65], v[170:173], v[138:141], v[50:65]
	v_mfma_f32_32x32x16_bf16 v[18:33], v[170:173], v[154:157], v[18:33]
	v_mfma_f32_32x32x16_bf16 v[50:65], v[174:177], v[142:145], v[50:65]
	v_mfma_f32_32x32x16_bf16 v[18:33], v[174:177], v[158:161], v[18:33]
	s_barrier
	ds_read_b128 v[162:165], v246 offset:32768
	ds_read_b128 v[166:169], v247 offset:32768
	ds_read_b128 v[170:173], v248 offset:32768
	ds_read_b128 v[174:177], v249 offset:32768
	s_add_u32 m0, s100, 0x1c000
	s_nop 0
	global_load_lds_dwordx4 v237, s[8:9]
	v_add_u32_e32 v237, 0x80, v237
	s_add_u32 m0, s100, 0x1e000
	s_nop 0
	global_load_lds_dwordx4 v239, s[8:9]
	v_add_u32_e32 v239, 0x80, v239
	s_waitcnt vmcnt(6)
	s_barrier
	s_waitcnt lgkmcnt(0)
	v_mfma_f32_32x32x16_bf16 v[34:49], v[180:183], v[130:133], v[34:49]
	v_mfma_f32_32x32x16_bf16 v[2:17], v[180:183], v[146:149], v[2:17]
	v_mfma_f32_32x32x16_bf16 v[34:49], v[186:189], v[134:137], v[34:49]
	v_mfma_f32_32x32x16_bf16 v[2:17], v[186:189], v[150:153], v[2:17]
	v_mfma_f32_32x32x16_bf16 v[34:49], v[190:193], v[138:141], v[34:49]
	v_mfma_f32_32x32x16_bf16 v[2:17], v[190:193], v[154:157], v[2:17]
	v_mfma_f32_32x32x16_bf16 v[34:49], v[194:197], v[142:145], v[34:49]
	v_mfma_f32_32x32x16_bf16 v[2:17], v[194:197], v[158:161], v[2:17]
	s_add_i32 s11, s11, 2
	s_cmp_lt_u32 s11, s25
	s_barrier
	s_cbranch_scc1 .Lg8_m246
	ds_read_b128 v[130:133], v240
	ds_read_b128 v[134:137], v241
	ds_read_b128 v[138:141], v242
	ds_read_b128 v[142:145], v243
	ds_read_b128 v[146:149], v240 offset:4096
	ds_read_b128 v[150:153], v241 offset:4096
	ds_read_b128 v[154:157], v242 offset:4096
	ds_read_b128 v[158:161], v243 offset:4096
	s_add_u32 m0, s100, 0x14000
	s_nop 0
	global_load_lds_dwordx4 v233, s[6:7]
	v_add_u32_e32 v233, 0x80, v233
	s_add_u32 m0, s100, 0x16000
	s_nop 0
	global_load_lds_dwordx4 v235, s[6:7]
	v_add_u32_e32 v235, 0x80, v235
	s_barrier
	s_waitcnt lgkmcnt(0)
	v_mfma_f32_32x32x16_bf16 v[114:129], v[162:165], v[130:133], v[114:129]
	v_mfma_f32_32x32x16_bf16 v[82:97], v[162:165], v[146:149], v[82:97]
	v_mfma_f32_32x32x16_bf16 v[114:129], v[166:169], v[134:137], v[114:129]
	v_mfma_f32_32x32x16_bf16 v[82:97], v[166:169], v[150:153], v[82:97]
	v_mfma_f32_32x32x16_bf16 v[114:129], v[170:173], v[138:141], v[114:129]
	v_mfma_f32_32x32x16_bf16 v[82:97], v[170:173], v[154:157], v[82:97]
	v_mfma_f32_32x32x16_bf16 v[114:129], v[174:177], v[142:145], v[114:129]
	v_mfma_f32_32x32x16_bf16 v[82:97], v[174:177], v[158:161], v[82:97]
	s_barrier
	ds_read_b128 v[180:183], v246 offset:49152
	ds_read_b128 v[186:189], v247 offset:49152
	ds_read_b128 v[190:193], v248 offset:49152
	ds_read_b128 v[194:197], v249 offset:49152
	s_barrier
	s_waitcnt lgkmcnt(0)
	v_mfma_f32_32x32x16_bf16 v[98:113], v[180:183], v[130:133], v[98:113]
	v_mfma_f32_32x32x16_bf16 v[66:81], v[180:183], v[146:149], v[66:81]
	v_mfma_f32_32x32x16_bf16 v[98:113], v[186:189], v[134:137], v[98:113]
	v_mfma_f32_32x32x16_bf16 v[66:81], v[186:189], v[150:153], v[66:81]
	v_mfma_f32_32x32x16_bf16 v[98:113], v[190:193], v[138:141], v[98:113]
	v_mfma_f32_32x32x16_bf16 v[66:81], v[190:193], v[154:157], v[66:81]
	v_mfma_f32_32x32x16_bf16 v[98:113], v[194:197], v[142:145], v[98:113]
	v_mfma_f32_32x32x16_bf16 v[66:81], v[194:197], v[158:161], v[66:81]
	s_barrier
; template <bool SWAP>
; DI void gemm_mainloop(f32x16 (&acc)[4][2], const u16* __restrict__ A, int lda, int rlo, int rhi,
;                       const u16* __restrict__ B, int ldb, int K, char* lds, const u16* zero_line) {
;     ...
; #pragma unroll 2
;   for (int kt = 0; kt < nk; ++kt) {
;     const char* st = lds + (kt & 1) * 65536;
;     ldfrag(st, 0, 0);
;     mma(1);
;     pat_rd();
;     if (kt + 1 < nk) glds(kt + 1, (kt + 1) & 1);
;     ldfrag(st, 1, 1);
;     mma(0);
;     pat_rd();
;     ldfrag(st, 2, 0);
;     mma(1);
;     pat_rd();
;     ldfrag(st, 3, 1);
;     mma(0);
;     pat_rd();
;     asm volatile("s_waitcnt vmcnt(0)" ::: "memory");
;     __syncthreads();
;   }
;   mma(1);
	ds_read_b128 v[130:133], v240 offset:16384
	ds_read_b128 v[134:137], v241 offset:16384
	ds_read_b128 v[138:141], v242 offset:16384
	ds_read_b128 v[142:145], v243 offset:16384
	ds_read_b128 v[146:149], v240 offset:20480
	ds_read_b128 v[150:153], v241 offset:20480
	ds_read_b128 v[154:157], v242 offset:20480
	ds_read_b128 v[158:161], v243 offset:20480
	s_waitcnt vmcnt(4)
	s_barrier
	s_waitcnt lgkmcnt(0)
	v_mfma_f32_32x32x16_bf16 v[50:65], v[162:165], v[130:133], v[50:65]
	v_mfma_f32_32x32x16_bf16 v[18:33], v[162:165], v[146:149], v[18:33]
	v_mfma_f32_32x32x16_bf16 v[50:65], v[166:169], v[134:137], v[50:65]
	v_mfma_f32_32x32x16_bf16 v[18:33], v[166:169], v[150:153], v[18:33]
	v_mfma_f32_32x32x16_bf16 v[50:65], v[170:173], v[138:141], v[50:65]
	v_mfma_f32_32x32x16_bf16 v[18:33], v[170:173], v[154:157], v[18:33]
	v_mfma_f32_32x32x16_bf16 v[50:65], v[174:177], v[142:145], v[50:65]
	v_mfma_f32_32x32x16_bf16 v[18:33], v[174:177], v[158:161], v[18:33]
	v_mfma_f32_32x32x16_bf16 v[34:49], v[180:183], v[130:133], v[34:49]
	v_mfma_f32_32x32x16_bf16 v[2:17], v[180:183], v[146:149], v[2:17]
	v_mfma_f32_32x32x16_bf16 v[34:49], v[186:189], v[134:137], v[34:49]
	v_mfma_f32_32x32x16_bf16 v[2:17], v[186:189], v[150:153], v[2:17]
	v_mfma_f32_32x32x16_bf16 v[34:49], v[190:193], v[138:141], v[34:49]
	v_mfma_f32_32x32x16_bf16 v[2:17], v[190:193], v[154:157], v[2:17]
	v_mfma_f32_32x32x16_bf16 v[34:49], v[194:197], v[142:145], v[34:49]
	v_mfma_f32_32x32x16_bf16 v[2:17], v[194:197], v[158:161], v[2:17]
	s_barrier
	v_add_u32_e32 v244, s10, v246
	v_add_u32_e32 v245, s10, v247
	ds_read_b128 v[162:165], v244 offset:32768
	ds_read_b128 v[166:169], v245 offset:32768
	v_add_u32_e32 v244, s10, v248
	v_add_u32_e32 v245, s10, v249
	ds_read_b128 v[170:173], v244 offset:32768
	ds_read_b128 v[174:177], v245 offset:32768
	v_add_u32_e32 v244, s10, v240
	v_add_u32_e32 v245, s10, v241
	ds_read_b128 v[130:133], v244
	ds_read_b128 v[134:137], v245
	ds_read_b128 v[146:149], v244 offset:4096
	ds_read_b128 v[150:153], v245 offset:4096
	v_add_u32_e32 v244, s10, v242
	v_add_u32_e32 v245, s10, v243
	ds_read_b128 v[138:141], v244
	ds_read_b128 v[142:145], v245
	ds_read_b128 v[154:157], v244 offset:4096
	ds_read_b128 v[158:161], v245 offset:4096
	s_waitcnt vmcnt(2)
	s_barrier
	s_waitcnt lgkmcnt(0)
	v_mfma_f32_32x32x16_bf16 v[114:129], v[162:165], v[130:133], v[114:129]
	v_mfma_f32_32x32x16_bf16 v[82:97], v[162:165], v[146:149], v[82:97]
	v_mfma_f32_32x32x16_bf16 v[114:129], v[166:169], v[134:137], v[114:129]
	v_mfma_f32_32x32x16_bf16 v[82:97], v[166:169], v[150:153], v[82:97]
	v_mfma_f32_32x32x16_bf16 v[114:129], v[170:173], v[138:141], v[114:129]
	v_mfma_f32_32x32x16_bf16 v[82:97], v[170:173], v[154:157], v[82:97]
	v_mfma_f32_32x32x16_bf16 v[114:129], v[174:177], v[142:145], v[114:129]
	v_mfma_f32_32x32x16_bf16 v[82:97], v[174:177], v[158:161], v[82:97]
	s_barrier
	v_add_u32_e32 v244, s10, v246
	v_add_u32_e32 v245, s10, v247
	ds_read_b128 v[180:183], v244 offset:49152
	ds_read_b128 v[186:189], v245 offset:49152
	v_add_u32_e32 v244, s10, v248
	v_add_u32_e32 v245, s10, v249
	ds_read_b128 v[190:193], v244 offset:49152
	ds_read_b128 v[194:197], v245 offset:49152
	s_waitcnt vmcnt(0)
	s_barrier
	s_waitcnt lgkmcnt(0)
	v_mfma_f32_32x32x16_bf16 v[98:113], v[180:183], v[130:133], v[98:113]
	v_mfma_f32_32x32x16_bf16 v[66:81], v[180:183], v[146:149], v[66:81]
	v_mfma_f32_32x32x16_bf16 v[98:113], v[186:189], v[134:137], v[98:113]
	v_mfma_f32_32x32x16_bf16 v[66:81], v[186:189], v[150:153], v[66:81]
	v_mfma_f32_32x32x16_bf16 v[98:113], v[190:193], v[138:141], v[98:113]
	v_mfma_f32_32x32x16_bf16 v[66:81], v[190:193], v[154:157], v[66:81]
	v_mfma_f32_32x32x16_bf16 v[98:113], v[194:197], v[142:145], v[98:113]
	v_mfma_f32_32x32x16_bf16 v[66:81], v[194:197], v[158:161], v[66:81]
	s_barrier
	v_add_u32_e32 v244, s10, v240
	v_add_u32_e32 v245, s10, v241
	ds_read_b128 v[130:133], v244 offset:16384
	ds_read_b128 v[134:137], v245 offset:16384
	ds_read_b128 v[146:149], v244 offset:20480
	ds_read_b128 v[150:153], v245 offset:20480
	v_add_u32_e32 v244, s10, v242
	v_add_u32_e32 v245, s10, v243
	ds_read_b128 v[138:141], v244 offset:16384
	ds_read_b128 v[142:145], v245 offset:16384
	ds_read_b128 v[154:157], v244 offset:20480
	ds_read_b128 v[158:161], v245 offset:20480
	s_barrier
	s_waitcnt lgkmcnt(0)
	v_mfma_f32_32x32x16_bf16 v[50:65], v[162:165], v[130:133], v[50:65]
	v_mfma_f32_32x32x16_bf16 v[18:33], v[162:165], v[146:149], v[18:33]
	v_mfma_f32_32x32x16_bf16 v[50:65], v[166:169], v[134:137], v[50:65]
	v_mfma_f32_32x32x16_bf16 v[18:33], v[166:169], v[150:153], v[18:33]
	v_mfma_f32_32x32x16_bf16 v[50:65], v[170:173], v[138:141], v[50:65]
	v_mfma_f32_32x32x16_bf16 v[18:33], v[170:173], v[154:157], v[18:33]
	v_mfma_f32_32x32x16_bf16 v[50:65], v[174:177], v[142:145], v[50:65]
	v_mfma_f32_32x32x16_bf16 v[18:33], v[174:177], v[158:161], v[18:33]
	v_mfma_f32_32x32x16_bf16 v[34:49], v[180:183], v[130:133], v[34:49]
	v_mfma_f32_32x32x16_bf16 v[2:17], v[180:183], v[146:149], v[2:17]
	v_mfma_f32_32x32x16_bf16 v[34:49], v[186:189], v[134:137], v[34:49]
	v_mfma_f32_32x32x16_bf16 v[2:17], v[186:189], v[150:153], v[2:17]
	v_mfma_f32_32x32x16_bf16 v[34:49], v[190:193], v[138:141], v[34:49]
	v_mfma_f32_32x32x16_bf16 v[2:17], v[190:193], v[154:157], v[2:17]
	v_mfma_f32_32x32x16_bf16 v[34:49], v[194:197], v[142:145], v[34:49]
	v_mfma_f32_32x32x16_bf16 v[2:17], v[194:197], v[158:161], v[2:17]
	s_barrier
	s_cmp_eq_u32 s101, 0
	s_cbranch_scc0 .Lg8_m246_p1
	s_barrier

; #define MFMA(a, b, c) __builtin_amdgcn_mfma_f32_32x32x16_bf16((a), (b), (c), 0, 0, 0)
; template <bool SWAP>
; DI void gemm_mainloop(f32x16 (&acc)[4][2], const u16* __restrict__ A, int lda, int rlo, int rhi,
;                       const u16* __restrict__ B, int ldb, int K, char* lds, const u16* zero_line) {
;     ...
;   auto glds = [&](int kt, int st) {
;     char* as_ = lds + st * 65536 + tid * 16;
; #pragma unroll
;     for (int i = 0; i < 4; ++i) {
;       const int rr = lr + 64 * i;
;       const u16* srca = (rr >= rlo && rr < rhi) ? (ap + (ptrdiff_t)(64 * i) * lda + kt * 64) : (zero_line + lc * 8);
;       __builtin_amdgcn_global_load_lds((const unsigned*)srca, (lds_u32*)(as_ + i * 8192), 16, 0, 0);
;       __builtin_amdgcn_global_load_lds((const unsigned*)(bp + (ptrdiff_t)(64 * i) * ldb + kt * 64), (lds_u32*)(as_ + 32768 + i * 8192), 16, 0, 0);
;     }
;   };
;     ...
;   auto ldfrag = [&](const char* st, int ks, int buf) {
;     const int co = ((2 * ks + h) ^ sw) << 4;
; #pragma unroll
;     for (int mi = 0; mi < 4; ++mi) fa[buf][mi] = *(const bf16x8*)(st + arow_off + mi * 4096 + co);
; #pragma unroll
;     for (int ni = 0; ni < 2; ++ni) fb[buf][ni] = *(const bf16x8*)(st + brow_off + ni * 4096 + co);
;   };
;   auto mma = [&](int buf) {
; #pragma unroll
;     for (int mi = 0; mi < 4; ++mi)
; #pragma unroll
;       for (int ni = 0; ni < 2; ++ni)
;         acc[mi][ni] = SWAP ? MFMA(fb[buf][ni], fa[buf][mi], acc[mi][ni]) : MFMA(fa[buf][mi], fb[buf][ni], acc[mi][ni]);
;   };
;   auto pat_rd = [&]() {
; #pragma unroll
;     for (int g = 0; g < 6; ++g) {
;       __builtin_amdgcn_sched_group_barrier(0x100, 1, 0);
;       __builtin_amdgcn_sched_group_barrier(0x008, 1, 0);
;     }
;     __builtin_amdgcn_sched_group_barrier(0x008, 2, 0);
;   };
; #pragma unroll 2
;   for (int kt = 0; kt < nk; ++kt) {
;     const char* st = lds + (kt & 1) * 65536;
;     ldfrag(st, 0, 0);
;     mma(1);
;     pat_rd();
;     if (kt + 1 < nk) glds(kt + 1, (kt + 1) & 1);
;     ldfrag(st, 1, 1);
;     mma(0);
;     pat_rd();
;     ldfrag(st, 2, 0);
;     mma(1);
;     pat_rd();
;     ldfrag(st, 3, 1);
;     mma(0);
;     pat_rd();
;     asm volatile("s_waitcnt vmcnt(0)" ::: "memory");
;     __syncthreads();
.Lg8_ia:
	ds_read_b128 v[130:133], v161
	ds_read_b128 v[134:137], v163
	ds_read_b128 v[138:141], v164
	ds_read_b128 v[142:145], v165
	ds_read_b128 v[146:149], v161 offset:4096
	ds_read_b128 v[150:153], v163 offset:4096
	ds_read_b128 v[168:171], v164 offset:4096
	ds_read_b128 v[172:175], v165 offset:4096
	s_add_u32 m0, s100, 0x14000
	s_nop 0
	global_load_lds_dwordx4 v241, s[6:7]
	v_add_u32_e32 v241, 0x80, v241
	s_add_u32 m0, s100, 0x16000
	s_nop 0
	global_load_lds_dwordx4 v243, s[6:7]
	v_add_u32_e32 v243, 0x80, v243
	s_barrier
	s_waitcnt lgkmcnt(0)
	v_mfma_f32_32x32x16_bf16 v[114:129], v[176:179], v[130:133], v[114:129]
	v_mfma_f32_32x32x16_bf16 v[98:113], v[176:179], v[146:149], v[98:113]
	v_mfma_f32_32x32x16_bf16 v[114:129], v[180:183], v[134:137], v[114:129]
	v_mfma_f32_32x32x16_bf16 v[98:113], v[180:183], v[150:153], v[98:113]
	v_mfma_f32_32x32x16_bf16 v[114:129], v[192:195], v[138:141], v[114:129]
	v_mfma_f32_32x32x16_bf16 v[98:113], v[192:195], v[168:171], v[98:113]
	v_mfma_f32_32x32x16_bf16 v[114:129], v[196:199], v[142:145], v[114:129]
	v_mfma_f32_32x32x16_bf16 v[98:113], v[196:199], v[172:175], v[98:113]
	s_barrier
	ds_read_b128 v[200:203], v248 offset:49152
	ds_read_b128 v[228:231], v186 offset:49152
	ds_read_b128 v[232:235], v187 offset:49152
	ds_read_b128 v[236:239], v249 offset:49152
	s_add_u32 m0, s100, 0x8000
	s_nop 0
	global_load_lds_dwordx4 v244, s[8:9]
	v_add_u32_e32 v244, 0x80, v244
	s_add_u32 m0, s100, 0xa000
	s_nop 0
	global_load_lds_dwordx4 v246, s[8:9]
	v_add_u32_e32 v246, 0x80, v246
	s_barrier
	s_waitcnt lgkmcnt(0)
	v_mfma_f32_32x32x16_bf16 v[82:97], v[200:203], v[130:133], v[82:97]
	v_mfma_f32_32x32x16_bf16 v[50:65], v[200:203], v[146:149], v[50:65]
	v_mfma_f32_32x32x16_bf16 v[82:97], v[228:231], v[134:137], v[82:97]
	v_mfma_f32_32x32x16_bf16 v[50:65], v[228:231], v[150:153], v[50:65]
	v_mfma_f32_32x32x16_bf16 v[82:97], v[232:235], v[138:141], v[82:97]
	v_mfma_f32_32x32x16_bf16 v[50:65], v[232:235], v[168:171], v[50:65]
	v_mfma_f32_32x32x16_bf16 v[82:97], v[236:239], v[142:145], v[82:97]
	v_mfma_f32_32x32x16_bf16 v[50:65], v[236:239], v[172:175], v[50:65]
	s_barrier
	ds_read_b128 v[130:133], v161 offset:16384
	ds_read_b128 v[134:137], v163 offset:16384
	ds_read_b128 v[138:141], v164 offset:16384
	ds_read_b128 v[142:145], v165 offset:16384
	ds_read_b128 v[146:149], v161 offset:20480
	ds_read_b128 v[150:153], v163 offset:20480
	ds_read_b128 v[168:171], v164 offset:20480
	ds_read_b128 v[172:175], v165 offset:20480
	s_add_u32 m0, s100, 0x0
	s_nop 0
	global_load_lds_dwordx4 v240, s[6:7]
	v_add_u32_e32 v240, 0x80, v240
	s_add_u32 m0, s100, 0x2000
	s_nop 0
	global_load_lds_dwordx4 v242, s[6:7]
	v_add_u32_e32 v242, 0x80, v242
	s_waitcnt vmcnt(10)
	s_barrier
	s_waitcnt lgkmcnt(0)
	v_mfma_f32_32x32x16_bf16 v[66:81], v[176:179], v[130:133], v[66:81]
	v_mfma_f32_32x32x16_bf16 v[34:49], v[176:179], v[146:149], v[34:49]
	v_mfma_f32_32x32x16_bf16 v[66:81], v[180:183], v[134:137], v[66:81]
	v_mfma_f32_32x32x16_bf16 v[34:49], v[180:183], v[150:153], v[34:49]
	v_mfma_f32_32x32x16_bf16 v[66:81], v[192:195], v[138:141], v[66:81]
	v_mfma_f32_32x32x16_bf16 v[34:49], v[192:195], v[168:171], v[34:49]
	v_mfma_f32_32x32x16_bf16 v[66:81], v[196:199], v[142:145], v[66:81]
	v_mfma_f32_32x32x16_bf16 v[34:49], v[196:199], v[172:175], v[34:49]
	s_barrier
	v_add_u32_e32 v166, s10, v248
	ds_read_b128 v[176:179], v166 offset:32768
	v_add_u32_e32 v166, s10, v186
	ds_read_b128 v[180:183], v166 offset:32768
	v_add_u32_e32 v166, s10, v187
	ds_read_b128 v[192:195], v166 offset:32768
	v_add_u32_e32 v166, s10, v249
	ds_read_b128 v[196:199], v166 offset:32768
	s_add_u32 m0, s100, 0xc000
	s_nop 0
	global_load_lds_dwordx4 v245, s[8:9]
	v_add_u32_e32 v245, 0x80, v245
	s_add_u32 m0, s100, 0xe000
	s_nop 0
	global_load_lds_dwordx4 v247, s[8:9]
	v_add_u32_e32 v247, 0x80, v247
	s_waitcnt vmcnt(6)
	s_barrier
	s_waitcnt lgkmcnt(0)
	v_mfma_f32_32x32x16_bf16 v[18:33], v[200:203], v[130:133], v[18:33]
	v_mfma_f32_32x32x16_bf16 v[2:17], v[200:203], v[146:149], v[2:17]
	v_mfma_f32_32x32x16_bf16 v[18:33], v[228:231], v[134:137], v[18:33]
	v_mfma_f32_32x32x16_bf16 v[2:17], v[228:231], v[150:153], v[2:17]
	v_mfma_f32_32x32x16_bf16 v[18:33], v[232:235], v[138:141], v[18:33]
	v_mfma_f32_32x32x16_bf16 v[2:17], v[232:235], v[168:171], v[2:17]
	v_mfma_f32_32x32x16_bf16 v[18:33], v[236:239], v[142:145], v[18:33]
	v_mfma_f32_32x32x16_bf16 v[2:17], v[236:239], v[172:175], v[2:17]
	s_barrier
	v_add_u32_e32 v166, s10, v161
	ds_read_b128 v[130:133], v166
	ds_read_b128 v[146:149], v166 offset:4096
	v_add_u32_e32 v166, s10, v163
	ds_read_b128 v[134:137], v166
	ds_read_b128 v[150:153], v166 offset:4096
	v_add_u32_e32 v166, s10, v164
	ds_read_b128 v[138:141], v166
	ds_read_b128 v[168:171], v166 offset:4096
	v_add_u32_e32 v166, s10, v165
	ds_read_b128 v[142:145], v166
	ds_read_b128 v[172:175], v166 offset:4096
	s_add_u32 m0, s100, 0x4000
	s_nop 0
	global_load_lds_dwordx4 v241, s[6:7]
	v_add_u32_e32 v241, 0x80, v241
	s_add_u32 m0, s100, 0x6000
	s_nop 0
	global_load_lds_dwordx4 v243, s[6:7]
	v_add_u32_e32 v243, 0x80, v243
	s_barrier
	s_waitcnt lgkmcnt(0)
	v_mfma_f32_32x32x16_bf16 v[114:129], v[176:179], v[130:133], v[114:129]
	v_mfma_f32_32x32x16_bf16 v[98:113], v[176:179], v[146:149], v[98:113]
	v_mfma_f32_32x32x16_bf16 v[114:129], v[180:183], v[134:137], v[114:129]
	v_mfma_f32_32x32x16_bf16 v[98:113], v[180:183], v[150:153], v[98:113]
	v_mfma_f32_32x32x16_bf16 v[114:129], v[192:195], v[138:141], v[114:129]
	v_mfma_f32_32x32x16_bf16 v[98:113], v[192:195], v[168:171], v[98:113]
	v_mfma_f32_32x32x16_bf16 v[114:129], v[196:199], v[142:145], v[114:129]
	v_mfma_f32_32x32x16_bf16 v[98:113], v[196:199], v[172:175], v[98:113]
	s_barrier
; template <bool SWAP>
; DI void gemm_mainloop(f32x16 (&acc)[4][2], const u16* __restrict__ A, int lda, int rlo, int rhi,
;                       const u16* __restrict__ B, int ldb, int K, char* lds, const u16* zero_line) {
;     ...
;   auto glds = [&](int kt, int st) {
;     char* as_ = lds + st * 65536 + tid * 16;
; #pragma unroll
;     for (int i = 0; i < 4; ++i) {
;       const int rr = lr + 64 * i;
;       const u16* srca = (rr >= rlo && rr < rhi) ? (ap + (ptrdiff_t)(64 * i) * lda + kt * 64) : (zero_line + lc * 8);
;       __builtin_amdgcn_global_load_lds((const unsigned*)srca, (lds_u32*)(as_ + i * 8192), 16, 0, 0);
;       __builtin_amdgcn_global_load_lds((const unsigned*)(bp + (ptrdiff_t)(64 * i) * ldb + kt * 64), (lds_u32*)(as_ + 32768 + i * 8192), 16, 0, 0);
;     }
;   };
;     ...
; #pragma unroll 2
;   for (int kt = 0; kt < nk; ++kt) {
;     const char* st = lds + (kt & 1) * 65536;
;     ldfrag(st, 0, 0);
;     mma(1);
;     pat_rd();
;     if (kt + 1 < nk) glds(kt + 1, (kt + 1) & 1);
;     ldfrag(st, 1, 1);
;     mma(0);
;     pat_rd();
;     ldfrag(st, 2, 0);
;     mma(1);
;     pat_rd();
;     ldfrag(st, 3, 1);
;     mma(0);
;     pat_rd();
;     asm volatile("s_waitcnt vmcnt(0)" ::: "memory");
;     __syncthreads();
;   }
;   mma(1);
	v_add_u32_e32 v166, s10, v248
	ds_read_b128 v[200:203], v166 offset:49152
	v_add_u32_e32 v166, s10, v186
	ds_read_b128 v[228:231], v166 offset:49152
	v_add_u32_e32 v166, s10, v187
	ds_read_b128 v[232:235], v166 offset:49152
	v_add_u32_e32 v166, s10, v249
	ds_read_b128 v[236:239], v166 offset:49152
	s_add_u32 m0, s100, 0x18000
	s_nop 0
	global_load_lds_dwordx4 v244, s[8:9]
	v_add_u32_e32 v244, 0x80, v244
	s_add_u32 m0, s100, 0x1a000
	s_nop 0
	global_load_lds_dwordx4 v246, s[8:9]
	v_add_u32_e32 v246, 0x80, v246
	s_barrier
	s_waitcnt lgkmcnt(0)
	v_mfma_f32_32x32x16_bf16 v[82:97], v[200:203], v[130:133], v[82:97]
	v_mfma_f32_32x32x16_bf16 v[50:65], v[200:203], v[146:149], v[50:65]
	v_mfma_f32_32x32x16_bf16 v[82:97], v[228:231], v[134:137], v[82:97]
	v_mfma_f32_32x32x16_bf16 v[50:65], v[228:231], v[150:153], v[50:65]
	v_mfma_f32_32x32x16_bf16 v[82:97], v[232:235], v[138:141], v[82:97]
	v_mfma_f32_32x32x16_bf16 v[50:65], v[232:235], v[168:171], v[50:65]
	v_mfma_f32_32x32x16_bf16 v[82:97], v[236:239], v[142:145], v[82:97]
	v_mfma_f32_32x32x16_bf16 v[50:65], v[236:239], v[172:175], v[50:65]
	s_barrier
	v_add_u32_e32 v166, s10, v161
	ds_read_b128 v[130:133], v166 offset:16384
	ds_read_b128 v[146:149], v166 offset:20480
	v_add_u32_e32 v166, s10, v163
	ds_read_b128 v[134:137], v166 offset:16384
	ds_read_b128 v[150:153], v166 offset:20480
	v_add_u32_e32 v166, s10, v164
	ds_read_b128 v[138:141], v166 offset:16384
	ds_read_b128 v[168:171], v166 offset:20480
	v_add_u32_e32 v166, s10, v165
	ds_read_b128 v[142:145], v166 offset:16384
	ds_read_b128 v[172:175], v166 offset:20480
	s_add_u32 m0, s100, 0x10000
	s_nop 0
	global_load_lds_dwordx4 v240, s[6:7]
	v_add_u32_e32 v240, 0x80, v240
	s_add_u32 m0, s100, 0x12000
	s_nop 0
	global_load_lds_dwordx4 v242, s[6:7]
	v_add_u32_e32 v242, 0x80, v242
	s_waitcnt vmcnt(10)
	s_barrier
	s_waitcnt lgkmcnt(0)
	v_mfma_f32_32x32x16_bf16 v[66:81], v[176:179], v[130:133], v[66:81]
	v_mfma_f32_32x32x16_bf16 v[34:49], v[176:179], v[146:149], v[34:49]
	v_mfma_f32_32x32x16_bf16 v[66:81], v[180:183], v[134:137], v[66:81]
	v_mfma_f32_32x32x16_bf16 v[34:49], v[180:183], v[150:153], v[34:49]
	v_mfma_f32_32x32x16_bf16 v[66:81], v[192:195], v[138:141], v[66:81]
	v_mfma_f32_32x32x16_bf16 v[34:49], v[192:195], v[168:171], v[34:49]
	v_mfma_f32_32x32x16_bf16 v[66:81], v[196:199], v[142:145], v[66:81]
	v_mfma_f32_32x32x16_bf16 v[34:49], v[196:199], v[172:175], v[34:49]
	s_barrier
	ds_read_b128 v[176:179], v248 offset:32768
	ds_read_b128 v[180:183], v186 offset:32768
	ds_read_b128 v[192:195], v187 offset:32768
	ds_read_b128 v[196:199], v249 offset:32768
	s_add_u32 m0, s100, 0x1c000
	s_nop 0
	global_load_lds_dwordx4 v245, s[8:9]
	v_add_u32_e32 v245, 0x80, v245
	s_add_u32 m0, s100, 0x1e000
	s_nop 0
	global_load_lds_dwordx4 v247, s[8:9]
	v_add_u32_e32 v247, 0x80, v247
	s_waitcnt vmcnt(6)
	s_barrier
	s_waitcnt lgkmcnt(0)
	v_mfma_f32_32x32x16_bf16 v[18:33], v[200:203], v[130:133], v[18:33]
	v_mfma_f32_32x32x16_bf16 v[2:17], v[200:203], v[146:149], v[2:17]
	v_mfma_f32_32x32x16_bf16 v[18:33], v[228:231], v[134:137], v[18:33]
	v_mfma_f32_32x32x16_bf16 v[2:17], v[228:231], v[150:153], v[2:17]
	v_mfma_f32_32x32x16_bf16 v[18:33], v[232:235], v[138:141], v[18:33]
	v_mfma_f32_32x32x16_bf16 v[2:17], v[232:235], v[168:171], v[2:17]
	v_mfma_f32_32x32x16_bf16 v[18:33], v[236:239], v[142:145], v[18:33]
	v_mfma_f32_32x32x16_bf16 v[2:17], v[236:239], v[172:175], v[2:17]
	s_add_i32 s11, s11, 2
	s_cmp_lt_u32 s11, 14
	s_barrier
	s_cbranch_scc1 .Lg8_ia
	ds_read_b128 v[130:133], v161
	ds_read_b128 v[134:137], v163
	ds_read_b128 v[138:141], v164
	ds_read_b128 v[142:145], v165
	ds_read_b128 v[146:149], v161 offset:4096
	ds_read_b128 v[150:153], v163 offset:4096
	ds_read_b128 v[168:171], v164 offset:4096
	ds_read_b128 v[172:175], v165 offset:4096
	s_add_u32 m0, s100, 0x14000
	s_nop 0
	global_load_lds_dwordx4 v241, s[6:7]
	v_add_u32_e32 v241, 0x80, v241
	s_add_u32 m0, s100, 0x16000
	s_nop 0
	global_load_lds_dwordx4 v243, s[6:7]
	v_add_u32_e32 v243, 0x80, v243
	s_barrier
	s_waitcnt lgkmcnt(0)
	v_mfma_f32_32x32x16_bf16 v[114:129], v[176:179], v[130:133], v[114:129]
	v_mfma_f32_32x32x16_bf16 v[98:113], v[176:179], v[146:149], v[98:113]
	v_mfma_f32_32x32x16_bf16 v[114:129], v[180:183], v[134:137], v[114:129]
	v_mfma_f32_32x32x16_bf16 v[98:113], v[180:183], v[150:153], v[98:113]
	v_mfma_f32_32x32x16_bf16 v[114:129], v[192:195], v[138:141], v[114:129]
	v_mfma_f32_32x32x16_bf16 v[98:113], v[192:195], v[168:171], v[98:113]
	v_mfma_f32_32x32x16_bf16 v[114:129], v[196:199], v[142:145], v[114:129]
	v_mfma_f32_32x32x16_bf16 v[98:113], v[196:199], v[172:175], v[98:113]
	s_barrier
	ds_read_b128 v[200:203], v248 offset:49152
	ds_read_b128 v[228:231], v186 offset:49152
	ds_read_b128 v[232:235], v187 offset:49152
	ds_read_b128 v[236:239], v249 offset:49152
	s_barrier
	s_waitcnt lgkmcnt(0)
	v_mfma_f32_32x32x16_bf16 v[82:97], v[200:203], v[130:133], v[82:97]
	v_mfma_f32_32x32x16_bf16 v[50:65], v[200:203], v[146:149], v[50:65]
	v_mfma_f32_32x32x16_bf16 v[82:97], v[228:231], v[134:137], v[82:97]
	v_mfma_f32_32x32x16_bf16 v[50:65], v[228:231], v[150:153], v[50:65]
	v_mfma_f32_32x32x16_bf16 v[82:97], v[232:235], v[138:141], v[82:97]
	v_mfma_f32_32x32x16_bf16 v[50:65], v[232:235], v[168:171], v[50:65]
	v_mfma_f32_32x32x16_bf16 v[82:97], v[236:239], v[142:145], v[82:97]
	v_mfma_f32_32x32x16_bf16 v[50:65], v[236:239], v[172:175], v[50:65]
	s_barrier
; template <bool SWAP>
; DI void gemm_mainloop(f32x16 (&acc)[4][2], const u16* __restrict__ A, int lda, int rlo, int rhi,
;                       const u16* __restrict__ B, int ldb, int K, char* lds, const u16* zero_line) {
;     ...
; #pragma unroll 2
;   for (int kt = 0; kt < nk; ++kt) {
;     const char* st = lds + (kt & 1) * 65536;
;     ldfrag(st, 0, 0);
;     mma(1);
;     pat_rd();
;     if (kt + 1 < nk) glds(kt + 1, (kt + 1) & 1);
;     ldfrag(st, 1, 1);
;     mma(0);
;     pat_rd();
;     ldfrag(st, 2, 0);
;     mma(1);
;     pat_rd();
;     ldfrag(st, 3, 1);
;     mma(0);
;     pat_rd();
;     asm volatile("s_waitcnt vmcnt(0)" ::: "memory");
;     __syncthreads();
;   }
;   mma(1);
	ds_read_b128 v[130:133], v161 offset:16384
	ds_read_b128 v[134:137], v163 offset:16384
	ds_read_b128 v[138:141], v164 offset:16384
	ds_read_b128 v[142:145], v165 offset:16384
	ds_read_b128 v[146:149], v161 offset:20480
	ds_read_b128 v[150:153], v163 offset:20480
	ds_read_b128 v[168:171], v164 offset:20480
	ds_read_b128 v[172:175], v165 offset:20480
	s_waitcnt vmcnt(4)
	s_barrier
	s_waitcnt lgkmcnt(0)
	v_mfma_f32_32x32x16_bf16 v[66:81], v[176:179], v[130:133], v[66:81]
	v_mfma_f32_32x32x16_bf16 v[34:49], v[176:179], v[146:149], v[34:49]
	v_mfma_f32_32x32x16_bf16 v[66:81], v[180:183], v[134:137], v[66:81]
	v_mfma_f32_32x32x16_bf16 v[34:49], v[180:183], v[150:153], v[34:49]
	v_mfma_f32_32x32x16_bf16 v[66:81], v[192:195], v[138:141], v[66:81]
	v_mfma_f32_32x32x16_bf16 v[34:49], v[192:195], v[168:171], v[34:49]
	v_mfma_f32_32x32x16_bf16 v[66:81], v[196:199], v[142:145], v[66:81]
	v_mfma_f32_32x32x16_bf16 v[34:49], v[196:199], v[172:175], v[34:49]
	v_mfma_f32_32x32x16_bf16 v[18:33], v[200:203], v[130:133], v[18:33]
	v_mfma_f32_32x32x16_bf16 v[2:17], v[200:203], v[146:149], v[2:17]
	v_mfma_f32_32x32x16_bf16 v[18:33], v[228:231], v[134:137], v[18:33]
	v_mfma_f32_32x32x16_bf16 v[2:17], v[228:231], v[150:153], v[2:17]
	v_mfma_f32_32x32x16_bf16 v[18:33], v[232:235], v[138:141], v[18:33]
	v_mfma_f32_32x32x16_bf16 v[2:17], v[232:235], v[168:171], v[2:17]
	v_mfma_f32_32x32x16_bf16 v[18:33], v[236:239], v[142:145], v[18:33]
	v_mfma_f32_32x32x16_bf16 v[2:17], v[236:239], v[172:175], v[2:17]
	s_barrier
	v_add_u32_e32 v166, s10, v248
	ds_read_b128 v[176:179], v166 offset:32768
	v_add_u32_e32 v166, s10, v186
	ds_read_b128 v[180:183], v166 offset:32768
	v_add_u32_e32 v166, s10, v187
	ds_read_b128 v[192:195], v166 offset:32768
	v_add_u32_e32 v166, s10, v249
	ds_read_b128 v[196:199], v166 offset:32768
	v_add_u32_e32 v166, s10, v161
	ds_read_b128 v[130:133], v166
	ds_read_b128 v[146:149], v166 offset:4096
	v_add_u32_e32 v166, s10, v163
	ds_read_b128 v[134:137], v166
	ds_read_b128 v[150:153], v166 offset:4096
	v_add_u32_e32 v166, s10, v164
	ds_read_b128 v[138:141], v166
	ds_read_b128 v[168:171], v166 offset:4096
	v_add_u32_e32 v166, s10, v165
	ds_read_b128 v[142:145], v166
	ds_read_b128 v[172:175], v166 offset:4096
	s_waitcnt vmcnt(2)
	s_barrier
	s_waitcnt lgkmcnt(0)
	v_mfma_f32_32x32x16_bf16 v[114:129], v[176:179], v[130:133], v[114:129]
	v_mfma_f32_32x32x16_bf16 v[98:113], v[176:179], v[146:149], v[98:113]
	v_mfma_f32_32x32x16_bf16 v[114:129], v[180:183], v[134:137], v[114:129]
	v_mfma_f32_32x32x16_bf16 v[98:113], v[180:183], v[150:153], v[98:113]
	v_mfma_f32_32x32x16_bf16 v[114:129], v[192:195], v[138:141], v[114:129]
	v_mfma_f32_32x32x16_bf16 v[98:113], v[192:195], v[168:171], v[98:113]
	v_mfma_f32_32x32x16_bf16 v[114:129], v[196:199], v[142:145], v[114:129]
	v_mfma_f32_32x32x16_bf16 v[98:113], v[196:199], v[172:175], v[98:113]
	s_barrier
	v_add_u32_e32 v166, s10, v248
	ds_read_b128 v[200:203], v166 offset:49152
	v_add_u32_e32 v166, s10, v186
	ds_read_b128 v[228:231], v166 offset:49152
	v_add_u32_e32 v166, s10, v187
	ds_read_b128 v[232:235], v166 offset:49152
	v_add_u32_e32 v166, s10, v249
	ds_read_b128 v[236:239], v166 offset:49152
	s_waitcnt vmcnt(0)
	s_barrier
	s_waitcnt lgkmcnt(0)
	v_mfma_f32_32x32x16_bf16 v[82:97], v[200:203], v[130:133], v[82:97]
	v_mfma_f32_32x32x16_bf16 v[50:65], v[200:203], v[146:149], v[50:65]
	v_mfma_f32_32x32x16_bf16 v[82:97], v[228:231], v[134:137], v[82:97]
	v_mfma_f32_32x32x16_bf16 v[50:65], v[228:231], v[150:153], v[50:65]
	v_mfma_f32_32x32x16_bf16 v[82:97], v[232:235], v[138:141], v[82:97]
	v_mfma_f32_32x32x16_bf16 v[50:65], v[232:235], v[168:171], v[50:65]
	v_mfma_f32_32x32x16_bf16 v[82:97], v[236:239], v[142:145], v[82:97]
	v_mfma_f32_32x32x16_bf16 v[50:65], v[236:239], v[172:175], v[50:65]
	s_barrier
	v_add_u32_e32 v166, s10, v161
	ds_read_b128 v[130:133], v166 offset:16384
	ds_read_b128 v[146:149], v166 offset:20480
	v_add_u32_e32 v166, s10, v163
	ds_read_b128 v[134:137], v166 offset:16384
	ds_read_b128 v[150:153], v166 offset:20480
	v_add_u32_e32 v166, s10, v164
	ds_read_b128 v[138:141], v166 offset:16384
	ds_read_b128 v[168:171], v166 offset:20480
	v_add_u32_e32 v166, s10, v165
	ds_read_b128 v[142:145], v166 offset:16384
	ds_read_b128 v[172:175], v166 offset:20480
	s_barrier
	s_waitcnt lgkmcnt(0)
	v_mfma_f32_32x32x16_bf16 v[66:81], v[176:179], v[130:133], v[66:81]
	v_mfma_f32_32x32x16_bf16 v[34:49], v[176:179], v[146:149], v[34:49]
	v_mfma_f32_32x32x16_bf16 v[66:81], v[180:183], v[134:137], v[66:81]
	v_mfma_f32_32x32x16_bf16 v[34:49], v[180:183], v[150:153], v[34:49]
	v_mfma_f32_32x32x16_bf16 v[66:81], v[192:195], v[138:141], v[66:81]
	v_mfma_f32_32x32x16_bf16 v[34:49], v[192:195], v[168:171], v[34:49]
	v_mfma_f32_32x32x16_bf16 v[66:81], v[196:199], v[142:145], v[66:81]
	v_mfma_f32_32x32x16_bf16 v[34:49], v[196:199], v[172:175], v[34:49]
	v_mfma_f32_32x32x16_bf16 v[18:33], v[200:203], v[130:133], v[18:33]
	v_mfma_f32_32x32x16_bf16 v[2:17], v[200:203], v[146:149], v[2:17]
	v_mfma_f32_32x32x16_bf16 v[18:33], v[228:231], v[134:137], v[18:33]
	v_mfma_f32_32x32x16_bf16 v[2:17], v[228:231], v[150:153], v[2:17]
	v_mfma_f32_32x32x16_bf16 v[18:33], v[232:235], v[138:141], v[18:33]
	v_mfma_f32_32x32x16_bf16 v[2:17], v[232:235], v[168:171], v[2:17]
	v_mfma_f32_32x32x16_bf16 v[18:33], v[236:239], v[142:145], v[18:33]
	v_mfma_f32_32x32x16_bf16 v[2:17], v[236:239], v[172:175], v[2:17]
	s_barrier
	s_cmp_eq_u32 s101, 0
	s_cbranch_scc0 .Lg8_ia_p1
	s_barrier

; #define MFMA(a, b, c) __builtin_amdgcn_mfma_f32_32x32x16_bf16((a), (b), (c), 0, 0, 0)
; template <bool SWAP>
; DI void gemm_mainloop(f32x16 (&acc)[4][2], const u16* __restrict__ A, int lda, int rlo, int rhi,
;                       const u16* __restrict__ B, int ldb, int K, char* lds, const u16* zero_line) {
;     ...
;   auto glds = [&](int kt, int st) {
;     char* as_ = lds + st * 65536 + tid * 16;
; #pragma unroll
;     for (int i = 0; i < 4; ++i) {
;       const int rr = lr + 64 * i;
;       const u16* srca = (rr >= rlo && rr < rhi) ? (ap + (ptrdiff_t)(64 * i) * lda + kt * 64) : (zero_line + lc * 8);
;       __builtin_amdgcn_global_load_lds((const unsigned*)srca, (lds_u32*)(as_ + i * 8192), 16, 0, 0);
;       __builtin_amdgcn_global_load_lds((const unsigned*)(bp + (ptrdiff_t)(64 * i) * ldb + kt * 64), (lds_u32*)(as_ + 32768 + i * 8192), 16, 0, 0);
;     }
;   };
;     ...
;   auto ldfrag = [&](const char* st, int ks, int buf) {
;     const int co = ((2 * ks + h) ^ sw) << 4;
; #pragma unroll
;     for (int mi = 0; mi < 4; ++mi) fa[buf][mi] = *(const bf16x8*)(st + arow_off + mi * 4096 + co);
; #pragma unroll
;     for (int ni = 0; ni < 2; ++ni) fb[buf][ni] = *(const bf16x8*)(st + brow_off + ni * 4096 + co);
;   };
;   auto mma = [&](int buf) {
; #pragma unroll
;     for (int mi = 0; mi < 4; ++mi)
; #pragma unroll
;       for (int ni = 0; ni < 2; ++ni)
;         acc[mi][ni] = SWAP ? MFMA(fb[buf][ni], fa[buf][mi], acc[mi][ni]) : MFMA(fa[buf][mi], fb[buf][ni], acc[mi][ni]);
;   };
;   auto pat_rd = [&]() {
; #pragma unroll
;     for (int g = 0; g < 6; ++g) {
;       __builtin_amdgcn_sched_group_barrier(0x100, 1, 0);
;       __builtin_amdgcn_sched_group_barrier(0x008, 1, 0);
;     }
;     __builtin_amdgcn_sched_group_barrier(0x008, 2, 0);
;   };
; #pragma unroll 2
;   for (int kt = 0; kt < nk; ++kt) {
;     const char* st = lds + (kt & 1) * 65536;
;     ldfrag(st, 0, 0);
;     mma(1);
;     pat_rd();
;     if (kt + 1 < nk) glds(kt + 1, (kt + 1) & 1);
;     ldfrag(st, 1, 1);
;     mma(0);
;     pat_rd();
;     ldfrag(st, 2, 0);
;     mma(1);
;     pat_rd();
;     ldfrag(st, 3, 1);
;     mma(0);
;     pat_rd();
;     asm volatile("s_waitcnt vmcnt(0)" ::: "memory");
;     __syncthreads();
.Lg8_ib:
	ds_read_b128 v[130:133], v161
	ds_read_b128 v[134:137], v163
	ds_read_b128 v[138:141], v164
	ds_read_b128 v[142:145], v165
	ds_read_b128 v[146:149], v161 offset:4096
	ds_read_b128 v[150:153], v163 offset:4096
	ds_read_b128 v[168:171], v164 offset:4096
	ds_read_b128 v[172:175], v165 offset:4096
	s_add_u32 m0, s100, 0x14000
	s_nop 0
	global_load_lds_dwordx4 v241, s[6:7]
	v_add_u32_e32 v241, 0x80, v241
	s_add_u32 m0, s100, 0x16000
	s_nop 0
	global_load_lds_dwordx4 v243, s[6:7]
	v_add_u32_e32 v243, 0x80, v243
	s_barrier
	s_waitcnt lgkmcnt(0)
	v_mfma_f32_32x32x16_bf16 v[114:129], v[130:133], v[176:179], v[114:129]
	v_mfma_f32_32x32x16_bf16 v[98:113], v[146:149], v[176:179], v[98:113]
	v_mfma_f32_32x32x16_bf16 v[114:129], v[134:137], v[180:183], v[114:129]
	v_mfma_f32_32x32x16_bf16 v[98:113], v[150:153], v[180:183], v[98:113]
	v_mfma_f32_32x32x16_bf16 v[114:129], v[138:141], v[192:195], v[114:129]
	v_mfma_f32_32x32x16_bf16 v[98:113], v[168:171], v[192:195], v[98:113]
	v_mfma_f32_32x32x16_bf16 v[114:129], v[142:145], v[196:199], v[114:129]
	v_mfma_f32_32x32x16_bf16 v[98:113], v[172:175], v[196:199], v[98:113]
	s_barrier
	ds_read_b128 v[200:203], v248 offset:49152
	ds_read_b128 v[228:231], v186 offset:49152
	ds_read_b128 v[232:235], v187 offset:49152
	ds_read_b128 v[236:239], v249 offset:49152
	s_add_u32 m0, s100, 0x8000
	s_nop 0
	global_load_lds_dwordx4 v244, s[8:9]
	v_add_u32_e32 v244, 0x80, v244
	s_add_u32 m0, s100, 0xa000
	s_nop 0
	global_load_lds_dwordx4 v246, s[8:9]
	v_add_u32_e32 v246, 0x80, v246
	s_barrier
	s_waitcnt lgkmcnt(0)
	v_mfma_f32_32x32x16_bf16 v[82:97], v[130:133], v[200:203], v[82:97]
	v_mfma_f32_32x32x16_bf16 v[50:65], v[146:149], v[200:203], v[50:65]
	v_mfma_f32_32x32x16_bf16 v[82:97], v[134:137], v[228:231], v[82:97]
	v_mfma_f32_32x32x16_bf16 v[50:65], v[150:153], v[228:231], v[50:65]
	v_mfma_f32_32x32x16_bf16 v[82:97], v[138:141], v[232:235], v[82:97]
	v_mfma_f32_32x32x16_bf16 v[50:65], v[168:171], v[232:235], v[50:65]
	v_mfma_f32_32x32x16_bf16 v[82:97], v[142:145], v[236:239], v[82:97]
	v_mfma_f32_32x32x16_bf16 v[50:65], v[172:175], v[236:239], v[50:65]
	s_barrier
	ds_read_b128 v[130:133], v161 offset:16384
	ds_read_b128 v[134:137], v163 offset:16384
	ds_read_b128 v[138:141], v164 offset:16384
	ds_read_b128 v[142:145], v165 offset:16384
	ds_read_b128 v[146:149], v161 offset:20480
	ds_read_b128 v[150:153], v163 offset:20480
	ds_read_b128 v[168:171], v164 offset:20480
	ds_read_b128 v[172:175], v165 offset:20480
	s_add_u32 m0, s100, 0x0
	s_nop 0
	global_load_lds_dwordx4 v240, s[6:7]
	v_add_u32_e32 v240, 0x80, v240
	s_add_u32 m0, s100, 0x2000
	s_nop 0
	global_load_lds_dwordx4 v242, s[6:7]
	v_add_u32_e32 v242, 0x80, v242
	s_waitcnt vmcnt(10)
	s_barrier
	s_waitcnt lgkmcnt(0)
	v_mfma_f32_32x32x16_bf16 v[66:81], v[130:133], v[176:179], v[66:81]
	v_mfma_f32_32x32x16_bf16 v[34:49], v[146:149], v[176:179], v[34:49]
	v_mfma_f32_32x32x16_bf16 v[66:81], v[134:137], v[180:183], v[66:81]
	v_mfma_f32_32x32x16_bf16 v[34:49], v[150:153], v[180:183], v[34:49]
	v_mfma_f32_32x32x16_bf16 v[66:81], v[138:141], v[192:195], v[66:81]
	v_mfma_f32_32x32x16_bf16 v[34:49], v[168:171], v[192:195], v[34:49]
	v_mfma_f32_32x32x16_bf16 v[66:81], v[142:145], v[196:199], v[66:81]
	v_mfma_f32_32x32x16_bf16 v[34:49], v[172:175], v[196:199], v[34:49]
	s_barrier
	v_add_u32_e32 v166, s10, v248
	ds_read_b128 v[176:179], v166 offset:32768
	v_add_u32_e32 v166, s10, v186
	ds_read_b128 v[180:183], v166 offset:32768
	v_add_u32_e32 v166, s10, v187
	ds_read_b128 v[192:195], v166 offset:32768
	v_add_u32_e32 v166, s10, v249
	ds_read_b128 v[196:199], v166 offset:32768
	s_add_u32 m0, s100, 0xc000
	s_nop 0
	global_load_lds_dwordx4 v245, s[8:9]
	v_add_u32_e32 v245, 0x80, v245
	s_add_u32 m0, s100, 0xe000
	s_nop 0
	global_load_lds_dwordx4 v247, s[8:9]
	v_add_u32_e32 v247, 0x80, v247
	s_waitcnt vmcnt(6)
	s_barrier
	s_waitcnt lgkmcnt(0)
	v_mfma_f32_32x32x16_bf16 v[18:33], v[130:133], v[200:203], v[18:33]
	v_mfma_f32_32x32x16_bf16 v[2:17], v[146:149], v[200:203], v[2:17]
	v_mfma_f32_32x32x16_bf16 v[18:33], v[134:137], v[228:231], v[18:33]
	v_mfma_f32_32x32x16_bf16 v[2:17], v[150:153], v[228:231], v[2:17]
	v_mfma_f32_32x32x16_bf16 v[18:33], v[138:141], v[232:235], v[18:33]
	v_mfma_f32_32x32x16_bf16 v[2:17], v[168:171], v[232:235], v[2:17]
	v_mfma_f32_32x32x16_bf16 v[18:33], v[142:145], v[236:239], v[18:33]
	v_mfma_f32_32x32x16_bf16 v[2:17], v[172:175], v[236:239], v[2:17]
	s_barrier
	v_add_u32_e32 v166, s10, v161
	ds_read_b128 v[130:133], v166
	ds_read_b128 v[146:149], v166 offset:4096
	v_add_u32_e32 v166, s10, v163
	ds_read_b128 v[134:137], v166
	ds_read_b128 v[150:153], v166 offset:4096
	v_add_u32_e32 v166, s10, v164
	ds_read_b128 v[138:141], v166
	ds_read_b128 v[168:171], v166 offset:4096
	v_add_u32_e32 v166, s10, v165
	ds_read_b128 v[142:145], v166
	ds_read_b128 v[172:175], v166 offset:4096
	s_add_u32 m0, s100, 0x4000
	s_nop 0
	global_load_lds_dwordx4 v241, s[6:7]
	v_add_u32_e32 v241, 0x80, v241
	s_add_u32 m0, s100, 0x6000
	s_nop 0
	global_load_lds_dwordx4 v243, s[6:7]
	v_add_u32_e32 v243, 0x80, v243
	s_barrier
	s_waitcnt lgkmcnt(0)
	v_mfma_f32_32x32x16_bf16 v[114:129], v[130:133], v[176:179], v[114:129]
	v_mfma_f32_32x32x16_bf16 v[98:113], v[146:149], v[176:179], v[98:113]
	v_mfma_f32_32x32x16_bf16 v[114:129], v[134:137], v[180:183], v[114:129]
	v_mfma_f32_32x32x16_bf16 v[98:113], v[150:153], v[180:183], v[98:113]
	v_mfma_f32_32x32x16_bf16 v[114:129], v[138:141], v[192:195], v[114:129]
	v_mfma_f32_32x32x16_bf16 v[98:113], v[168:171], v[192:195], v[98:113]
	v_mfma_f32_32x32x16_bf16 v[114:129], v[142:145], v[196:199], v[114:129]
	v_mfma_f32_32x32x16_bf16 v[98:113], v[172:175], v[196:199], v[98:113]
	s_barrier
; template <bool SWAP>
; DI void gemm_mainloop(f32x16 (&acc)[4][2], const u16* __restrict__ A, int lda, int rlo, int rhi,
;                       const u16* __restrict__ B, int ldb, int K, char* lds, const u16* zero_line) {
;     ...
;   auto glds = [&](int kt, int st) {
;     char* as_ = lds + st * 65536 + tid * 16;
; #pragma unroll
;     for (int i = 0; i < 4; ++i) {
;       const int rr = lr + 64 * i;
;       const u16* srca = (rr >= rlo && rr < rhi) ? (ap + (ptrdiff_t)(64 * i) * lda + kt * 64) : (zero_line + lc * 8);
;       __builtin_amdgcn_global_load_lds((const unsigned*)srca, (lds_u32*)(as_ + i * 8192), 16, 0, 0);
;       __builtin_amdgcn_global_load_lds((const unsigned*)(bp + (ptrdiff_t)(64 * i) * ldb + kt * 64), (lds_u32*)(as_ + 32768 + i * 8192), 16, 0, 0);
;     }
;   };
;     ...
; #pragma unroll 2
;   for (int kt = 0; kt < nk; ++kt) {
;     const char* st = lds + (kt & 1) * 65536;
;     ldfrag(st, 0, 0);
;     mma(1);
;     pat_rd();
;     if (kt + 1 < nk) glds(kt + 1, (kt + 1) & 1);
;     ldfrag(st, 1, 1);
;     mma(0);
;     pat_rd();
;     ldfrag(st, 2, 0);
;     mma(1);
;     pat_rd();
;     ldfrag(st, 3, 1);
;     mma(0);
;     pat_rd();
;     asm volatile("s_waitcnt vmcnt(0)" ::: "memory");
;     __syncthreads();
;   }
;   mma(1);
	v_add_u32_e32 v166, s10, v248
	ds_read_b128 v[200:203], v166 offset:49152
	v_add_u32_e32 v166, s10, v186
	ds_read_b128 v[228:231], v166 offset:49152
	v_add_u32_e32 v166, s10, v187
	ds_read_b128 v[232:235], v166 offset:49152
	v_add_u32_e32 v166, s10, v249
	ds_read_b128 v[236:239], v166 offset:49152
	s_add_u32 m0, s100, 0x18000
	s_nop 0
	global_load_lds_dwordx4 v244, s[8:9]
	v_add_u32_e32 v244, 0x80, v244
	s_add_u32 m0, s100, 0x1a000
	s_nop 0
	global_load_lds_dwordx4 v246, s[8:9]
	v_add_u32_e32 v246, 0x80, v246
	s_barrier
	s_waitcnt lgkmcnt(0)
	v_mfma_f32_32x32x16_bf16 v[82:97], v[130:133], v[200:203], v[82:97]
	v_mfma_f32_32x32x16_bf16 v[50:65], v[146:149], v[200:203], v[50:65]
	v_mfma_f32_32x32x16_bf16 v[82:97], v[134:137], v[228:231], v[82:97]
	v_mfma_f32_32x32x16_bf16 v[50:65], v[150:153], v[228:231], v[50:65]
	v_mfma_f32_32x32x16_bf16 v[82:97], v[138:141], v[232:235], v[82:97]
	v_mfma_f32_32x32x16_bf16 v[50:65], v[168:171], v[232:235], v[50:65]
	v_mfma_f32_32x32x16_bf16 v[82:97], v[142:145], v[236:239], v[82:97]
	v_mfma_f32_32x32x16_bf16 v[50:65], v[172:175], v[236:239], v[50:65]
	s_barrier
	v_add_u32_e32 v166, s10, v161
	ds_read_b128 v[130:133], v166 offset:16384
	ds_read_b128 v[146:149], v166 offset:20480
	v_add_u32_e32 v166, s10, v163
	ds_read_b128 v[134:137], v166 offset:16384
	ds_read_b128 v[150:153], v166 offset:20480
	v_add_u32_e32 v166, s10, v164
	ds_read_b128 v[138:141], v166 offset:16384
	ds_read_b128 v[168:171], v166 offset:20480
	v_add_u32_e32 v166, s10, v165
	ds_read_b128 v[142:145], v166 offset:16384
	ds_read_b128 v[172:175], v166 offset:20480
	s_add_u32 m0, s100, 0x10000
	s_nop 0
	global_load_lds_dwordx4 v240, s[6:7]
	v_add_u32_e32 v240, 0x80, v240
	s_add_u32 m0, s100, 0x12000
	s_nop 0
	global_load_lds_dwordx4 v242, s[6:7]
	v_add_u32_e32 v242, 0x80, v242
	s_waitcnt vmcnt(10)
	s_barrier
	s_waitcnt lgkmcnt(0)
	v_mfma_f32_32x32x16_bf16 v[66:81], v[130:133], v[176:179], v[66:81]
	v_mfma_f32_32x32x16_bf16 v[34:49], v[146:149], v[176:179], v[34:49]
	v_mfma_f32_32x32x16_bf16 v[66:81], v[134:137], v[180:183], v[66:81]
	v_mfma_f32_32x32x16_bf16 v[34:49], v[150:153], v[180:183], v[34:49]
	v_mfma_f32_32x32x16_bf16 v[66:81], v[138:141], v[192:195], v[66:81]
	v_mfma_f32_32x32x16_bf16 v[34:49], v[168:171], v[192:195], v[34:49]
	v_mfma_f32_32x32x16_bf16 v[66:81], v[142:145], v[196:199], v[66:81]
	v_mfma_f32_32x32x16_bf16 v[34:49], v[172:175], v[196:199], v[34:49]
	s_barrier
	ds_read_b128 v[176:179], v248 offset:32768
	ds_read_b128 v[180:183], v186 offset:32768
	ds_read_b128 v[192:195], v187 offset:32768
	ds_read_b128 v[196:199], v249 offset:32768
	s_add_u32 m0, s100, 0x1c000
	s_nop 0
	global_load_lds_dwordx4 v245, s[8:9]
	v_add_u32_e32 v245, 0x80, v245
	s_add_u32 m0, s100, 0x1e000
	s_nop 0
	global_load_lds_dwordx4 v247, s[8:9]
	v_add_u32_e32 v247, 0x80, v247
	s_waitcnt vmcnt(6)
	s_barrier
	s_waitcnt lgkmcnt(0)
	v_mfma_f32_32x32x16_bf16 v[18:33], v[130:133], v[200:203], v[18:33]
	v_mfma_f32_32x32x16_bf16 v[2:17], v[146:149], v[200:203], v[2:17]
	v_mfma_f32_32x32x16_bf16 v[18:33], v[134:137], v[228:231], v[18:33]
	v_mfma_f32_32x32x16_bf16 v[2:17], v[150:153], v[228:231], v[2:17]
	v_mfma_f32_32x32x16_bf16 v[18:33], v[138:141], v[232:235], v[18:33]
	v_mfma_f32_32x32x16_bf16 v[2:17], v[168:171], v[232:235], v[2:17]
	v_mfma_f32_32x32x16_bf16 v[18:33], v[142:145], v[236:239], v[18:33]
	v_mfma_f32_32x32x16_bf16 v[2:17], v[172:175], v[236:239], v[2:17]
	s_add_i32 s11, s11, 2
	s_cmp_lt_u32 s11, 14
	s_barrier
	s_cbranch_scc1 .Lg8_ib
	ds_read_b128 v[130:133], v161
	ds_read_b128 v[134:137], v163
	ds_read_b128 v[138:141], v164
	ds_read_b128 v[142:145], v165
	ds_read_b128 v[146:149], v161 offset:4096
	ds_read_b128 v[150:153], v163 offset:4096
	ds_read_b128 v[168:171], v164 offset:4096
	ds_read_b128 v[172:175], v165 offset:4096
	s_add_u32 m0, s100, 0x14000
	s_nop 0
	global_load_lds_dwordx4 v241, s[6:7]
	v_add_u32_e32 v241, 0x80, v241
	s_add_u32 m0, s100, 0x16000
	s_nop 0
	global_load_lds_dwordx4 v243, s[6:7]
	v_add_u32_e32 v243, 0x80, v243
	s_barrier
	s_waitcnt lgkmcnt(0)
	v_mfma_f32_32x32x16_bf16 v[114:129], v[130:133], v[176:179], v[114:129]
	v_mfma_f32_32x32x16_bf16 v[98:113], v[146:149], v[176:179], v[98:113]
	v_mfma_f32_32x32x16_bf16 v[114:129], v[134:137], v[180:183], v[114:129]
	v_mfma_f32_32x32x16_bf16 v[98:113], v[150:153], v[180:183], v[98:113]
	v_mfma_f32_32x32x16_bf16 v[114:129], v[138:141], v[192:195], v[114:129]
	v_mfma_f32_32x32x16_bf16 v[98:113], v[168:171], v[192:195], v[98:113]
	v_mfma_f32_32x32x16_bf16 v[114:129], v[142:145], v[196:199], v[114:129]
	v_mfma_f32_32x32x16_bf16 v[98:113], v[172:175], v[196:199], v[98:113]
	s_barrier
	ds_read_b128 v[200:203], v248 offset:49152
	ds_read_b128 v[228:231], v186 offset:49152
	ds_read_b128 v[232:235], v187 offset:49152
	ds_read_b128 v[236:239], v249 offset:49152
	s_barrier
	s_waitcnt lgkmcnt(0)
	v_mfma_f32_32x32x16_bf16 v[82:97], v[130:133], v[200:203], v[82:97]
	v_mfma_f32_32x32x16_bf16 v[50:65], v[146:149], v[200:203], v[50:65]
	v_mfma_f32_32x32x16_bf16 v[82:97], v[134:137], v[228:231], v[82:97]
	v_mfma_f32_32x32x16_bf16 v[50:65], v[150:153], v[228:231], v[50:65]
	v_mfma_f32_32x32x16_bf16 v[82:97], v[138:141], v[232:235], v[82:97]
	v_mfma_f32_32x32x16_bf16 v[50:65], v[168:171], v[232:235], v[50:65]
	v_mfma_f32_32x32x16_bf16 v[82:97], v[142:145], v[236:239], v[82:97]
	v_mfma_f32_32x32x16_bf16 v[50:65], v[172:175], v[236:239], v[50:65]
	s_barrier
; template <bool SWAP>
; DI void gemm_mainloop(f32x16 (&acc)[4][2], const u16* __restrict__ A, int lda, int rlo, int rhi,
;                       const u16* __restrict__ B, int ldb, int K, char* lds, const u16* zero_line) {
;     ...
; #pragma unroll 2
;   for (int kt = 0; kt < nk; ++kt) {
;     const char* st = lds + (kt & 1) * 65536;
;     ldfrag(st, 0, 0);
;     mma(1);
;     pat_rd();
;     if (kt + 1 < nk) glds(kt + 1, (kt + 1) & 1);
;     ldfrag(st, 1, 1);
;     mma(0);
;     pat_rd();
;     ldfrag(st, 2, 0);
;     mma(1);
;     pat_rd();
;     ldfrag(st, 3, 1);
;     mma(0);
;     pat_rd();
;     asm volatile("s_waitcnt vmcnt(0)" ::: "memory");
;     __syncthreads();
;   }
;   mma(1);
	ds_read_b128 v[130:133], v161 offset:16384
	ds_read_b128 v[134:137], v163 offset:16384
	ds_read_b128 v[138:141], v164 offset:16384
	ds_read_b128 v[142:145], v165 offset:16384
	ds_read_b128 v[146:149], v161 offset:20480
	ds_read_b128 v[150:153], v163 offset:20480
	ds_read_b128 v[168:171], v164 offset:20480
	ds_read_b128 v[172:175], v165 offset:20480
	s_waitcnt vmcnt(4)
	s_barrier
	s_waitcnt lgkmcnt(0)
	v_mfma_f32_32x32x16_bf16 v[66:81], v[130:133], v[176:179], v[66:81]
	v_mfma_f32_32x32x16_bf16 v[34:49], v[146:149], v[176:179], v[34:49]
	v_mfma_f32_32x32x16_bf16 v[66:81], v[134:137], v[180:183], v[66:81]
	v_mfma_f32_32x32x16_bf16 v[34:49], v[150:153], v[180:183], v[34:49]
	v_mfma_f32_32x32x16_bf16 v[66:81], v[138:141], v[192:195], v[66:81]
	v_mfma_f32_32x32x16_bf16 v[34:49], v[168:171], v[192:195], v[34:49]
	v_mfma_f32_32x32x16_bf16 v[66:81], v[142:145], v[196:199], v[66:81]
	v_mfma_f32_32x32x16_bf16 v[34:49], v[172:175], v[196:199], v[34:49]
	v_mfma_f32_32x32x16_bf16 v[18:33], v[130:133], v[200:203], v[18:33]
	v_mfma_f32_32x32x16_bf16 v[2:17], v[146:149], v[200:203], v[2:17]
	v_mfma_f32_32x32x16_bf16 v[18:33], v[134:137], v[228:231], v[18:33]
	v_mfma_f32_32x32x16_bf16 v[2:17], v[150:153], v[228:231], v[2:17]
	v_mfma_f32_32x32x16_bf16 v[18:33], v[138:141], v[232:235], v[18:33]
	v_mfma_f32_32x32x16_bf16 v[2:17], v[168:171], v[232:235], v[2:17]
	v_mfma_f32_32x32x16_bf16 v[18:33], v[142:145], v[236:239], v[18:33]
	v_mfma_f32_32x32x16_bf16 v[2:17], v[172:175], v[236:239], v[2:17]
	s_barrier
	v_add_u32_e32 v166, s10, v248
	ds_read_b128 v[176:179], v166 offset:32768
	v_add_u32_e32 v166, s10, v186
	ds_read_b128 v[180:183], v166 offset:32768
	v_add_u32_e32 v166, s10, v187
	ds_read_b128 v[192:195], v166 offset:32768
	v_add_u32_e32 v166, s10, v249
	ds_read_b128 v[196:199], v166 offset:32768
	v_add_u32_e32 v166, s10, v161
	ds_read_b128 v[130:133], v166
	ds_read_b128 v[146:149], v166 offset:4096
	v_add_u32_e32 v166, s10, v163
	ds_read_b128 v[134:137], v166
	ds_read_b128 v[150:153], v166 offset:4096
	v_add_u32_e32 v166, s10, v164
	ds_read_b128 v[138:141], v166
	ds_read_b128 v[168:171], v166 offset:4096
	v_add_u32_e32 v166, s10, v165
	ds_read_b128 v[142:145], v166
	ds_read_b128 v[172:175], v166 offset:4096
	s_waitcnt vmcnt(2)
	s_barrier
	s_waitcnt lgkmcnt(0)
	v_mfma_f32_32x32x16_bf16 v[114:129], v[130:133], v[176:179], v[114:129]
	v_mfma_f32_32x32x16_bf16 v[98:113], v[146:149], v[176:179], v[98:113]
	v_mfma_f32_32x32x16_bf16 v[114:129], v[134:137], v[180:183], v[114:129]
	v_mfma_f32_32x32x16_bf16 v[98:113], v[150:153], v[180:183], v[98:113]
	v_mfma_f32_32x32x16_bf16 v[114:129], v[138:141], v[192:195], v[114:129]
	v_mfma_f32_32x32x16_bf16 v[98:113], v[168:171], v[192:195], v[98:113]
	v_mfma_f32_32x32x16_bf16 v[114:129], v[142:145], v[196:199], v[114:129]
	v_mfma_f32_32x32x16_bf16 v[98:113], v[172:175], v[196:199], v[98:113]
	s_barrier
	v_add_u32_e32 v166, s10, v248
	ds_read_b128 v[200:203], v166 offset:49152
	v_add_u32_e32 v166, s10, v186
	ds_read_b128 v[228:231], v166 offset:49152
	v_add_u32_e32 v166, s10, v187
	ds_read_b128 v[232:235], v166 offset:49152
	v_add_u32_e32 v166, s10, v249
	ds_read_b128 v[236:239], v166 offset:49152
	s_waitcnt vmcnt(0)
	s_barrier
	s_waitcnt lgkmcnt(0)
	v_mfma_f32_32x32x16_bf16 v[82:97], v[130:133], v[200:203], v[82:97]
	v_mfma_f32_32x32x16_bf16 v[50:65], v[146:149], v[200:203], v[50:65]
	v_mfma_f32_32x32x16_bf16 v[82:97], v[134:137], v[228:231], v[82:97]
	v_mfma_f32_32x32x16_bf16 v[50:65], v[150:153], v[228:231], v[50:65]
	v_mfma_f32_32x32x16_bf16 v[82:97], v[138:141], v[232:235], v[82:97]
	v_mfma_f32_32x32x16_bf16 v[50:65], v[168:171], v[232:235], v[50:65]
	v_mfma_f32_32x32x16_bf16 v[82:97], v[142:145], v[236:239], v[82:97]
	v_mfma_f32_32x32x16_bf16 v[50:65], v[172:175], v[236:239], v[50:65]
	s_barrier
	v_add_u32_e32 v166, s10, v161
	ds_read_b128 v[130:133], v166 offset:16384
	ds_read_b128 v[146:149], v166 offset:20480
	v_add_u32_e32 v166, s10, v163
	ds_read_b128 v[134:137], v166 offset:16384
	ds_read_b128 v[150:153], v166 offset:20480
	v_add_u32_e32 v166, s10, v164
	ds_read_b128 v[138:141], v166 offset:16384
	ds_read_b128 v[168:171], v166 offset:20480
	v_add_u32_e32 v166, s10, v165
	ds_read_b128 v[142:145], v166 offset:16384
	ds_read_b128 v[172:175], v166 offset:20480
	s_barrier
	s_waitcnt lgkmcnt(0)
	v_mfma_f32_32x32x16_bf16 v[66:81], v[130:133], v[176:179], v[66:81]
	v_mfma_f32_32x32x16_bf16 v[34:49], v[146:149], v[176:179], v[34:49]
	v_mfma_f32_32x32x16_bf16 v[66:81], v[134:137], v[180:183], v[66:81]
	v_mfma_f32_32x32x16_bf16 v[34:49], v[150:153], v[180:183], v[34:49]
	v_mfma_f32_32x32x16_bf16 v[66:81], v[138:141], v[192:195], v[66:81]
	v_mfma_f32_32x32x16_bf16 v[34:49], v[168:171], v[192:195], v[34:49]
	v_mfma_f32_32x32x16_bf16 v[66:81], v[142:145], v[196:199], v[66:81]
	v_mfma_f32_32x32x16_bf16 v[34:49], v[172:175], v[196:199], v[34:49]
	v_mfma_f32_32x32x16_bf16 v[18:33], v[130:133], v[200:203], v[18:33]
	v_mfma_f32_32x32x16_bf16 v[2:17], v[146:149], v[200:203], v[2:17]
	v_mfma_f32_32x32x16_bf16 v[18:33], v[134:137], v[228:231], v[18:33]
	v_mfma_f32_32x32x16_bf16 v[2:17], v[150:153], v[228:231], v[2:17]
	v_mfma_f32_32x32x16_bf16 v[18:33], v[138:141], v[232:235], v[18:33]
	v_mfma_f32_32x32x16_bf16 v[2:17], v[168:171], v[232:235], v[2:17]
	v_mfma_f32_32x32x16_bf16 v[18:33], v[142:145], v[236:239], v[18:33]
	v_mfma_f32_32x32x16_bf16 v[2:17], v[172:175], v[236:239], v[2:17]
	s_barrier
	s_cmp_eq_u32 s101, 0
	s_cbranch_scc0 .Lg8_ib_p1
	s_barrier
